# cache policy: weight-transpose and conv 16-byte stores also write-through (sc0 sc1); on top of v69
# speedup vs baseline: 1.0128x; 1.0036x over previous
; #define LAS __attribute__((address_space(3)))
; __device__ __forceinline__ void lds_wait() { asm volatile("s_waitcnt lgkmcnt(0)" ::: "memory"); }
; __device__ __forceinline__ void transpose_item(const float* W, int K, int N, bf16_t* WT, int gate, const float* kscale, LAS float* scr, int item, int lane) {
;     const int nblk = N / 64, kb = item / nblk, nb = item % nblk, k0 = 64 * kb, n0 = 64 * nb;
;     const int c4 = (lane & 15) * 4, kr = lane >> 4;
;     f32x4 v[16];
; #pragma unroll
;     for (int i = 0; i < 16; ++i) v[i] = __builtin_nontemporal_load((const f32x4*)(W + (size_t)(k0 + 4 * i + kr) * N + n0 + c4));
; #pragma unroll
;     for (int i = 0; i < 16; ++i) { LAS float* d = scr + (4 * i + kr) * 65 + c4; d[0] = v[i][0]; d[1] = v[i][1]; d[2] = v[i][2]; d[3] = v[i][3]; }
;     lds_wait();
.LBB0_24:
	s_mul_hi_i32 s5, s4, 0x2aaaaaab
	s_lshr_b32 s6, s5, 31
	s_ashr_i32 s5, s5, 4
	s_add_i32 s5, s5, s6
	s_lshl_b32 s6, s5, 6
	s_mulk_i32 s5, 0xe800
	s_add_i32 s8, s0, s5
	v_add_u32_e32 v52, s6, v21
	s_ashr_i32 s9, s8, 31
	s_ashr_i32 s7, s6, 31
	v_add_u32_e32 v54, 4, v52
	v_add_u32_e32 v56, 8, v52
	v_add_u32_e32 v58, 12, v52
	v_add_u32_e32 v59, 16, v52
	v_add_u32_e32 v62, 20, v52
	v_add_u32_e32 v63, 24, v52
	v_add_u32_e32 v66, 28, v52
	v_add_u32_e32 v67, 32, v52
	v_add_u32_e32 v70, 36, v52
	v_add_u32_e32 v71, 40, v52
	v_add_u32_e32 v74, 44, v52
	v_add_u32_e32 v75, 48, v52
	v_add_u32_e32 v78, 52, v52
	v_add_u32_e32 v79, 56, v52
	v_add_u32_e32 v82, 60, v52
	v_add_u32_e32 v48, s8, v6
	v_lshl_add_u64 v[50:51], s[8:9], 2, v[0:1]
	v_lshl_add_u64 v[112:113], s[6:7], 1, v[2:3]
	v_ashrrev_i32_e32 v49, 31, v48
	v_mad_i64_i32 v[52:53], s[6:7], v52, s1, v[50:51]
	v_mad_i64_i32 v[54:55], s[6:7], v54, s1, v[50:51]
	v_mad_i64_i32 v[56:57], s[6:7], v56, s1, v[50:51]
	v_mad_i64_i32 v[60:61], s[6:7], v58, s1, v[50:51]
	v_mad_i64_i32 v[64:65], s[6:7], v59, s1, v[50:51]
	v_mad_i64_i32 v[68:69], s[6:7], v62, s1, v[50:51]
	v_mad_i64_i32 v[72:73], s[6:7], v63, s1, v[50:51]
	v_mad_i64_i32 v[76:77], s[6:7], v66, s1, v[50:51]
	v_mad_i64_i32 v[80:81], s[6:7], v67, s1, v[50:51]
	v_mad_i64_i32 v[84:85], s[6:7], v70, s1, v[50:51]
	v_mad_i64_i32 v[88:89], s[6:7], v71, s1, v[50:51]
	v_mad_i64_i32 v[92:93], s[6:7], v74, s1, v[50:51]
	v_mad_i64_i32 v[96:97], s[6:7], v75, s1, v[50:51]
	v_mad_i64_i32 v[100:101], s[6:7], v78, s1, v[50:51]
	v_mad_i64_i32 v[104:105], s[6:7], v79, s1, v[50:51]
	v_mad_i64_i32 v[108:109], s[6:7], v82, s1, v[50:51]
	v_add_u32_e32 v114, 8, v48
	v_add_u32_e32 v116, 16, v48
	v_add_u32_e32 v118, 24, v48
	v_add_u32_e32 v120, 32, v48
	v_add_u32_e32 v122, 40, v48
	v_add_u32_e32 v124, 48, v48
	v_add_u32_e32 v126, 56, v48
	v_lshlrev_b64 v[128:129], 12, v[48:49]
	global_load_dwordx4 v[48:51], v[52:53], off nt
	s_nop 0
	global_load_dwordx4 v[52:55], v[54:55], off nt
	s_nop 0
	global_load_dwordx4 v[56:59], v[56:57], off nt
	s_nop 0
	global_load_dwordx4 v[60:63], v[60:61], off nt
	s_nop 0
	global_load_dwordx4 v[64:67], v[64:65], off nt
	s_nop 0
	global_load_dwordx4 v[68:71], v[68:69], off nt
	s_nop 0
	global_load_dwordx4 v[72:75], v[72:73], off nt
	s_nop 0
	global_load_dwordx4 v[76:79], v[76:77], off nt
	s_nop 0
	global_load_dwordx4 v[80:83], v[80:81], off nt
	s_nop 0
	global_load_dwordx4 v[84:87], v[84:85], off nt
	s_nop 0
	global_load_dwordx4 v[88:91], v[88:89], off nt
	s_nop 0
	global_load_dwordx4 v[92:95], v[92:93], off nt
	s_nop 0
	global_load_dwordx4 v[96:99], v[96:97], off nt
	s_nop 0
	global_load_dwordx4 v[100:103], v[100:101], off nt
	s_nop 0
	global_load_dwordx4 v[104:107], v[104:105], off nt
	s_nop 0
	global_load_dwordx4 v[108:111], v[108:109], off nt
	v_add_u32_e32 v130, 0x38e8, v11
	v_add_u32_e32 v131, 0x3cf0, v11
	v_add_u32_e32 v132, 0x3cf8, v11
	v_ashrrev_i32_e32 v115, 31, v114
	v_ashrrev_i32_e32 v117, 31, v116
	v_ashrrev_i32_e32 v119, 31, v118
	v_ashrrev_i32_e32 v121, 31, v120
	v_ashrrev_i32_e32 v123, 31, v122
	v_ashrrev_i32_e32 v125, 31, v124
	v_ashrrev_i32_e32 v127, 31, v126
	v_lshlrev_b64 v[114:115], 12, v[114:115]
	v_lshlrev_b64 v[116:117], 12, v[116:117]
	v_lshlrev_b64 v[118:119], 12, v[118:119]
	v_lshlrev_b64 v[120:121], 12, v[120:121]
	v_lshlrev_b64 v[122:123], 12, v[122:123]
	v_lshlrev_b64 v[124:125], 12, v[124:125]
	v_lshlrev_b64 v[126:127], 12, v[126:127]
	v_add_u32_e32 v133, 0x400, v7
	s_waitcnt vmcnt(15)
	ds_write2_b32 v11, v48, v49 offset1:1
	ds_write2_b32 v11, v50, v51 offset0:2 offset1:3
	s_waitcnt vmcnt(14)
	ds_write2_b32 v12, v52, v53 offset1:1
	ds_write2_b32 v13, v54, v55 offset1:1
	s_waitcnt vmcnt(13)
	ds_write2_b32 v14, v56, v57 offset1:1
	ds_write2_b32 v15, v58, v59 offset1:1
	s_waitcnt vmcnt(12)
	ds_write2_b32 v16, v60, v61 offset1:1
	ds_write2_b32 v17, v62, v63 offset1:1
	s_waitcnt vmcnt(11)
	ds_write2_b32 v18, v64, v65 offset1:1
	ds_write2_b32 v19, v66, v67 offset1:1
	s_waitcnt vmcnt(10)
	ds_write2_b32 v29, v68, v69 offset1:1
	ds_write2_b32 v30, v70, v71 offset1:1
	s_waitcnt vmcnt(9)
	ds_write2_b32 v31, v72, v73 offset1:1
	ds_write2_b32 v32, v74, v75 offset1:1
	s_waitcnt vmcnt(8)
	ds_write2_b32 v33, v76, v77 offset1:1
	ds_write2_b32 v34, v78, v79 offset1:1
	s_waitcnt vmcnt(7)
	ds_write2_b32 v35, v80, v81 offset1:1
	ds_write2_b32 v36, v82, v83 offset1:1
	s_waitcnt vmcnt(6)
	ds_write2_b32 v37, v84, v85 offset1:1
	ds_write2_b32 v38, v86, v87 offset1:1
	s_waitcnt vmcnt(5)
; #define LAS __attribute__((address_space(3)))
; __device__ __forceinline__ void lds_wait() { asm volatile("s_waitcnt lgkmcnt(0)" ::: "memory"); }
; __device__ __forceinline__ void transpose_item(const float* W, int K, int N, bf16_t* WT, int gate, const float* kscale, LAS float* scr, int item, int lane) {
;     ...
;     for (int i = 0; i < 16; ++i) { LAS float* d = scr + (4 * i + kr) * 65 + c4; d[0] = v[i][0]; d[1] = v[i][1]; d[2] = v[i][2]; d[3] = v[i][3]; }
;     lds_wait();
;     const int c = lane & 7;
;     f32x4 k0v = {1.f, 1.f, 1.f, 1.f}, k1v = k0v;
;     if (kscale) { k0v = *(const f32x4*)(kscale + k0 + 8 * c); k1v = *(const f32x4*)(kscale + k0 + 8 * c + 4); }
; #pragma unroll
;     for (int j = 0; j < 8; ++j) { const int n = (lane >> 3) + 8 * j; const LAS float* s = scr + (8 * c) * 65 + n;
;         u32x4 o; o.x = pk2(s[0 * 65] * k0v[0], s[1 * 65] * k0v[1]); o.y = pk2(s[2 * 65] * k0v[2], s[3 * 65] * k0v[3]); o.z = pk2(s[4 * 65] * k1v[0], s[5 * 65] * k1v[1]); o.w = pk2(s[6 * 65] * k1v[2], s[7 * 65] * k1v[3]);
;         const int nn = n0 + n; const int row = gate < 0 ? nn : (256 * (nn >> 7) + 128 * gate + (nn & 127));
;         *(u32x4*)(WT + (size_t)row * K + k0 + 8 * c) = o; }
;     lds_wait();
	ds_write2_b32 v39, v88, v89 offset1:1
	ds_write2_b32 v40, v90, v91 offset1:1
	s_waitcnt vmcnt(4)
	ds_write2_b32 v41, v92, v93 offset1:1
	ds_write2_b32 v42, v94, v95 offset1:1
	s_waitcnt vmcnt(3)
	ds_write2_b32 v43, v96, v97 offset1:1
	ds_write2_b32 v44, v98, v99 offset1:1
	s_waitcnt vmcnt(2)
	ds_write2_b32 v45, v100, v101 offset1:1
	ds_write2_b32 v46, v102, v103 offset1:1
	s_waitcnt vmcnt(1)
	ds_write2_b32 v47, v104, v105 offset1:1
	ds_write2_b32 v130, v106, v107 offset1:1
	s_waitcnt vmcnt(0)
	ds_write2_b32 v131, v108, v109 offset1:1
	ds_write2_b32 v132, v110, v111 offset1:1
	s_waitcnt lgkmcnt(0)
	v_lshl_add_u64 v[128:129], v[112:113], 0, v[128:129]
	v_lshl_add_u64 v[114:115], v[112:113], 0, v[114:115]
	v_lshl_add_u64 v[116:117], v[112:113], 0, v[116:117]
	v_lshl_add_u64 v[118:119], v[112:113], 0, v[118:119]
	v_lshl_add_u64 v[120:121], v[112:113], 0, v[120:121]
	v_lshl_add_u64 v[122:123], v[112:113], 0, v[122:123]
	v_lshl_add_u64 v[124:125], v[112:113], 0, v[124:125]
	v_lshl_add_u64 v[112:113], v[112:113], 0, v[126:127]
	ds_read2_b32 v[52:53], v7 offset0:65 offset1:73
	ds_read2_b32 v[54:55], v7 offset1:8
	ds_read2_b32 v[56:57], v7 offset0:130 offset1:138
	ds_read2_b32 v[58:59], v7 offset0:195 offset1:203
	ds_read2_b32 v[60:61], v133 offset0:4 offset1:12
	ds_read2_b32 v[62:63], v133 offset0:69 offset1:77
	ds_read2_b32 v[64:65], v133 offset0:134 offset1:142
	ds_read2_b32 v[66:67], v133 offset0:199 offset1:207
	ds_read2_b32 v[68:69], v7 offset0:81 offset1:89
	ds_read2_b32 v[70:71], v7 offset0:16 offset1:24
	ds_read2_b32 v[72:73], v7 offset0:146 offset1:154
	ds_read2_b32 v[74:75], v7 offset0:211 offset1:219
	ds_read2_b32 v[76:77], v133 offset0:20 offset1:28
	ds_read2_b32 v[78:79], v133 offset0:85 offset1:93
	ds_read2_b32 v[80:81], v133 offset0:150 offset1:158
	ds_read2_b32 v[82:83], v133 offset0:215 offset1:223
	ds_read2_b32 v[84:85], v7 offset0:32 offset1:40
	ds_read2_b32 v[86:87], v7 offset0:97 offset1:105
	ds_read2_b32 v[88:89], v7 offset0:162 offset1:170
	ds_read2_b32 v[90:91], v7 offset0:227 offset1:235
	ds_read2_b32 v[92:93], v133 offset0:36 offset1:44
	ds_read2_b32 v[94:95], v133 offset0:101 offset1:109
	ds_read2_b32 v[96:97], v133 offset0:166 offset1:174
	ds_read2_b32 v[98:99], v133 offset0:231 offset1:239
	ds_read2_b32 v[100:101], v7 offset0:48 offset1:56
	ds_read2_b32 v[102:103], v7 offset0:113 offset1:121
	ds_read2_b32 v[104:105], v7 offset0:178 offset1:186
	ds_read2_b32 v[106:107], v7 offset0:243 offset1:251
	ds_read2_b32 v[108:109], v133 offset0:52 offset1:60
	ds_read2_b32 v[110:111], v133 offset0:117 offset1:125
	ds_read2_b32 v[126:127], v133 offset0:182 offset1:190
	ds_read2_b32 v[130:131], v133 offset0:247 offset1:255
	s_waitcnt lgkmcnt(14)
	v_cvt_pk_bf16_f32 v48, v54, v52
	v_cvt_pk_bf16_f32 v49, v56, v58
	v_cvt_pk_bf16_f32 v50, v60, v62
	v_cvt_pk_bf16_f32 v51, v64, v66
	v_cvt_pk_bf16_f32 v52, v55, v53
	v_cvt_pk_bf16_f32 v53, v57, v59
	v_cvt_pk_bf16_f32 v54, v61, v63
	v_cvt_pk_bf16_f32 v55, v65, v67
	v_cvt_pk_bf16_f32 v56, v70, v68
	v_cvt_pk_bf16_f32 v57, v72, v74
	v_cvt_pk_bf16_f32 v58, v76, v78
	v_cvt_pk_bf16_f32 v59, v80, v82
	v_cvt_pk_bf16_f32 v60, v71, v69
	v_cvt_pk_bf16_f32 v61, v73, v75
	v_cvt_pk_bf16_f32 v62, v77, v79
	v_cvt_pk_bf16_f32 v63, v81, v83
	v_cvt_pk_bf16_f32 v64, v84, v86
	s_waitcnt lgkmcnt(12)
	v_cvt_pk_bf16_f32 v65, v88, v90
	v_cvt_pk_bf16_f32 v68, v85, v87
	v_cvt_pk_bf16_f32 v69, v89, v91
	s_waitcnt lgkmcnt(10)
	v_cvt_pk_bf16_f32 v66, v92, v94
	v_cvt_pk_bf16_f32 v70, v93, v95
	s_waitcnt lgkmcnt(8)
	v_cvt_pk_bf16_f32 v67, v96, v98
	v_cvt_pk_bf16_f32 v71, v97, v99
	s_waitcnt lgkmcnt(6)
	v_cvt_pk_bf16_f32 v72, v100, v102
	s_waitcnt lgkmcnt(4)
	v_cvt_pk_bf16_f32 v73, v104, v106
	v_cvt_pk_bf16_f32 v76, v101, v103
	v_cvt_pk_bf16_f32 v77, v105, v107
	s_waitcnt lgkmcnt(2)
	v_cvt_pk_bf16_f32 v74, v108, v110
	v_cvt_pk_bf16_f32 v78, v109, v111
	s_waitcnt lgkmcnt(0)
	v_cvt_pk_bf16_f32 v75, v126, v130
	v_cvt_pk_bf16_f32 v79, v127, v131
	global_store_dwordx4 v[128:129], v[48:51], off sc0 sc1
	global_store_dwordx4 v[114:115], v[52:55], off sc0 sc1
	global_store_dwordx4 v[116:117], v[56:59], off sc0 sc1
	global_store_dwordx4 v[118:119], v[60:63], off sc0 sc1
	global_store_dwordx4 v[120:121], v[64:67], off sc0 sc1
	global_store_dwordx4 v[122:123], v[68:71], off sc0 sc1
	global_store_dwordx4 v[124:125], v[72:75], off sc0 sc1
	global_store_dwordx4 v[112:113], v[76:79], off sc0 sc1
	s_waitcnt lgkmcnt(0)
	s_add_i32 s4, s4, s92
	s_add_i32 s0, s0, s38
	s_cmpk_lt_i32 s4, 0xc00
	s_cbranch_scc1 .LBB0_24
	v_mov_b32_e32 v29, v6

; #define LAS __attribute__((address_space(3)))
; __device__ __forceinline__ void lds_wait() { asm volatile("s_waitcnt lgkmcnt(0)" ::: "memory"); }
; __device__ __forceinline__ void transpose_item(const float* W, int K, int N, bf16_t* WT, int gate, const float* kscale, LAS float* scr, int item, int lane) {
;     const int nblk = N / 64, kb = item / nblk, nb = item % nblk, k0 = 64 * kb, n0 = 64 * nb;
;     const int c4 = (lane & 15) * 4, kr = lane >> 4;
;     f32x4 v[16];
; #pragma unroll
;     for (int i = 0; i < 16; ++i) v[i] = __builtin_nontemporal_load((const f32x4*)(W + (size_t)(k0 + 4 * i + kr) * N + n0 + c4));
; #pragma unroll
;     for (int i = 0; i < 16; ++i) { LAS float* d = scr + (4 * i + kr) * 65 + c4; d[0] = v[i][0]; d[1] = v[i][1]; d[2] = v[i][2]; d[3] = v[i][3]; }
;     lds_wait();
.LBB0_30:
	s_ashr_i32 s19, s18, 31
	s_lshr_b32 s19, s19, 30
	s_add_i32 s19, s18, s19
	s_ashr_i32 s19, s19, 2
	s_lshl_b32 s20, s19, 6
	s_lshl_b32 s21, s19, 8
	v_add_u32_e32 v78, s20, v21
	s_lshl_b32 s19, s19, 9
	s_sub_i32 s22, s13, s21
	v_add_u32_e32 v80, 4, v78
	v_add_u32_e32 v82, 8, v78
	v_add_u32_e32 v84, 12, v78
	v_add_u32_e32 v86, 16, v78
	v_add_u32_e32 v88, 20, v78
	v_add_u32_e32 v90, 24, v78
	v_add_u32_e32 v92, 28, v78
	v_add_u32_e32 v94, 32, v78
	v_add_u32_e32 v96, 36, v78
	v_add_u32_e32 v98, 40, v78
	v_add_u32_e32 v100, 44, v78
	v_add_u32_e32 v102, 48, v78
	v_add_u32_e32 v104, 52, v78
	v_add_u32_e32 v106, 56, v78
	v_add_u32_e32 v108, 60, v78
	s_sub_i32 s19, s12, s19
	s_ashr_i32 s23, s22, 31
	v_ashrrev_i32_e32 v79, 31, v78
	v_add_u32_e32 v112, s22, v29
	v_add_u32_e32 v113, s22, v22
	v_add_u32_e32 v116, s22, v23
	v_add_u32_e32 v118, s22, v24
	v_add_u32_e32 v120, s22, v25
	v_add_u32_e32 v122, s22, v26
	v_add_u32_e32 v124, s22, v27
	v_add_u32_e32 v126, s22, v28
	v_ashrrev_i32_e32 v81, 31, v80
	v_ashrrev_i32_e32 v83, 31, v82
	v_ashrrev_i32_e32 v85, 31, v84
	v_ashrrev_i32_e32 v87, 31, v86
	v_ashrrev_i32_e32 v89, 31, v88
	v_ashrrev_i32_e32 v91, 31, v90
	v_ashrrev_i32_e32 v93, 31, v92
	v_ashrrev_i32_e32 v95, 31, v94
	v_ashrrev_i32_e32 v97, 31, v96
	v_ashrrev_i32_e32 v99, 31, v98
	v_ashrrev_i32_e32 v101, 31, v100
	v_ashrrev_i32_e32 v103, 31, v102
	v_ashrrev_i32_e32 v105, 31, v104
	v_ashrrev_i32_e32 v107, 31, v106
	v_ashrrev_i32_e32 v109, 31, v108
	v_add_u32_e32 v114, s19, v39
	v_add_u32_e32 v115, s19, v19
	v_add_u32_e32 v117, s19, v18
	v_add_u32_e32 v119, s19, v17
	v_add_u32_e32 v121, s19, v16
	v_add_u32_e32 v123, s19, v15
	v_add_u32_e32 v125, s19, v14
	v_add_u32_e32 v127, s19, v11
	v_lshl_add_u64 v[110:111], s[22:23], 2, v[12:13]
	v_lshlrev_b64 v[78:79], 10, v[78:79]
	v_and_b32_e32 v128, 0x7f, v112
	v_and_b32_e32 v129, 0x7f, v113
	v_and_b32_e32 v116, 0x7f, v116
	v_and_b32_e32 v118, 0x7f, v118
	v_and_b32_e32 v120, 0x7f, v120
	v_and_b32_e32 v122, 0x7f, v122
	v_and_b32_e32 v124, 0x7f, v124
	v_and_b32_e32 v126, 0x7f, v126
	v_lshlrev_b64 v[112:113], 10, v[80:81]
	v_lshlrev_b64 v[82:83], 10, v[82:83]
	v_lshlrev_b64 v[84:85], 10, v[84:85]
	v_lshlrev_b64 v[86:87], 10, v[86:87]
	v_lshlrev_b64 v[88:89], 10, v[88:89]
	v_lshlrev_b64 v[90:91], 10, v[90:91]
	v_lshlrev_b64 v[92:93], 10, v[92:93]
	v_lshlrev_b64 v[94:95], 10, v[94:95]
	v_lshlrev_b64 v[96:97], 10, v[96:97]
	v_lshlrev_b64 v[98:99], 10, v[98:99]
	v_lshlrev_b64 v[100:101], 10, v[100:101]
	v_lshlrev_b64 v[102:103], 10, v[102:103]
	v_lshlrev_b64 v[104:105], 10, v[104:105]
	v_lshlrev_b64 v[106:107], 10, v[106:107]
	v_lshlrev_b64 v[108:109], 10, v[108:109]
	v_lshl_add_u64 v[78:79], v[110:111], 0, v[78:79]
	v_and_or_b32 v144, v114, s10, v128
	v_and_or_b32 v146, v115, s10, v129
	v_and_or_b32 v148, v117, s10, v116
	v_and_or_b32 v150, v119, s10, v118
	v_and_or_b32 v152, v121, s10, v120
	v_and_or_b32 v154, v123, s10, v122
	v_and_or_b32 v156, v125, s10, v124
	v_and_or_b32 v158, v127, s10, v126
	v_lshl_add_u64 v[112:113], v[110:111], 0, v[112:113]
	v_lshl_add_u64 v[114:115], v[110:111], 0, v[82:83]
	v_lshl_add_u64 v[116:117], v[110:111], 0, v[84:85]
	v_lshl_add_u64 v[118:119], v[110:111], 0, v[86:87]
	v_lshl_add_u64 v[120:121], v[110:111], 0, v[88:89]
	v_lshl_add_u64 v[122:123], v[110:111], 0, v[90:91]
	v_lshl_add_u64 v[124:125], v[110:111], 0, v[92:93]
	v_lshl_add_u64 v[126:127], v[110:111], 0, v[94:95]
	v_lshl_add_u64 v[128:129], v[110:111], 0, v[96:97]
	v_lshl_add_u64 v[130:131], v[110:111], 0, v[98:99]
	v_lshl_add_u64 v[132:133], v[110:111], 0, v[100:101]
	v_lshl_add_u64 v[134:135], v[110:111], 0, v[102:103]
	v_lshl_add_u64 v[136:137], v[110:111], 0, v[104:105]
	v_lshl_add_u64 v[138:139], v[110:111], 0, v[106:107]
	v_lshl_add_u64 v[140:141], v[110:111], 0, v[108:109]
	global_load_dwordx4 v[78:81], v[78:79], off nt
	s_nop 0
	global_load_dwordx4 v[82:85], v[112:113], off nt
	global_load_dwordx4 v[86:89], v[114:115], off nt
	global_load_dwordx4 v[90:93], v[116:117], off nt
	global_load_dwordx4 v[94:97], v[118:119], off nt
	global_load_dwordx4 v[98:101], v[120:121], off nt
	global_load_dwordx4 v[102:105], v[122:123], off nt
	global_load_dwordx4 v[106:109], v[124:125], off nt
	global_load_dwordx4 v[110:113], v[126:127], off nt
	global_load_dwordx4 v[114:117], v[128:129], off nt
	s_nop 0
	global_load_dwordx4 v[118:121], v[130:131], off nt
	global_load_dwordx4 v[122:125], v[132:133], off nt
	global_load_dwordx4 v[126:129], v[134:135], off nt
	s_nop 0
	global_load_dwordx4 v[130:133], v[136:137], off nt
	s_nop 0
	global_load_dwordx4 v[134:137], v[138:139], off nt
	s_nop 0
	global_load_dwordx4 v[138:141], v[140:141], off nt
	v_add_u32_e32 v64, 0x34d0, v30
	v_add_u32_e32 v65, 0x34d8, v30
	v_add_u32_e32 v66, 0x38e0, v30
	v_add_u32_e32 v67, 0x38e8, v30
	v_add_u32_e32 v68, 0x3cf0, v30
	v_add_u32_e32 v69, 0x3cf8, v30
	s_waitcnt vmcnt(15)
	ds_write2_b32 v30, v78, v79 offset1:1
	ds_write2_b32 v30, v80, v81 offset0:2 offset1:3
	s_waitcnt vmcnt(14)
	ds_write2_b32 v40, v82, v83 offset1:1
	ds_write2_b32 v41, v84, v85 offset1:1
	s_waitcnt vmcnt(13)
	ds_write2_b32 v42, v86, v87 offset1:1
	ds_write2_b32 v43, v88, v89 offset1:1
	s_waitcnt vmcnt(12)
	ds_write2_b32 v44, v90, v91 offset1:1
	ds_write2_b32 v45, v92, v93 offset1:1
	s_waitcnt vmcnt(11)
	ds_write2_b32 v46, v94, v95 offset1:1
	ds_write2_b32 v47, v96, v97 offset1:1
	s_waitcnt vmcnt(10)
	ds_write2_b32 v48, v98, v99 offset1:1
	ds_write2_b32 v49, v100, v101 offset1:1
	s_waitcnt vmcnt(9)
	ds_write2_b32 v50, v102, v103 offset1:1
	ds_write2_b32 v51, v104, v105 offset1:1
	s_waitcnt vmcnt(8)
	ds_write2_b32 v52, v106, v107 offset1:1
	ds_write2_b32 v53, v108, v109 offset1:1
	s_waitcnt vmcnt(7)
; #define LAS __attribute__((address_space(3)))
; __device__ __forceinline__ void lds_wait() { asm volatile("s_waitcnt lgkmcnt(0)" ::: "memory"); }
; __device__ __forceinline__ void transpose_item(const float* W, int K, int N, bf16_t* WT, int gate, const float* kscale, LAS float* scr, int item, int lane) {
;     ...
;     const int c = lane & 7;
;     f32x4 k0v = {1.f, 1.f, 1.f, 1.f}, k1v = k0v;
;     if (kscale) { k0v = *(const f32x4*)(kscale + k0 + 8 * c); k1v = *(const f32x4*)(kscale + k0 + 8 * c + 4); }
; #pragma unroll
;     for (int j = 0; j < 8; ++j) { const int n = (lane >> 3) + 8 * j; const LAS float* s = scr + (8 * c) * 65 + n;
;         u32x4 o; o.x = pk2(s[0 * 65] * k0v[0], s[1 * 65] * k0v[1]); o.y = pk2(s[2 * 65] * k0v[2], s[3 * 65] * k0v[3]); o.z = pk2(s[4 * 65] * k1v[0], s[5 * 65] * k1v[1]); o.w = pk2(s[6 * 65] * k1v[2], s[7 * 65] * k1v[3]);
;         const int nn = n0 + n; const int row = gate < 0 ? nn : (256 * (nn >> 7) + 128 * gate + (nn & 127));
;         *(u32x4*)(WT + (size_t)row * K + k0 + 8 * c) = o; }
;     lds_wait();
	ds_write2_b32 v54, v110, v111 offset1:1
	ds_write2_b32 v55, v112, v113 offset1:1
	s_waitcnt vmcnt(6)
	ds_write2_b32 v56, v114, v115 offset1:1
	ds_write2_b32 v57, v116, v117 offset1:1
	s_waitcnt vmcnt(5)
	ds_write2_b32 v58, v118, v119 offset1:1
	ds_write2_b32 v59, v120, v121 offset1:1
	s_waitcnt vmcnt(4)
	ds_write2_b32 v60, v122, v123 offset1:1
	ds_write2_b32 v61, v124, v125 offset1:1
	s_waitcnt vmcnt(3)
	ds_write2_b32 v62, v126, v127 offset1:1
	ds_write2_b32 v63, v128, v129 offset1:1
	s_waitcnt vmcnt(2)
	ds_write2_b32 v64, v130, v131 offset1:1
	ds_write2_b32 v65, v132, v133 offset1:1
	s_waitcnt vmcnt(1)
	ds_write2_b32 v66, v134, v135 offset1:1
	ds_write2_b32 v67, v136, v137 offset1:1
	s_waitcnt vmcnt(0)
	ds_write2_b32 v68, v138, v139 offset1:1
	ds_write2_b32 v69, v140, v141 offset1:1
	s_waitcnt lgkmcnt(0)
	v_add_u32_e32 v70, 0x400, v31
	v_add_u32_e32 v71, 0x400, v32
	v_add_u32_e32 v72, 0x400, v33
	v_add_u32_e32 v73, 0x400, v34
	v_add_u32_e32 v74, 0x400, v35
	v_add_u32_e32 v75, 0x400, v36
	v_add_u32_e32 v76, 0x400, v37
	v_add_u32_e32 v77, 0x400, v38
	ds_read2_b32 v[78:79], v31 offset1:65
	ds_read2_b32 v[80:81], v31 offset0:130 offset1:195
	ds_read2_b32 v[82:83], v70 offset0:4 offset1:69
	ds_read2_b32 v[84:85], v70 offset0:134 offset1:199
	ds_read2_b32 v[86:87], v32 offset1:65
	ds_read2_b32 v[88:89], v32 offset0:130 offset1:195
	ds_read2_b32 v[90:91], v71 offset0:4 offset1:69
	ds_read2_b32 v[92:93], v71 offset0:134 offset1:199
	ds_read2_b32 v[94:95], v33 offset1:65
	ds_read2_b32 v[96:97], v33 offset0:130 offset1:195
	ds_read2_b32 v[98:99], v72 offset0:4 offset1:69
	ds_read2_b32 v[100:101], v72 offset0:134 offset1:199
	ds_read2_b32 v[102:103], v34 offset1:65
	ds_read2_b32 v[104:105], v34 offset0:130 offset1:195
	ds_read2_b32 v[106:107], v73 offset0:4 offset1:69
	ds_read2_b32 v[108:109], v73 offset0:134 offset1:199
	ds_read2_b32 v[110:111], v35 offset1:65
	ds_read2_b32 v[112:113], v35 offset0:130 offset1:195
	ds_read2_b32 v[114:115], v74 offset0:4 offset1:69
	ds_read2_b32 v[116:117], v74 offset0:134 offset1:199
	ds_read2_b32 v[118:119], v36 offset1:65
	ds_read2_b32 v[120:121], v36 offset0:130 offset1:195
	ds_read2_b32 v[122:123], v75 offset0:4 offset1:69
	ds_read2_b32 v[124:125], v75 offset0:134 offset1:199
	ds_read2_b32 v[126:127], v37 offset1:65
	ds_read2_b32 v[128:129], v37 offset0:130 offset1:195
	ds_read2_b32 v[130:131], v76 offset0:4 offset1:69
	ds_read2_b32 v[132:133], v76 offset0:134 offset1:199
	ds_read2_b32 v[134:135], v38 offset1:65
	ds_read2_b32 v[136:137], v38 offset0:130 offset1:195
	ds_read2_b32 v[138:139], v77 offset0:4 offset1:69
	ds_read2_b32 v[140:141], v77 offset0:134 offset1:199
	s_ashr_i32 s21, s20, 31
	v_ashrrev_i32_e32 v145, 31, v144
	v_lshl_add_u64 v[142:143], s[20:21], 1, v[6:7]
	v_ashrrev_i32_e32 v147, 31, v146
	v_ashrrev_i32_e32 v149, 31, v148
	v_ashrrev_i32_e32 v151, 31, v150
	v_ashrrev_i32_e32 v153, 31, v152
	v_ashrrev_i32_e32 v155, 31, v154
	v_ashrrev_i32_e32 v157, 31, v156
	v_ashrrev_i32_e32 v159, 31, v158
	v_lshlrev_b64 v[144:145], 9, v[144:145]
	v_lshlrev_b64 v[146:147], 9, v[146:147]
	v_lshlrev_b64 v[148:149], 9, v[148:149]
	v_lshlrev_b64 v[150:151], 9, v[150:151]
	v_lshlrev_b64 v[152:153], 9, v[152:153]
	v_lshlrev_b64 v[154:155], 9, v[154:155]
	v_lshlrev_b64 v[156:157], 9, v[156:157]
	v_lshlrev_b64 v[158:159], 9, v[158:159]
	v_lshl_add_u64 v[144:145], v[142:143], 0, v[144:145]
	s_waitcnt lgkmcnt(14)
	v_cvt_pk_bf16_f32 v78, v78, v79
	v_cvt_pk_bf16_f32 v79, v80, v81
	v_cvt_pk_bf16_f32 v80, v82, v83
	v_cvt_pk_bf16_f32 v81, v84, v85
	v_lshl_add_u64 v[146:147], v[142:143], 0, v[146:147]
	v_lshl_add_u64 v[148:149], v[142:143], 0, v[148:149]
	v_lshl_add_u64 v[150:151], v[142:143], 0, v[150:151]
	v_lshl_add_u64 v[152:153], v[142:143], 0, v[152:153]
	v_lshl_add_u64 v[154:155], v[142:143], 0, v[154:155]
	v_lshl_add_u64 v[156:157], v[142:143], 0, v[156:157]
	v_lshl_add_u64 v[142:143], v[142:143], 0, v[158:159]
	v_cvt_pk_bf16_f32 v82, v86, v87
	v_cvt_pk_bf16_f32 v83, v88, v89
	v_cvt_pk_bf16_f32 v84, v90, v91
	v_cvt_pk_bf16_f32 v85, v92, v93
	v_cvt_pk_bf16_f32 v86, v94, v95
	v_cvt_pk_bf16_f32 v87, v96, v97
	v_cvt_pk_bf16_f32 v88, v98, v99
	v_cvt_pk_bf16_f32 v89, v100, v101
	v_cvt_pk_bf16_f32 v90, v102, v103
	v_cvt_pk_bf16_f32 v91, v104, v105
	v_cvt_pk_bf16_f32 v92, v106, v107
	v_cvt_pk_bf16_f32 v93, v108, v109
	v_cvt_pk_bf16_f32 v94, v110, v111
	v_cvt_pk_bf16_f32 v95, v112, v113
	s_waitcnt lgkmcnt(13)
	v_cvt_pk_bf16_f32 v96, v114, v115
	s_waitcnt lgkmcnt(12)
	v_cvt_pk_bf16_f32 v97, v116, v117
	s_waitcnt lgkmcnt(11)
	v_cvt_pk_bf16_f32 v98, v118, v119
	s_waitcnt lgkmcnt(10)
	v_cvt_pk_bf16_f32 v99, v120, v121
	s_waitcnt lgkmcnt(9)
	v_cvt_pk_bf16_f32 v100, v122, v123
	s_waitcnt lgkmcnt(8)
	v_cvt_pk_bf16_f32 v101, v124, v125
	s_waitcnt lgkmcnt(7)
	v_cvt_pk_bf16_f32 v102, v126, v127
	s_waitcnt lgkmcnt(6)
	v_cvt_pk_bf16_f32 v103, v128, v129
	s_waitcnt lgkmcnt(5)
	v_cvt_pk_bf16_f32 v104, v130, v131
	s_waitcnt lgkmcnt(4)
	v_cvt_pk_bf16_f32 v105, v132, v133
	s_waitcnt lgkmcnt(3)
	v_cvt_pk_bf16_f32 v106, v134, v135
	s_waitcnt lgkmcnt(2)
	v_cvt_pk_bf16_f32 v107, v136, v137
	s_waitcnt lgkmcnt(1)
	v_cvt_pk_bf16_f32 v108, v138, v139
	s_waitcnt lgkmcnt(0)
	v_cvt_pk_bf16_f32 v109, v140, v141
	global_store_dwordx4 v[144:145], v[78:81], off sc0 sc1
	global_store_dwordx4 v[146:147], v[82:85], off sc0 sc1
	global_store_dwordx4 v[148:149], v[86:89], off sc0 sc1
	global_store_dwordx4 v[150:151], v[90:93], off sc0 sc1
	global_store_dwordx4 v[152:153], v[94:97], off sc0 sc1
	global_store_dwordx4 v[154:155], v[98:101], off sc0 sc1
	global_store_dwordx4 v[156:157], v[102:105], off sc0 sc1
	global_store_dwordx4 v[142:143], v[106:109], off sc0 sc1
	s_waitcnt lgkmcnt(0)
	s_add_i32 s18, s18, s92
	s_add_i32 s13, s13, s38
	s_add_i32 s12, s12, s3
	s_cmp_lt_i32 s18, 16
	s_cbranch_scc1 .LBB0_30
	v_lshl_add_u64 v[12:13], s[6:7], 2, v[2:3]
	s_mov_b32 s6, s9
	s_mov_b32 s7, s8
	s_mov_b32 s12, s54
; #define LAS __attribute__((address_space(3)))
; __device__ __forceinline__ void lds_wait() { asm volatile("s_waitcnt lgkmcnt(0)" ::: "memory"); }
; __device__ __forceinline__ void transpose_item(const float* W, int K, int N, bf16_t* WT, int gate, const float* kscale, LAS float* scr, int item, int lane) {
;     const int nblk = N / 64, kb = item / nblk, nb = item % nblk, k0 = 64 * kb, n0 = 64 * nb;
;     const int c4 = (lane & 15) * 4, kr = lane >> 4;
;     f32x4 v[16];
; #pragma unroll
;     for (int i = 0; i < 16; ++i) v[i] = __builtin_nontemporal_load((const f32x4*)(W + (size_t)(k0 + 4 * i + kr) * N + n0 + c4));
; #pragma unroll
;     for (int i = 0; i < 16; ++i) { LAS float* d = scr + (4 * i + kr) * 65 + c4; d[0] = v[i][0]; d[1] = v[i][1]; d[2] = v[i][2]; d[3] = v[i][3]; }
;     lds_wait();
.LBB0_32:
	s_ashr_i32 s13, s12, 31
	s_lshr_b32 s13, s13, 30
	s_add_i32 s13, s12, s13
	s_ashr_i32 s13, s13, 2
	s_lshl_b32 s18, s13, 6
	s_lshl_b32 s19, s13, 8
	s_lshl_b32 s13, s13, 9
	v_add_u32_e32 v78, s18, v21
	s_sub_i32 s20, s7, s19
	s_sub_i32 s13, s6, s13
	v_add_u32_e32 v80, 4, v78
	v_add_u32_e32 v82, 8, v78
	v_add_u32_e32 v84, 12, v78
	v_add_u32_e32 v86, 16, v78
	v_add_u32_e32 v88, 20, v78
	v_add_u32_e32 v90, 24, v78
	v_add_u32_e32 v92, 28, v78
	v_add_u32_e32 v94, 32, v78
	v_add_u32_e32 v96, 36, v78
	v_add_u32_e32 v98, 40, v78
	v_add_u32_e32 v100, 44, v78
	v_add_u32_e32 v102, 48, v78
	v_add_u32_e32 v104, 52, v78
	v_add_u32_e32 v106, 56, v78
	v_add_u32_e32 v108, 60, v78
	s_ashr_i32 s21, s20, 31
	v_ashrrev_i32_e32 v79, 31, v78
	v_add_u32_e32 v112, s20, v29
	v_add_u32_e32 v113, s13, v39
	v_add_u32_e32 v114, s20, v22
	v_add_u32_e32 v115, s13, v19
	v_add_u32_e32 v116, s20, v23
	v_add_u32_e32 v117, s13, v18
	v_add_u32_e32 v118, s20, v24
	v_add_u32_e32 v119, s13, v17
	v_add_u32_e32 v120, s20, v25
	v_add_u32_e32 v121, s13, v16
	v_add_u32_e32 v122, s20, v26
	v_add_u32_e32 v123, s13, v15
	v_add_u32_e32 v124, s20, v27
	v_add_u32_e32 v125, s13, v14
	v_add_u32_e32 v126, s20, v28
	v_add_u32_e32 v127, s13, v11
	v_ashrrev_i32_e32 v81, 31, v80
	v_ashrrev_i32_e32 v83, 31, v82
	v_ashrrev_i32_e32 v85, 31, v84
	v_ashrrev_i32_e32 v87, 31, v86
	v_ashrrev_i32_e32 v89, 31, v88
	v_ashrrev_i32_e32 v91, 31, v90
	v_ashrrev_i32_e32 v93, 31, v92
	v_ashrrev_i32_e32 v95, 31, v94
	v_ashrrev_i32_e32 v97, 31, v96
	v_ashrrev_i32_e32 v99, 31, v98
	v_ashrrev_i32_e32 v101, 31, v100
	v_ashrrev_i32_e32 v103, 31, v102
	v_ashrrev_i32_e32 v105, 31, v104
	v_ashrrev_i32_e32 v107, 31, v106
	v_ashrrev_i32_e32 v109, 31, v108
	v_lshl_add_u64 v[110:111], s[20:21], 2, v[12:13]
	v_lshlrev_b64 v[78:79], 10, v[78:79]
	v_and_b32_e32 v128, 0xffffff00, v113
	v_and_b32_e32 v129, 0x7f, v112
	v_and_b32_e32 v115, 0xffffff00, v115
	v_and_b32_e32 v114, 0x7f, v114
	v_and_b32_e32 v117, 0xffffff00, v117
	v_and_b32_e32 v116, 0x7f, v116
	v_and_b32_e32 v119, 0xffffff00, v119
	v_and_b32_e32 v118, 0x7f, v118
	v_and_b32_e32 v121, 0xffffff00, v121
	v_and_b32_e32 v120, 0x7f, v120
	v_and_b32_e32 v123, 0xffffff00, v123
	v_and_b32_e32 v122, 0x7f, v122
	v_and_b32_e32 v125, 0xffffff00, v125
	v_and_b32_e32 v124, 0x7f, v124
	v_and_b32_e32 v127, 0xffffff00, v127
	v_and_b32_e32 v126, 0x7f, v126
	v_lshlrev_b64 v[112:113], 10, v[80:81]
	v_lshlrev_b64 v[82:83], 10, v[82:83]
	v_lshlrev_b64 v[84:85], 10, v[84:85]
	v_lshlrev_b64 v[86:87], 10, v[86:87]
	v_lshlrev_b64 v[88:89], 10, v[88:89]
	v_lshlrev_b64 v[90:91], 10, v[90:91]
	v_lshlrev_b64 v[92:93], 10, v[92:93]
	v_lshlrev_b64 v[94:95], 10, v[94:95]
	v_lshlrev_b64 v[96:97], 10, v[96:97]
	v_lshlrev_b64 v[98:99], 10, v[98:99]
	v_lshlrev_b64 v[100:101], 10, v[100:101]
	v_lshlrev_b64 v[102:103], 10, v[102:103]
	v_lshlrev_b64 v[104:105], 10, v[104:105]
	v_lshlrev_b64 v[106:107], 10, v[106:107]
	v_lshlrev_b64 v[108:109], 10, v[108:109]
	v_lshl_add_u64 v[78:79], v[110:111], 0, v[78:79]
	v_or3_b32 v144, v129, v128, s11
	v_or3_b32 v146, v114, v115, s11
	v_or3_b32 v148, v116, v117, s11
	v_or3_b32 v150, v118, v119, s11
	v_or3_b32 v152, v120, v121, s11
	v_or3_b32 v154, v122, v123, s11
	v_or3_b32 v156, v124, v125, s11
	v_or3_b32 v158, v126, v127, s11
	v_lshl_add_u64 v[112:113], v[110:111], 0, v[112:113]
	v_lshl_add_u64 v[114:115], v[110:111], 0, v[82:83]
	v_lshl_add_u64 v[116:117], v[110:111], 0, v[84:85]
	v_lshl_add_u64 v[118:119], v[110:111], 0, v[86:87]
	v_lshl_add_u64 v[120:121], v[110:111], 0, v[88:89]
	v_lshl_add_u64 v[122:123], v[110:111], 0, v[90:91]
	v_lshl_add_u64 v[124:125], v[110:111], 0, v[92:93]
	v_lshl_add_u64 v[126:127], v[110:111], 0, v[94:95]
	v_lshl_add_u64 v[128:129], v[110:111], 0, v[96:97]
	v_lshl_add_u64 v[130:131], v[110:111], 0, v[98:99]
	v_lshl_add_u64 v[132:133], v[110:111], 0, v[100:101]
	v_lshl_add_u64 v[134:135], v[110:111], 0, v[102:103]
	v_lshl_add_u64 v[136:137], v[110:111], 0, v[104:105]
	v_lshl_add_u64 v[138:139], v[110:111], 0, v[106:107]
	v_lshl_add_u64 v[140:141], v[110:111], 0, v[108:109]
	global_load_dwordx4 v[78:81], v[78:79], off nt
	s_nop 0
	global_load_dwordx4 v[82:85], v[112:113], off nt
	global_load_dwordx4 v[86:89], v[114:115], off nt
	global_load_dwordx4 v[90:93], v[116:117], off nt
	global_load_dwordx4 v[94:97], v[118:119], off nt
	global_load_dwordx4 v[98:101], v[120:121], off nt
	global_load_dwordx4 v[102:105], v[122:123], off nt
	global_load_dwordx4 v[106:109], v[124:125], off nt
	global_load_dwordx4 v[110:113], v[126:127], off nt
	global_load_dwordx4 v[114:117], v[128:129], off nt
	s_nop 0
	global_load_dwordx4 v[118:121], v[130:131], off nt
	global_load_dwordx4 v[122:125], v[132:133], off nt
	global_load_dwordx4 v[126:129], v[134:135], off nt
	s_nop 0
	global_load_dwordx4 v[130:133], v[136:137], off nt
	s_nop 0
	global_load_dwordx4 v[134:137], v[138:139], off nt
	s_nop 0
	global_load_dwordx4 v[138:141], v[140:141], off nt
	s_waitcnt vmcnt(15)
	ds_write2_b32 v30, v78, v79 offset1:1
	ds_write2_b32 v30, v80, v81 offset0:2 offset1:3
	s_waitcnt vmcnt(14)
	ds_write2_b32 v40, v82, v83 offset1:1
	ds_write2_b32 v41, v84, v85 offset1:1
	s_waitcnt vmcnt(13)
	ds_write2_b32 v42, v86, v87 offset1:1
	ds_write2_b32 v43, v88, v89 offset1:1
	s_waitcnt vmcnt(12)
	ds_write2_b32 v44, v90, v91 offset1:1
	ds_write2_b32 v45, v92, v93 offset1:1
	s_waitcnt vmcnt(11)
	ds_write2_b32 v46, v94, v95 offset1:1
	ds_write2_b32 v47, v96, v97 offset1:1
	s_waitcnt vmcnt(10)
	ds_write2_b32 v48, v98, v99 offset1:1
	ds_write2_b32 v49, v100, v101 offset1:1
	s_waitcnt vmcnt(9)
	ds_write2_b32 v50, v102, v103 offset1:1
	ds_write2_b32 v51, v104, v105 offset1:1
	s_waitcnt vmcnt(8)
; #define LAS __attribute__((address_space(3)))
; __device__ __forceinline__ void lds_wait() { asm volatile("s_waitcnt lgkmcnt(0)" ::: "memory"); }
; __device__ __forceinline__ void transpose_item(const float* W, int K, int N, bf16_t* WT, int gate, const float* kscale, LAS float* scr, int item, int lane) {
;     ...
;     const int c = lane & 7;
;     f32x4 k0v = {1.f, 1.f, 1.f, 1.f}, k1v = k0v;
;     if (kscale) { k0v = *(const f32x4*)(kscale + k0 + 8 * c); k1v = *(const f32x4*)(kscale + k0 + 8 * c + 4); }
; #pragma unroll
;     for (int j = 0; j < 8; ++j) { const int n = (lane >> 3) + 8 * j; const LAS float* s = scr + (8 * c) * 65 + n;
;         u32x4 o; o.x = pk2(s[0 * 65] * k0v[0], s[1 * 65] * k0v[1]); o.y = pk2(s[2 * 65] * k0v[2], s[3 * 65] * k0v[3]); o.z = pk2(s[4 * 65] * k1v[0], s[5 * 65] * k1v[1]); o.w = pk2(s[6 * 65] * k1v[2], s[7 * 65] * k1v[3]);
;         const int nn = n0 + n; const int row = gate < 0 ? nn : (256 * (nn >> 7) + 128 * gate + (nn & 127));
;         *(u32x4*)(WT + (size_t)row * K + k0 + 8 * c) = o; }
;     lds_wait();
	ds_write2_b32 v52, v106, v107 offset1:1
	ds_write2_b32 v53, v108, v109 offset1:1
	s_waitcnt vmcnt(7)
	ds_write2_b32 v54, v110, v111 offset1:1
	ds_write2_b32 v55, v112, v113 offset1:1
	s_waitcnt vmcnt(6)
	ds_write2_b32 v56, v114, v115 offset1:1
	ds_write2_b32 v57, v116, v117 offset1:1
	s_waitcnt vmcnt(5)
	ds_write2_b32 v58, v118, v119 offset1:1
	ds_write2_b32 v59, v120, v121 offset1:1
	s_waitcnt vmcnt(4)
	ds_write2_b32 v60, v122, v123 offset1:1
	ds_write2_b32 v61, v124, v125 offset1:1
	s_waitcnt vmcnt(3)
	ds_write2_b32 v62, v126, v127 offset1:1
	ds_write2_b32 v63, v128, v129 offset1:1
	s_waitcnt vmcnt(2)
	ds_write2_b32 v64, v130, v131 offset1:1
	ds_write2_b32 v65, v132, v133 offset1:1
	s_waitcnt vmcnt(1)
	ds_write2_b32 v66, v134, v135 offset1:1
	ds_write2_b32 v67, v136, v137 offset1:1
	s_waitcnt vmcnt(0)
	ds_write2_b32 v68, v138, v139 offset1:1
	ds_write2_b32 v69, v140, v141 offset1:1
	s_waitcnt lgkmcnt(0)
	ds_read2_b32 v[78:79], v31 offset1:65
	ds_read2_b32 v[80:81], v31 offset0:130 offset1:195
	ds_read2_b32 v[82:83], v70 offset0:4 offset1:69
	ds_read2_b32 v[84:85], v70 offset0:134 offset1:199
	ds_read2_b32 v[86:87], v32 offset1:65
	ds_read2_b32 v[88:89], v32 offset0:130 offset1:195
	ds_read2_b32 v[90:91], v71 offset0:4 offset1:69
	ds_read2_b32 v[92:93], v71 offset0:134 offset1:199
	ds_read2_b32 v[94:95], v33 offset1:65
	ds_read2_b32 v[96:97], v33 offset0:130 offset1:195
	ds_read2_b32 v[98:99], v72 offset0:4 offset1:69
	ds_read2_b32 v[100:101], v72 offset0:134 offset1:199
	ds_read2_b32 v[102:103], v34 offset1:65
	ds_read2_b32 v[104:105], v34 offset0:130 offset1:195
	ds_read2_b32 v[106:107], v73 offset0:4 offset1:69
	ds_read2_b32 v[108:109], v73 offset0:134 offset1:199
	ds_read2_b32 v[110:111], v35 offset1:65
	ds_read2_b32 v[112:113], v35 offset0:130 offset1:195
	ds_read2_b32 v[114:115], v74 offset0:4 offset1:69
	ds_read2_b32 v[116:117], v74 offset0:134 offset1:199
	ds_read2_b32 v[118:119], v36 offset1:65
	ds_read2_b32 v[120:121], v36 offset0:130 offset1:195
	ds_read2_b32 v[122:123], v75 offset0:4 offset1:69
	ds_read2_b32 v[124:125], v75 offset0:134 offset1:199
	ds_read2_b32 v[126:127], v37 offset1:65
	ds_read2_b32 v[128:129], v37 offset0:130 offset1:195
	ds_read2_b32 v[130:131], v76 offset0:4 offset1:69
	ds_read2_b32 v[132:133], v76 offset0:134 offset1:199
	ds_read2_b32 v[134:135], v38 offset1:65
	ds_read2_b32 v[136:137], v38 offset0:130 offset1:195
	ds_read2_b32 v[138:139], v77 offset0:4 offset1:69
	ds_read2_b32 v[140:141], v77 offset0:134 offset1:199
	s_ashr_i32 s19, s18, 31
	v_ashrrev_i32_e32 v145, 31, v144
	v_lshl_add_u64 v[142:143], s[18:19], 1, v[6:7]
	v_ashrrev_i32_e32 v147, 31, v146
	v_ashrrev_i32_e32 v149, 31, v148
	v_ashrrev_i32_e32 v151, 31, v150
	v_ashrrev_i32_e32 v153, 31, v152
	v_ashrrev_i32_e32 v155, 31, v154
	v_ashrrev_i32_e32 v157, 31, v156
	v_ashrrev_i32_e32 v159, 31, v158
	v_lshlrev_b64 v[144:145], 9, v[144:145]
	v_lshlrev_b64 v[146:147], 9, v[146:147]
	v_lshlrev_b64 v[148:149], 9, v[148:149]
	v_lshlrev_b64 v[150:151], 9, v[150:151]
	v_lshlrev_b64 v[152:153], 9, v[152:153]
	v_lshlrev_b64 v[154:155], 9, v[154:155]
	v_lshlrev_b64 v[156:157], 9, v[156:157]
	v_lshlrev_b64 v[158:159], 9, v[158:159]
	v_lshl_add_u64 v[144:145], v[142:143], 0, v[144:145]
	s_waitcnt lgkmcnt(14)
	v_cvt_pk_bf16_f32 v78, v78, v79
	v_cvt_pk_bf16_f32 v79, v80, v81
	v_cvt_pk_bf16_f32 v80, v82, v83
	v_cvt_pk_bf16_f32 v81, v84, v85
	v_lshl_add_u64 v[146:147], v[142:143], 0, v[146:147]
	v_lshl_add_u64 v[148:149], v[142:143], 0, v[148:149]
	v_lshl_add_u64 v[150:151], v[142:143], 0, v[150:151]
	v_lshl_add_u64 v[152:153], v[142:143], 0, v[152:153]
	v_lshl_add_u64 v[154:155], v[142:143], 0, v[154:155]
	v_lshl_add_u64 v[156:157], v[142:143], 0, v[156:157]
	v_lshl_add_u64 v[142:143], v[142:143], 0, v[158:159]
	v_cvt_pk_bf16_f32 v82, v86, v87
	v_cvt_pk_bf16_f32 v83, v88, v89
	v_cvt_pk_bf16_f32 v84, v90, v91
	v_cvt_pk_bf16_f32 v85, v92, v93
	v_cvt_pk_bf16_f32 v86, v94, v95
	v_cvt_pk_bf16_f32 v87, v96, v97
	v_cvt_pk_bf16_f32 v88, v98, v99
	v_cvt_pk_bf16_f32 v89, v100, v101
	v_cvt_pk_bf16_f32 v90, v102, v103
	v_cvt_pk_bf16_f32 v91, v104, v105
	v_cvt_pk_bf16_f32 v92, v106, v107
	v_cvt_pk_bf16_f32 v93, v108, v109
	v_cvt_pk_bf16_f32 v94, v110, v111
	v_cvt_pk_bf16_f32 v95, v112, v113
	s_waitcnt lgkmcnt(13)
	v_cvt_pk_bf16_f32 v96, v114, v115
	s_waitcnt lgkmcnt(12)
	v_cvt_pk_bf16_f32 v97, v116, v117
	s_waitcnt lgkmcnt(11)
	v_cvt_pk_bf16_f32 v98, v118, v119
	s_waitcnt lgkmcnt(10)
	v_cvt_pk_bf16_f32 v99, v120, v121
	s_waitcnt lgkmcnt(9)
	v_cvt_pk_bf16_f32 v100, v122, v123
	s_waitcnt lgkmcnt(8)
	v_cvt_pk_bf16_f32 v101, v124, v125
	s_waitcnt lgkmcnt(7)
	v_cvt_pk_bf16_f32 v102, v126, v127
	s_waitcnt lgkmcnt(6)
	v_cvt_pk_bf16_f32 v103, v128, v129
	s_waitcnt lgkmcnt(5)
	v_cvt_pk_bf16_f32 v104, v130, v131
	s_waitcnt lgkmcnt(4)
	v_cvt_pk_bf16_f32 v105, v132, v133
	s_waitcnt lgkmcnt(3)
	v_cvt_pk_bf16_f32 v106, v134, v135
	s_waitcnt lgkmcnt(2)
	v_cvt_pk_bf16_f32 v107, v136, v137
	s_waitcnt lgkmcnt(1)
	v_cvt_pk_bf16_f32 v108, v138, v139
	s_waitcnt lgkmcnt(0)
	v_cvt_pk_bf16_f32 v109, v140, v141
	global_store_dwordx4 v[144:145], v[78:81], off sc0 sc1
	global_store_dwordx4 v[146:147], v[82:85], off sc0 sc1
	global_store_dwordx4 v[148:149], v[86:89], off sc0 sc1
	global_store_dwordx4 v[150:151], v[90:93], off sc0 sc1
	global_store_dwordx4 v[152:153], v[94:97], off sc0 sc1
	global_store_dwordx4 v[154:155], v[98:101], off sc0 sc1
	global_store_dwordx4 v[156:157], v[102:105], off sc0 sc1
	global_store_dwordx4 v[142:143], v[106:109], off sc0 sc1
	s_waitcnt lgkmcnt(0)
	s_add_i32 s12, s12, s92
	s_add_i32 s7, s7, s38
	s_add_i32 s6, s6, s3
	s_cmp_lt_i32 s12, 16
	s_cbranch_scc1 .LBB0_32
	s_branch .LBB0_27

; #define LAS __attribute__((address_space(3)))
; __device__ __forceinline__ void lds_wait() { asm volatile("s_waitcnt lgkmcnt(0)" ::: "memory"); }
; __device__ __forceinline__ void transpose_item(const float* W, int K, int N, bf16_t* WT, int gate, const float* kscale, LAS float* scr, int item, int lane) {
;     const int nblk = N / 64, kb = item / nblk, nb = item % nblk, k0 = 64 * kb, n0 = 64 * nb;
;     const int c4 = (lane & 15) * 4, kr = lane >> 4;
;     f32x4 v[16];
; #pragma unroll
;     for (int i = 0; i < 16; ++i) v[i] = __builtin_nontemporal_load((const f32x4*)(W + (size_t)(k0 + 4 * i + kr) * N + n0 + c4));
; #pragma unroll
;     for (int i = 0; i < 16; ++i) { LAS float* d = scr + (4 * i + kr) * 65 + c4; d[0] = v[i][0]; d[1] = v[i][1]; d[2] = v[i][2]; d[3] = v[i][3]; }
;     lds_wait();
.LBB0_35:
	s_ashr_i32 s3, s1, 31
	s_lshr_b32 s3, s3, 27
	s_add_i32 s3, s1, s3
	s_ashr_i32 s3, s3, 5
	s_lshl_b32 s4, s3, 6
	s_lshl_b32 s3, s3, 11
	v_add_u32_e32 v64, s4, v21
	s_sub_i32 s6, s0, s3
	v_add_u32_e32 v66, 4, v64
	v_add_u32_e32 v68, 8, v64
	v_add_u32_e32 v70, 12, v64
	v_add_u32_e32 v72, 16, v64
	v_add_u32_e32 v74, 20, v64
	v_add_u32_e32 v76, 24, v64
	s_ashr_i32 s7, s6, 31
	v_ashrrev_i32_e32 v65, 31, v64
	v_add_u32_e32 v78, 28, v64
	v_add_u32_e32 v80, 32, v64
	v_add_u32_e32 v82, 36, v64
	v_add_u32_e32 v84, 40, v64
	v_add_u32_e32 v86, 44, v64
	v_add_u32_e32 v88, 48, v64
	v_add_u32_e32 v90, 52, v64
	v_add_u32_e32 v92, 56, v64
	v_add_u32_e32 v94, 60, v64
	v_add_u32_e32 v98, s6, v29
	v_add_u32_e32 v100, s6, v22
	v_add_u32_e32 v102, s6, v23
	v_add_u32_e32 v104, s6, v24
	v_add_u32_e32 v106, s6, v25
	v_add_u32_e32 v108, s6, v26
	v_add_u32_e32 v110, s6, v27
	v_add_u32_e32 v112, s6, v28
	v_ashrrev_i32_e32 v67, 31, v66
	v_ashrrev_i32_e32 v69, 31, v68
	v_ashrrev_i32_e32 v71, 31, v70
	v_ashrrev_i32_e32 v73, 31, v72
	v_ashrrev_i32_e32 v75, 31, v74
	v_ashrrev_i32_e32 v77, 31, v76
	s_ashr_i32 s5, s4, 31
	v_lshl_add_u64 v[114:115], s[6:7], 2, v[0:1]
	v_lshlrev_b64 v[64:65], 13, v[64:65]
	v_ashrrev_i32_e32 v79, 31, v78
	v_ashrrev_i32_e32 v81, 31, v80
	v_ashrrev_i32_e32 v83, 31, v82
	v_ashrrev_i32_e32 v85, 31, v84
	v_ashrrev_i32_e32 v87, 31, v86
	v_ashrrev_i32_e32 v89, 31, v88
	v_ashrrev_i32_e32 v91, 31, v90
	v_ashrrev_i32_e32 v93, 31, v92
	v_ashrrev_i32_e32 v95, 31, v94
	v_ashrrev_i32_e32 v99, 31, v98
	v_ashrrev_i32_e32 v101, 31, v100
	v_ashrrev_i32_e32 v103, 31, v102
	v_ashrrev_i32_e32 v105, 31, v104
	v_ashrrev_i32_e32 v107, 31, v106
	v_ashrrev_i32_e32 v109, 31, v108
	v_ashrrev_i32_e32 v111, 31, v110
	v_ashrrev_i32_e32 v113, 31, v112
	v_lshlrev_b64 v[116:117], 13, v[66:67]
	v_lshlrev_b64 v[68:69], 13, v[68:69]
	v_lshlrev_b64 v[70:71], 13, v[70:71]
	v_lshlrev_b64 v[72:73], 13, v[72:73]
	v_lshlrev_b64 v[74:75], 13, v[74:75]
	v_lshlrev_b64 v[76:77], 13, v[76:77]
	v_lshl_add_u64 v[96:97], s[4:5], 1, v[2:3]
	v_lshl_add_u64 v[64:65], v[114:115], 0, v[64:65]
	v_lshlrev_b64 v[78:79], 13, v[78:79]
	v_lshlrev_b64 v[80:81], 13, v[80:81]
	v_lshlrev_b64 v[82:83], 13, v[82:83]
	v_lshlrev_b64 v[84:85], 13, v[84:85]
	v_lshlrev_b64 v[86:87], 13, v[86:87]
	v_lshlrev_b64 v[88:89], 13, v[88:89]
	v_lshlrev_b64 v[90:91], 13, v[90:91]
	v_lshlrev_b64 v[92:93], 13, v[92:93]
	v_lshlrev_b64 v[94:95], 13, v[94:95]
	v_lshlrev_b64 v[98:99], 12, v[98:99]
	v_lshlrev_b64 v[100:101], 12, v[100:101]
	v_lshlrev_b64 v[102:103], 12, v[102:103]
	v_lshlrev_b64 v[104:105], 12, v[104:105]
	v_lshlrev_b64 v[106:107], 12, v[106:107]
	v_lshlrev_b64 v[108:109], 12, v[108:109]
	v_lshlrev_b64 v[110:111], 12, v[110:111]
	v_lshlrev_b64 v[112:113], 12, v[112:113]
	v_lshl_add_u64 v[116:117], v[114:115], 0, v[116:117]
	v_lshl_add_u64 v[118:119], v[114:115], 0, v[68:69]
	v_lshl_add_u64 v[120:121], v[114:115], 0, v[70:71]
	v_lshl_add_u64 v[122:123], v[114:115], 0, v[72:73]
	v_lshl_add_u64 v[124:125], v[114:115], 0, v[74:75]
	v_lshl_add_u64 v[126:127], v[114:115], 0, v[76:77]
	global_load_dwordx4 v[64:67], v[64:65], off nt
	v_lshl_add_u64 v[128:129], v[114:115], 0, v[78:79]
	v_lshl_add_u64 v[130:131], v[114:115], 0, v[80:81]
	v_lshl_add_u64 v[132:133], v[114:115], 0, v[82:83]
	v_lshl_add_u64 v[134:135], v[114:115], 0, v[84:85]
	v_lshl_add_u64 v[136:137], v[114:115], 0, v[86:87]
	v_lshl_add_u64 v[138:139], v[114:115], 0, v[88:89]
	v_lshl_add_u64 v[140:141], v[114:115], 0, v[90:91]
	v_lshl_add_u64 v[142:143], v[114:115], 0, v[92:93]
	v_lshl_add_u64 v[144:145], v[114:115], 0, v[94:95]
	v_lshl_add_u64 v[146:147], v[96:97], 0, v[98:99]
	v_lshl_add_u64 v[148:149], v[96:97], 0, v[100:101]
	v_lshl_add_u64 v[150:151], v[96:97], 0, v[102:103]
	v_lshl_add_u64 v[152:153], v[96:97], 0, v[104:105]
	v_lshl_add_u64 v[154:155], v[96:97], 0, v[106:107]
	v_lshl_add_u64 v[156:157], v[96:97], 0, v[108:109]
	v_lshl_add_u64 v[158:159], v[96:97], 0, v[110:111]
	v_lshl_add_u64 v[160:161], v[96:97], 0, v[112:113]
	global_load_dwordx4 v[68:71], v[116:117], off nt
	global_load_dwordx4 v[72:75], v[118:119], off nt
	global_load_dwordx4 v[76:79], v[120:121], off nt
	global_load_dwordx4 v[80:83], v[122:123], off nt
	global_load_dwordx4 v[84:87], v[124:125], off nt
	global_load_dwordx4 v[88:91], v[126:127], off nt
	global_load_dwordx4 v[92:95], v[128:129], off nt
	global_load_dwordx4 v[96:99], v[130:131], off nt
	global_load_dwordx4 v[100:103], v[132:133], off nt
	global_load_dwordx4 v[104:107], v[134:135], off nt
	global_load_dwordx4 v[108:111], v[136:137], off nt
	global_load_dwordx4 v[112:115], v[138:139], off nt
	global_load_dwordx4 v[116:119], v[140:141], off nt
	global_load_dwordx4 v[120:123], v[142:143], off nt
	global_load_dwordx4 v[124:127], v[144:145], off nt
	s_waitcnt vmcnt(15)
	ds_write2_b32 v30, v64, v65 offset1:1
	ds_write2_b32 v30, v66, v67 offset0:2 offset1:3
	s_waitcnt vmcnt(14)
	ds_write2_b32 v4, v68, v69 offset1:1
	ds_write2_b32 v5, v70, v71 offset1:1
	s_waitcnt vmcnt(13)
; #define LAS __attribute__((address_space(3)))
; __device__ __forceinline__ void lds_wait() { asm volatile("s_waitcnt lgkmcnt(0)" ::: "memory"); }
; __device__ __forceinline__ void transpose_item(const float* W, int K, int N, bf16_t* WT, int gate, const float* kscale, LAS float* scr, int item, int lane) {
;     ...
;     for (int i = 0; i < 16; ++i) { LAS float* d = scr + (4 * i + kr) * 65 + c4; d[0] = v[i][0]; d[1] = v[i][1]; d[2] = v[i][2]; d[3] = v[i][3]; }
;     lds_wait();
;     const int c = lane & 7;
;     f32x4 k0v = {1.f, 1.f, 1.f, 1.f}, k1v = k0v;
;     if (kscale) { k0v = *(const f32x4*)(kscale + k0 + 8 * c); k1v = *(const f32x4*)(kscale + k0 + 8 * c + 4); }
; #pragma unroll
;     for (int j = 0; j < 8; ++j) { const int n = (lane >> 3) + 8 * j; const LAS float* s = scr + (8 * c) * 65 + n;
;         u32x4 o; o.x = pk2(s[0 * 65] * k0v[0], s[1 * 65] * k0v[1]); o.y = pk2(s[2 * 65] * k0v[2], s[3 * 65] * k0v[3]); o.z = pk2(s[4 * 65] * k1v[0], s[5 * 65] * k1v[1]); o.w = pk2(s[6 * 65] * k1v[2], s[7 * 65] * k1v[3]);
;         const int nn = n0 + n; const int row = gate < 0 ? nn : (256 * (nn >> 7) + 128 * gate + (nn & 127));
;         *(u32x4*)(WT + (size_t)row * K + k0 + 8 * c) = o; }
;     lds_wait();
	ds_write2_b32 v6, v72, v73 offset1:1
	ds_write2_b32 v7, v74, v75 offset1:1
	s_waitcnt vmcnt(12)
	ds_write2_b32 v11, v76, v77 offset1:1
	ds_write2_b32 v12, v78, v79 offset1:1
	s_waitcnt vmcnt(11)
	ds_write2_b32 v13, v80, v81 offset1:1
	ds_write2_b32 v14, v82, v83 offset1:1
	s_waitcnt vmcnt(10)
	ds_write2_b32 v15, v84, v85 offset1:1
	ds_write2_b32 v16, v86, v87 offset1:1
	s_waitcnt vmcnt(9)
	ds_write2_b32 v17, v88, v89 offset1:1
	ds_write2_b32 v18, v90, v91 offset1:1
	s_waitcnt vmcnt(8)
	ds_write2_b32 v19, v92, v93 offset1:1
	ds_write2_b32 v39, v94, v95 offset1:1
	s_waitcnt vmcnt(7)
	ds_write2_b32 v40, v96, v97 offset1:1
	ds_write2_b32 v41, v98, v99 offset1:1
	s_waitcnt vmcnt(6)
	ds_write2_b32 v42, v100, v101 offset1:1
	ds_write2_b32 v43, v102, v103 offset1:1
	s_waitcnt vmcnt(5)
	ds_write2_b32 v44, v104, v105 offset1:1
	ds_write2_b32 v45, v106, v107 offset1:1
	s_waitcnt vmcnt(4)
	ds_write2_b32 v46, v108, v109 offset1:1
	ds_write2_b32 v47, v110, v111 offset1:1
	s_waitcnt vmcnt(3)
	ds_write2_b32 v48, v112, v113 offset1:1
	ds_write2_b32 v49, v114, v115 offset1:1
	s_waitcnt vmcnt(2)
	ds_write2_b32 v50, v116, v117 offset1:1
	ds_write2_b32 v51, v118, v119 offset1:1
	s_waitcnt vmcnt(1)
	ds_write2_b32 v52, v120, v121 offset1:1
	ds_write2_b32 v53, v122, v123 offset1:1
	s_waitcnt vmcnt(0)
	ds_write2_b32 v54, v124, v125 offset1:1
	ds_write2_b32 v55, v126, v127 offset1:1
	s_waitcnt lgkmcnt(0)
	ds_read2_b32 v[64:65], v31 offset1:65
	ds_read2_b32 v[66:67], v31 offset0:130 offset1:195
	ds_read2_b32 v[68:69], v56 offset0:4 offset1:69
	ds_read2_b32 v[70:71], v56 offset0:134 offset1:199
	ds_read2_b32 v[72:73], v32 offset1:65
	ds_read2_b32 v[74:75], v32 offset0:130 offset1:195
	ds_read2_b32 v[76:77], v57 offset0:4 offset1:69
	ds_read2_b32 v[78:79], v57 offset0:134 offset1:199
	ds_read2_b32 v[80:81], v33 offset1:65
	ds_read2_b32 v[82:83], v33 offset0:130 offset1:195
	ds_read2_b32 v[84:85], v58 offset0:4 offset1:69
	ds_read2_b32 v[86:87], v58 offset0:134 offset1:199
	ds_read2_b32 v[88:89], v34 offset1:65
	ds_read2_b32 v[90:91], v34 offset0:130 offset1:195
	ds_read2_b32 v[92:93], v59 offset0:4 offset1:69
	ds_read2_b32 v[94:95], v59 offset0:134 offset1:199
	ds_read2_b32 v[96:97], v35 offset1:65
	ds_read2_b32 v[98:99], v35 offset0:130 offset1:195
	ds_read2_b32 v[100:101], v60 offset0:4 offset1:69
	ds_read2_b32 v[102:103], v60 offset0:134 offset1:199
	ds_read2_b32 v[104:105], v36 offset1:65
	ds_read2_b32 v[106:107], v36 offset0:130 offset1:195
	ds_read2_b32 v[108:109], v61 offset0:4 offset1:69
	ds_read2_b32 v[110:111], v61 offset0:134 offset1:199
	ds_read2_b32 v[112:113], v37 offset1:65
	ds_read2_b32 v[114:115], v37 offset0:130 offset1:195
	ds_read2_b32 v[116:117], v62 offset0:4 offset1:69
	ds_read2_b32 v[118:119], v62 offset0:134 offset1:199
	ds_read2_b32 v[120:121], v38 offset1:65
	ds_read2_b32 v[122:123], v38 offset0:130 offset1:195
	ds_read2_b32 v[124:125], v63 offset0:4 offset1:69
	ds_read2_b32 v[126:127], v63 offset0:134 offset1:199
	s_waitcnt lgkmcnt(14)
	v_cvt_pk_bf16_f32 v64, v64, v65
	v_cvt_pk_bf16_f32 v65, v66, v67
	v_cvt_pk_bf16_f32 v66, v68, v69
	v_cvt_pk_bf16_f32 v67, v70, v71
	v_cvt_pk_bf16_f32 v68, v72, v73
	v_cvt_pk_bf16_f32 v69, v74, v75
	v_cvt_pk_bf16_f32 v70, v76, v77
	v_cvt_pk_bf16_f32 v71, v78, v79
	v_cvt_pk_bf16_f32 v72, v80, v81
	v_cvt_pk_bf16_f32 v73, v82, v83
	v_cvt_pk_bf16_f32 v74, v84, v85
	v_cvt_pk_bf16_f32 v75, v86, v87
	v_cvt_pk_bf16_f32 v76, v88, v89
	v_cvt_pk_bf16_f32 v77, v90, v91
	v_cvt_pk_bf16_f32 v78, v92, v93
	v_cvt_pk_bf16_f32 v79, v94, v95
	v_cvt_pk_bf16_f32 v80, v96, v97
	v_cvt_pk_bf16_f32 v81, v98, v99
	s_waitcnt lgkmcnt(13)
	v_cvt_pk_bf16_f32 v82, v100, v101
	s_waitcnt lgkmcnt(12)
	v_cvt_pk_bf16_f32 v83, v102, v103
	s_waitcnt lgkmcnt(11)
	v_cvt_pk_bf16_f32 v84, v104, v105
	s_waitcnt lgkmcnt(10)
	v_cvt_pk_bf16_f32 v85, v106, v107
	s_waitcnt lgkmcnt(9)
	v_cvt_pk_bf16_f32 v86, v108, v109
	s_waitcnt lgkmcnt(8)
	v_cvt_pk_bf16_f32 v87, v110, v111
	s_waitcnt lgkmcnt(7)
	v_cvt_pk_bf16_f32 v88, v112, v113
	s_waitcnt lgkmcnt(6)
	v_cvt_pk_bf16_f32 v89, v114, v115
	s_waitcnt lgkmcnt(5)
	v_cvt_pk_bf16_f32 v90, v116, v117
	s_waitcnt lgkmcnt(4)
	v_cvt_pk_bf16_f32 v91, v118, v119
	s_waitcnt lgkmcnt(3)
	v_cvt_pk_bf16_f32 v92, v120, v121
	s_waitcnt lgkmcnt(2)
	v_cvt_pk_bf16_f32 v93, v122, v123
	s_waitcnt lgkmcnt(1)
	v_cvt_pk_bf16_f32 v94, v124, v125
	s_waitcnt lgkmcnt(0)
	v_cvt_pk_bf16_f32 v95, v126, v127
	global_store_dwordx4 v[146:147], v[64:67], off sc0 sc1
	global_store_dwordx4 v[148:149], v[68:71], off sc0 sc1
	global_store_dwordx4 v[150:151], v[72:75], off sc0 sc1
	global_store_dwordx4 v[152:153], v[76:79], off sc0 sc1
	global_store_dwordx4 v[154:155], v[80:83], off sc0 sc1
	global_store_dwordx4 v[156:157], v[84:87], off sc0 sc1
	global_store_dwordx4 v[158:159], v[88:91], off sc0 sc1
	global_store_dwordx4 v[160:161], v[92:95], off sc0 sc1
	s_waitcnt lgkmcnt(0)
	s_add_i32 s1, s1, s92
	s_add_i32 s0, s0, s38
	s_cmpk_lt_i32 s1, 0x400
	s_cbranch_scc1 .LBB0_35

; #define LAS __attribute__((address_space(3)))
; __device__ __forceinline__ void lds_wait() { asm volatile("s_waitcnt lgkmcnt(0)" ::: "memory"); }
; __device__ __forceinline__ void transpose_item(const float* W, int K, int N, bf16_t* WT, int gate, const float* kscale, LAS float* scr, int item, int lane) {
;     ...
;     const int c = lane & 7;
;     f32x4 k0v = {1.f, 1.f, 1.f, 1.f}, k1v = k0v;
;     if (kscale) { k0v = *(const f32x4*)(kscale + k0 + 8 * c); k1v = *(const f32x4*)(kscale + k0 + 8 * c + 4); }
; #pragma unroll
;     for (int j = 0; j < 8; ++j) { const int n = (lane >> 3) + 8 * j; const LAS float* s = scr + (8 * c) * 65 + n;
;         u32x4 o; o.x = pk2(s[0 * 65] * k0v[0], s[1 * 65] * k0v[1]); o.y = pk2(s[2 * 65] * k0v[2], s[3 * 65] * k0v[3]); o.z = pk2(s[4 * 65] * k1v[0], s[5 * 65] * k1v[1]); o.w = pk2(s[6 * 65] * k1v[2], s[7 * 65] * k1v[3]);
;         const int nn = n0 + n; const int row = gate < 0 ? nn : (256 * (nn >> 7) + 128 * gate + (nn & 127));
;         *(u32x4*)(WT + (size_t)row * K + k0 + 8 * c) = o; }
;     lds_wait();
.LBB0_39:
	ds_read2_b32 v[68:69], v31 offset1:65
	ds_read2_b32 v[70:71], v31 offset0:130 offset1:195
	s_sub_i32 s27, 0, s27
	v_lshl_add_u64 v[18:19], s[4:5], 1, v[16:17]
	s_add_i32 s4, s27, s25
	s_waitcnt vmcnt(0) lgkmcnt(1)
	v_mul_f32_e32 v68, v4, v68
	v_mul_f32_e32 v69, v5, v69
	v_cvt_pk_bf16_f32 v68, v68, v69
	v_add_u32_e32 v69, 0x400, v31
	ds_read2_b32 v[72:73], v69 offset0:4 offset1:69
	ds_read2_b32 v[74:75], v69 offset0:134 offset1:199
	s_waitcnt lgkmcnt(2)
	v_mul_f32_e32 v70, v6, v70
	v_mul_f32_e32 v71, v7, v71
	v_cvt_pk_bf16_f32 v69, v70, v71
	s_waitcnt lgkmcnt(1)
	v_mul_f32_e32 v70, v0, v72
	v_mul_f32_e32 v71, v1, v73
	v_cvt_pk_bf16_f32 v70, v70, v71
	s_waitcnt lgkmcnt(0)
	v_mul_f32_e32 v71, v2, v74
	v_mul_f32_e32 v72, v3, v75
	ds_read2_b32 v[74:75], v32 offset1:65
	v_cvt_pk_bf16_f32 v71, v71, v72
	v_add_u32_e32 v72, s4, v29
	v_ashrrev_i32_e32 v73, 31, v72
	v_lshlrev_b64 v[72:73], 12, v[72:73]
	v_lshl_add_u64 v[72:73], v[18:19], 0, v[72:73]
	global_store_dwordx4 v[72:73], v[68:71], off sc0 sc1
	ds_read2_b32 v[70:71], v32 offset0:130 offset1:195
	s_add_i32 s26, s26, s92
	s_waitcnt lgkmcnt(1)
	v_mul_f32_e32 v68, v4, v74
	v_mul_f32_e32 v69, v5, v75
	v_cvt_pk_bf16_f32 v68, v68, v69
	v_add_u32_e32 v69, 0x400, v32
	ds_read2_b32 v[72:73], v69 offset0:4 offset1:69
	ds_read2_b32 v[74:75], v69 offset0:134 offset1:199
	s_waitcnt lgkmcnt(2)
	v_mul_f32_e32 v70, v6, v70
	v_mul_f32_e32 v71, v7, v71
	v_cvt_pk_bf16_f32 v69, v70, v71
	s_waitcnt lgkmcnt(1)
	v_mul_f32_e32 v70, v0, v72
	v_mul_f32_e32 v71, v1, v73
	v_cvt_pk_bf16_f32 v70, v70, v71
	s_waitcnt lgkmcnt(0)
	v_mul_f32_e32 v71, v2, v74
	v_mul_f32_e32 v72, v3, v75
	ds_read2_b32 v[74:75], v33 offset1:65
	v_cvt_pk_bf16_f32 v71, v71, v72
	v_add_u32_e32 v72, s4, v22
	v_ashrrev_i32_e32 v73, 31, v72
	v_lshlrev_b64 v[72:73], 12, v[72:73]
	v_lshl_add_u64 v[72:73], v[18:19], 0, v[72:73]
	global_store_dwordx4 v[72:73], v[68:71], off sc0 sc1
	ds_read2_b32 v[70:71], v33 offset0:130 offset1:195
	s_add_i32 s25, s25, s38
	s_waitcnt lgkmcnt(1)
	v_mul_f32_e32 v68, v4, v74
	v_mul_f32_e32 v69, v5, v75
	v_cvt_pk_bf16_f32 v68, v68, v69
	v_add_u32_e32 v69, 0x400, v33
	ds_read2_b32 v[72:73], v69 offset0:4 offset1:69
	ds_read2_b32 v[74:75], v69 offset0:134 offset1:199
	s_waitcnt lgkmcnt(2)
	v_mul_f32_e32 v70, v6, v70
	v_mul_f32_e32 v71, v7, v71
	v_cvt_pk_bf16_f32 v69, v70, v71
	s_waitcnt lgkmcnt(1)
	v_mul_f32_e32 v70, v0, v72
	v_mul_f32_e32 v71, v1, v73
	v_cvt_pk_bf16_f32 v70, v70, v71
	s_waitcnt lgkmcnt(0)
	v_mul_f32_e32 v71, v2, v74
	v_mul_f32_e32 v72, v3, v75
	ds_read2_b32 v[74:75], v34 offset1:65
	v_cvt_pk_bf16_f32 v71, v71, v72
	v_add_u32_e32 v72, s4, v23
	v_ashrrev_i32_e32 v73, 31, v72
	v_lshlrev_b64 v[72:73], 12, v[72:73]
	v_lshl_add_u64 v[72:73], v[18:19], 0, v[72:73]
	global_store_dwordx4 v[72:73], v[68:71], off sc0 sc1
	ds_read2_b32 v[70:71], v34 offset0:130 offset1:195
	s_cmpk_lt_i32 s26, 0x1000
	s_waitcnt lgkmcnt(1)
	v_mul_f32_e32 v68, v4, v74
	v_mul_f32_e32 v69, v5, v75
	v_cvt_pk_bf16_f32 v68, v68, v69
	v_add_u32_e32 v69, 0x400, v34
	ds_read2_b32 v[72:73], v69 offset0:4 offset1:69
	ds_read2_b32 v[74:75], v69 offset0:134 offset1:199
	s_waitcnt lgkmcnt(2)
	v_mul_f32_e32 v70, v6, v70
	v_mul_f32_e32 v71, v7, v71
	v_cvt_pk_bf16_f32 v69, v70, v71
	s_waitcnt lgkmcnt(1)
	v_mul_f32_e32 v70, v0, v72
	v_mul_f32_e32 v71, v1, v73
	v_cvt_pk_bf16_f32 v70, v70, v71
	s_waitcnt lgkmcnt(0)
; #define LAS __attribute__((address_space(3)))
; __device__ __forceinline__ void lds_wait() { asm volatile("s_waitcnt lgkmcnt(0)" ::: "memory"); }
; __device__ __forceinline__ void transpose_item(const float* W, int K, int N, bf16_t* WT, int gate, const float* kscale, LAS float* scr, int item, int lane) {
;     ...
;     const int c = lane & 7;
;     f32x4 k0v = {1.f, 1.f, 1.f, 1.f}, k1v = k0v;
;     if (kscale) { k0v = *(const f32x4*)(kscale + k0 + 8 * c); k1v = *(const f32x4*)(kscale + k0 + 8 * c + 4); }
; #pragma unroll
;     for (int j = 0; j < 8; ++j) { const int n = (lane >> 3) + 8 * j; const LAS float* s = scr + (8 * c) * 65 + n;
;         u32x4 o; o.x = pk2(s[0 * 65] * k0v[0], s[1 * 65] * k0v[1]); o.y = pk2(s[2 * 65] * k0v[2], s[3 * 65] * k0v[3]); o.z = pk2(s[4 * 65] * k1v[0], s[5 * 65] * k1v[1]); o.w = pk2(s[6 * 65] * k1v[2], s[7 * 65] * k1v[3]);
;         const int nn = n0 + n; const int row = gate < 0 ? nn : (256 * (nn >> 7) + 128 * gate + (nn & 127));
;         *(u32x4*)(WT + (size_t)row * K + k0 + 8 * c) = o; }
;     lds_wait();
	v_mul_f32_e32 v71, v2, v74
	v_mul_f32_e32 v72, v3, v75
	ds_read2_b32 v[74:75], v35 offset1:65
	v_cvt_pk_bf16_f32 v71, v71, v72
	v_add_u32_e32 v72, s4, v24
	v_ashrrev_i32_e32 v73, 31, v72
	v_lshlrev_b64 v[72:73], 12, v[72:73]
	v_lshl_add_u64 v[72:73], v[18:19], 0, v[72:73]
	global_store_dwordx4 v[72:73], v[68:71], off sc0 sc1
	ds_read2_b32 v[70:71], v35 offset0:130 offset1:195
	s_waitcnt lgkmcnt(1)
	v_mul_f32_e32 v68, v4, v74
	v_mul_f32_e32 v69, v5, v75
	v_cvt_pk_bf16_f32 v68, v68, v69
	v_add_u32_e32 v69, 0x400, v35
	ds_read2_b32 v[72:73], v69 offset0:4 offset1:69
	ds_read2_b32 v[74:75], v69 offset0:134 offset1:199
	s_waitcnt lgkmcnt(2)
	v_mul_f32_e32 v70, v6, v70
	v_mul_f32_e32 v71, v7, v71
	v_cvt_pk_bf16_f32 v69, v70, v71
	s_waitcnt lgkmcnt(1)
	v_mul_f32_e32 v70, v0, v72
	v_mul_f32_e32 v71, v1, v73
	v_cvt_pk_bf16_f32 v70, v70, v71
	s_waitcnt lgkmcnt(0)
	v_mul_f32_e32 v71, v2, v74
	v_mul_f32_e32 v72, v3, v75
	ds_read2_b32 v[74:75], v36 offset1:65
	v_cvt_pk_bf16_f32 v71, v71, v72
	v_add_u32_e32 v72, s4, v25
	v_ashrrev_i32_e32 v73, 31, v72
	v_lshlrev_b64 v[72:73], 12, v[72:73]
	v_lshl_add_u64 v[72:73], v[18:19], 0, v[72:73]
	global_store_dwordx4 v[72:73], v[68:71], off sc0 sc1
	ds_read2_b32 v[70:71], v36 offset0:130 offset1:195
	s_waitcnt lgkmcnt(1)
	v_mul_f32_e32 v68, v4, v74
	v_mul_f32_e32 v69, v5, v75
	v_cvt_pk_bf16_f32 v68, v68, v69
	v_add_u32_e32 v69, 0x400, v36
	ds_read2_b32 v[72:73], v69 offset0:4 offset1:69
	ds_read2_b32 v[74:75], v69 offset0:134 offset1:199
	s_waitcnt lgkmcnt(2)
	v_mul_f32_e32 v70, v6, v70
	v_mul_f32_e32 v71, v7, v71
	v_cvt_pk_bf16_f32 v69, v70, v71
	s_waitcnt lgkmcnt(1)
	v_mul_f32_e32 v70, v0, v72
	v_mul_f32_e32 v71, v1, v73
	v_cvt_pk_bf16_f32 v70, v70, v71
	s_waitcnt lgkmcnt(0)
	v_mul_f32_e32 v71, v2, v74
	v_mul_f32_e32 v72, v3, v75
	ds_read2_b32 v[74:75], v37 offset1:65
	v_cvt_pk_bf16_f32 v71, v71, v72
	v_add_u32_e32 v72, s4, v26
	v_ashrrev_i32_e32 v73, 31, v72
	v_lshlrev_b64 v[72:73], 12, v[72:73]
	v_lshl_add_u64 v[72:73], v[18:19], 0, v[72:73]
	global_store_dwordx4 v[72:73], v[68:71], off sc0 sc1
	ds_read2_b32 v[70:71], v37 offset0:130 offset1:195
	s_waitcnt lgkmcnt(1)
	v_mul_f32_e32 v68, v4, v74
	v_mul_f32_e32 v69, v5, v75
	v_cvt_pk_bf16_f32 v68, v68, v69
	v_add_u32_e32 v69, 0x400, v37
	ds_read2_b32 v[72:73], v69 offset0:4 offset1:69
	ds_read2_b32 v[74:75], v69 offset0:134 offset1:199
	s_waitcnt lgkmcnt(2)
	v_mul_f32_e32 v70, v6, v70
	v_mul_f32_e32 v71, v7, v71
	v_cvt_pk_bf16_f32 v69, v70, v71
	s_waitcnt lgkmcnt(1)
	v_mul_f32_e32 v70, v0, v72
	v_mul_f32_e32 v71, v1, v73
	v_cvt_pk_bf16_f32 v70, v70, v71
	s_waitcnt lgkmcnt(0)
	v_mul_f32_e32 v71, v2, v74
	v_mul_f32_e32 v72, v3, v75
	v_cvt_pk_bf16_f32 v71, v71, v72
	v_add_u32_e32 v72, s4, v27
	ds_read2_b32 v[74:75], v38 offset1:65
	v_ashrrev_i32_e32 v73, 31, v72
	v_lshlrev_b64 v[72:73], 12, v[72:73]
	v_lshl_add_u64 v[72:73], v[18:19], 0, v[72:73]
	global_store_dwordx4 v[72:73], v[68:71], off sc0 sc1
	ds_read2_b32 v[68:69], v38 offset0:130 offset1:195
	s_waitcnt lgkmcnt(1)
	v_mul_f32_e32 v4, v4, v74
	v_mul_f32_e32 v5, v5, v75
	v_cvt_pk_bf16_f32 v4, v4, v5
	v_add_u32_e32 v5, 0x400, v38
	ds_read2_b32 v[70:71], v5 offset0:4 offset1:69
	s_waitcnt lgkmcnt(1)
	v_mul_f32_e32 v6, v6, v68
	v_mul_f32_e32 v7, v7, v69
	ds_read2_b32 v[68:69], v5 offset0:134 offset1:199
	v_cvt_pk_bf16_f32 v5, v6, v7
	s_waitcnt lgkmcnt(1)
	v_mul_f32_e32 v0, v0, v70
	v_mul_f32_e32 v1, v1, v71
	v_cvt_pk_bf16_f32 v6, v0, v1
	s_waitcnt lgkmcnt(0)
	v_mul_f32_e32 v0, v2, v68
	v_mul_f32_e32 v1, v3, v69
	v_cvt_pk_bf16_f32 v7, v0, v1
	v_add_u32_e32 v0, s4, v28
	v_ashrrev_i32_e32 v1, 31, v0
	v_lshlrev_b64 v[0:1], 12, v[0:1]
	v_lshl_add_u64 v[0:1], v[18:19], 0, v[0:1]
	global_store_dwordx4 v[0:1], v[4:7], off sc0 sc1
	s_waitcnt lgkmcnt(0)
	s_cbranch_scc0 .LBB0_42

; #define LAS __attribute__((address_space(3)))
; __device__ __forceinline__ void lds_wait() { asm volatile("s_waitcnt lgkmcnt(0)" ::: "memory"); }
; __device__ __forceinline__ void transpose_item(const float* W, int K, int N, bf16_t* WT, int gate, const float* kscale, LAS float* scr, int item, int lane) {
;     const int nblk = N / 64, kb = item / nblk, nb = item % nblk, k0 = 64 * kb, n0 = 64 * nb;
;     const int c4 = (lane & 15) * 4, kr = lane >> 4;
;     f32x4 v[16];
; #pragma unroll
;     for (int i = 0; i < 16; ++i) v[i] = __builtin_nontemporal_load((const f32x4*)(W + (size_t)(k0 + 4 * i + kr) * N + n0 + c4));
; #pragma unroll
;     for (int i = 0; i < 16; ++i) { LAS float* d = scr + (4 * i + kr) * 65 + c4; d[0] = v[i][0]; d[1] = v[i][1]; d[2] = v[i][2]; d[3] = v[i][3]; }
;     lds_wait();
.LBB0_43:
	s_ashr_i32 s1, s0, 31
	s_lshr_b32 s1, s1, 27
	s_add_i32 s1, s0, s1
	s_ashr_i32 s1, s1, 5
	s_lshl_b32 s4, s1, 6
	s_lshl_b32 s1, s1, 11
	v_add_u32_e32 v4, s4, v21
	s_sub_i32 s6, s3, s1
	v_add_u32_e32 v6, 4, v4
	v_add_u32_e32 v8, 8, v4
	v_add_u32_e32 v10, 12, v4
	v_add_u32_e32 v12, 16, v4
	v_add_u32_e32 v14, 20, v4
	v_add_u32_e32 v16, 24, v4
	s_ashr_i32 s7, s6, 31
	v_ashrrev_i32_e32 v5, 31, v4
	v_add_u32_e32 v18, 28, v4
	v_add_u32_e32 v40, 32, v4
	v_add_u32_e32 v42, 36, v4
	v_add_u32_e32 v44, 40, v4
	v_add_u32_e32 v46, 44, v4
	v_add_u32_e32 v48, 48, v4
	v_add_u32_e32 v50, 52, v4
	v_add_u32_e32 v52, 56, v4
	v_add_u32_e32 v54, 60, v4
	v_add_u32_e32 v58, s6, v29
	v_add_u32_e32 v60, s6, v22
	v_add_u32_e32 v62, s6, v23
	v_add_u32_e32 v64, s6, v24
	v_add_u32_e32 v66, s6, v25
	v_add_u32_e32 v68, s6, v26
	v_add_u32_e32 v70, s6, v27
	v_add_u32_e32 v72, s6, v28
	v_ashrrev_i32_e32 v7, 31, v6
	v_ashrrev_i32_e32 v9, 31, v8
	v_ashrrev_i32_e32 v11, 31, v10
	v_ashrrev_i32_e32 v13, 31, v12
	v_ashrrev_i32_e32 v15, 31, v14
	v_ashrrev_i32_e32 v17, 31, v16
	s_ashr_i32 s5, s4, 31
	v_lshl_add_u64 v[74:75], s[6:7], 2, v[0:1]
	v_lshlrev_b64 v[4:5], 13, v[4:5]
	v_ashrrev_i32_e32 v19, 31, v18
	v_ashrrev_i32_e32 v41, 31, v40
	v_ashrrev_i32_e32 v43, 31, v42
	v_ashrrev_i32_e32 v45, 31, v44
	v_ashrrev_i32_e32 v47, 31, v46
	v_ashrrev_i32_e32 v49, 31, v48
	v_ashrrev_i32_e32 v51, 31, v50
	v_ashrrev_i32_e32 v53, 31, v52
	v_ashrrev_i32_e32 v55, 31, v54
	v_ashrrev_i32_e32 v59, 31, v58
	v_ashrrev_i32_e32 v61, 31, v60
	v_ashrrev_i32_e32 v63, 31, v62
	v_ashrrev_i32_e32 v65, 31, v64
	v_ashrrev_i32_e32 v67, 31, v66
	v_ashrrev_i32_e32 v69, 31, v68
	v_ashrrev_i32_e32 v71, 31, v70
	v_ashrrev_i32_e32 v73, 31, v72
	v_lshlrev_b64 v[6:7], 13, v[6:7]
	v_lshlrev_b64 v[8:9], 13, v[8:9]
	v_lshlrev_b64 v[10:11], 13, v[10:11]
	v_lshlrev_b64 v[12:13], 13, v[12:13]
	v_lshlrev_b64 v[14:15], 13, v[14:15]
	v_lshlrev_b64 v[16:17], 13, v[16:17]
	v_lshl_add_u64 v[56:57], s[4:5], 1, v[2:3]
	v_lshl_add_u64 v[4:5], v[74:75], 0, v[4:5]
	v_lshlrev_b64 v[18:19], 13, v[18:19]
	v_lshlrev_b64 v[40:41], 13, v[40:41]
	v_lshlrev_b64 v[42:43], 13, v[42:43]
	v_lshlrev_b64 v[44:45], 13, v[44:45]
	v_lshlrev_b64 v[46:47], 13, v[46:47]
	v_lshlrev_b64 v[48:49], 13, v[48:49]
	v_lshlrev_b64 v[50:51], 13, v[50:51]
	v_lshlrev_b64 v[52:53], 13, v[52:53]
	v_lshlrev_b64 v[54:55], 13, v[54:55]
	v_lshlrev_b64 v[58:59], 14, v[58:59]
	v_lshlrev_b64 v[60:61], 14, v[60:61]
	v_lshlrev_b64 v[62:63], 14, v[62:63]
	v_lshlrev_b64 v[64:65], 14, v[64:65]
	v_lshlrev_b64 v[66:67], 14, v[66:67]
	v_lshlrev_b64 v[68:69], 14, v[68:69]
	v_lshlrev_b64 v[70:71], 14, v[70:71]
	v_lshlrev_b64 v[72:73], 14, v[72:73]
	v_lshl_add_u64 v[76:77], v[74:75], 0, v[6:7]
	v_lshl_add_u64 v[78:79], v[74:75], 0, v[8:9]
	v_lshl_add_u64 v[80:81], v[74:75], 0, v[10:11]
	v_lshl_add_u64 v[82:83], v[74:75], 0, v[12:13]
	v_lshl_add_u64 v[84:85], v[74:75], 0, v[14:15]
	v_lshl_add_u64 v[86:87], v[74:75], 0, v[16:17]
	v_lshl_add_u64 v[88:89], v[74:75], 0, v[18:19]
	v_lshl_add_u64 v[90:91], v[74:75], 0, v[40:41]
	v_lshl_add_u64 v[92:93], v[74:75], 0, v[42:43]
	v_lshl_add_u64 v[94:95], v[74:75], 0, v[44:45]
	v_lshl_add_u64 v[96:97], v[74:75], 0, v[46:47]
	v_lshl_add_u64 v[98:99], v[74:75], 0, v[48:49]
	v_lshl_add_u64 v[100:101], v[74:75], 0, v[50:51]
	v_lshl_add_u64 v[102:103], v[74:75], 0, v[52:53]
	v_lshl_add_u64 v[104:105], v[74:75], 0, v[54:55]
	v_lshl_add_u64 v[106:107], v[56:57], 0, v[58:59]
	v_lshl_add_u64 v[108:109], v[56:57], 0, v[60:61]
	v_lshl_add_u64 v[110:111], v[56:57], 0, v[62:63]
	v_lshl_add_u64 v[112:113], v[56:57], 0, v[64:65]
	v_lshl_add_u64 v[114:115], v[56:57], 0, v[66:67]
	v_lshl_add_u64 v[116:117], v[56:57], 0, v[68:69]
	v_lshl_add_u64 v[118:119], v[56:57], 0, v[70:71]
	global_load_dwordx4 v[4:7], v[4:5], off nt
	v_lshl_add_u64 v[120:121], v[56:57], 0, v[72:73]
	global_load_dwordx4 v[8:11], v[76:77], off nt
	global_load_dwordx4 v[12:15], v[78:79], off nt
	global_load_dwordx4 v[16:19], v[80:81], off nt
	global_load_dwordx4 v[40:43], v[82:83], off nt
	global_load_dwordx4 v[44:47], v[84:85], off nt
	global_load_dwordx4 v[48:51], v[86:87], off nt
	global_load_dwordx4 v[52:55], v[88:89], off nt
	global_load_dwordx4 v[56:59], v[90:91], off nt
	global_load_dwordx4 v[60:63], v[92:93], off nt
	global_load_dwordx4 v[64:67], v[94:95], off nt
	global_load_dwordx4 v[68:71], v[96:97], off nt
	global_load_dwordx4 v[72:75], v[98:99], off nt
	global_load_dwordx4 v[76:79], v[100:101], off nt
	global_load_dwordx4 v[80:83], v[102:103], off nt
	global_load_dwordx4 v[84:87], v[104:105], off nt
	v_add_u32_e32 v39, 0x410, v30
	v_add_u32_e32 v122, 0x418, v30
	v_add_u32_e32 v123, 0x820, v30
	v_add_u32_e32 v124, 0x828, v30
	v_add_u32_e32 v125, 0xc30, v30
	v_add_u32_e32 v126, 0xc38, v30
	v_add_u32_e32 v127, 0x1040, v30
	v_add_u32_e32 v128, 0x1048, v30
	v_add_u32_e32 v129, 0x1450, v30
	v_add_u32_e32 v130, 0x1458, v30
	v_add_u32_e32 v131, 0x1860, v30
	v_add_u32_e32 v132, 0x1868, v30
	v_add_u32_e32 v133, 0x1c70, v30
	v_add_u32_e32 v134, 0x1c78, v30
	v_add_u32_e32 v135, 0x2080, v30
	v_add_u32_e32 v136, 0x2088, v30
	v_add_u32_e32 v137, 0x2490, v30
	v_add_u32_e32 v138, 0x2498, v30
	v_add_u32_e32 v139, 0x28a0, v30
	v_add_u32_e32 v140, 0x28a8, v30
	v_add_u32_e32 v141, 0x2cb0, v30
	v_add_u32_e32 v142, 0x2cb8, v30
	v_add_u32_e32 v143, 0x30c0, v30
	v_add_u32_e32 v144, 0x30c8, v30
	v_add_u32_e32 v145, 0x34d0, v30
	v_add_u32_e32 v146, 0x34d8, v30
	v_add_u32_e32 v147, 0x38e0, v30
	v_add_u32_e32 v148, 0x38e8, v30
	v_add_u32_e32 v149, 0x3cf0, v30
	v_add_u32_e32 v150, 0x3cf8, v30
	s_waitcnt vmcnt(15)
; #define LAS __attribute__((address_space(3)))
; __device__ __forceinline__ void lds_wait() { asm volatile("s_waitcnt lgkmcnt(0)" ::: "memory"); }
; __device__ __forceinline__ void transpose_item(const float* W, int K, int N, bf16_t* WT, int gate, const float* kscale, LAS float* scr, int item, int lane) {
;     ...
;     for (int i = 0; i < 16; ++i) { LAS float* d = scr + (4 * i + kr) * 65 + c4; d[0] = v[i][0]; d[1] = v[i][1]; d[2] = v[i][2]; d[3] = v[i][3]; }
;     lds_wait();
;     const int c = lane & 7;
;     f32x4 k0v = {1.f, 1.f, 1.f, 1.f}, k1v = k0v;
;     if (kscale) { k0v = *(const f32x4*)(kscale + k0 + 8 * c); k1v = *(const f32x4*)(kscale + k0 + 8 * c + 4); }
; #pragma unroll
;     for (int j = 0; j < 8; ++j) { const int n = (lane >> 3) + 8 * j; const LAS float* s = scr + (8 * c) * 65 + n;
;         u32x4 o; o.x = pk2(s[0 * 65] * k0v[0], s[1 * 65] * k0v[1]); o.y = pk2(s[2 * 65] * k0v[2], s[3 * 65] * k0v[3]); o.z = pk2(s[4 * 65] * k1v[0], s[5 * 65] * k1v[1]); o.w = pk2(s[6 * 65] * k1v[2], s[7 * 65] * k1v[3]);
;         const int nn = n0 + n; const int row = gate < 0 ? nn : (256 * (nn >> 7) + 128 * gate + (nn & 127));
;         *(u32x4*)(WT + (size_t)row * K + k0 + 8 * c) = o; }
;     lds_wait();
	ds_write2_b32 v30, v4, v5 offset1:1
	ds_write2_b32 v30, v6, v7 offset0:2 offset1:3
	s_waitcnt vmcnt(14)
	ds_write2_b32 v39, v8, v9 offset1:1
	ds_write2_b32 v122, v10, v11 offset1:1
	s_waitcnt vmcnt(13)
	ds_write2_b32 v123, v12, v13 offset1:1
	ds_write2_b32 v124, v14, v15 offset1:1
	s_waitcnt vmcnt(12)
	ds_write2_b32 v125, v16, v17 offset1:1
	ds_write2_b32 v126, v18, v19 offset1:1
	s_waitcnt vmcnt(11)
	ds_write2_b32 v127, v40, v41 offset1:1
	ds_write2_b32 v128, v42, v43 offset1:1
	s_waitcnt vmcnt(10)
	ds_write2_b32 v129, v44, v45 offset1:1
	ds_write2_b32 v130, v46, v47 offset1:1
	s_waitcnt vmcnt(9)
	ds_write2_b32 v131, v48, v49 offset1:1
	ds_write2_b32 v132, v50, v51 offset1:1
	s_waitcnt vmcnt(8)
	ds_write2_b32 v133, v52, v53 offset1:1
	ds_write2_b32 v134, v54, v55 offset1:1
	s_waitcnt vmcnt(7)
	ds_write2_b32 v135, v56, v57 offset1:1
	ds_write2_b32 v136, v58, v59 offset1:1
	s_waitcnt vmcnt(6)
	ds_write2_b32 v137, v60, v61 offset1:1
	ds_write2_b32 v138, v62, v63 offset1:1
	s_waitcnt vmcnt(5)
	ds_write2_b32 v139, v64, v65 offset1:1
	ds_write2_b32 v140, v66, v67 offset1:1
	s_waitcnt vmcnt(4)
	ds_write2_b32 v141, v68, v69 offset1:1
	ds_write2_b32 v142, v70, v71 offset1:1
	s_waitcnt vmcnt(3)
	ds_write2_b32 v143, v72, v73 offset1:1
	ds_write2_b32 v144, v74, v75 offset1:1
	s_waitcnt vmcnt(2)
	ds_write2_b32 v145, v76, v77 offset1:1
	ds_write2_b32 v146, v78, v79 offset1:1
	s_waitcnt vmcnt(1)
	ds_write2_b32 v147, v80, v81 offset1:1
	ds_write2_b32 v148, v82, v83 offset1:1
	s_waitcnt vmcnt(0)
	ds_write2_b32 v149, v84, v85 offset1:1
	ds_write2_b32 v150, v86, v87 offset1:1
	s_waitcnt lgkmcnt(0)
	v_add_u32_e32 v151, 0x400, v31
	v_add_u32_e32 v152, 0x400, v32
	v_add_u32_e32 v153, 0x400, v33
	v_add_u32_e32 v154, 0x400, v34
	v_add_u32_e32 v155, 0x400, v35
	v_add_u32_e32 v156, 0x400, v36
	v_add_u32_e32 v157, 0x400, v37
	v_add_u32_e32 v158, 0x400, v38
	ds_read2_b32 v[4:5], v31 offset1:65
	ds_read2_b32 v[6:7], v31 offset0:130 offset1:195
	ds_read2_b32 v[8:9], v151 offset0:4 offset1:69
	ds_read2_b32 v[10:11], v151 offset0:134 offset1:199
	ds_read2_b32 v[12:13], v32 offset1:65
	ds_read2_b32 v[14:15], v32 offset0:130 offset1:195
	ds_read2_b32 v[16:17], v152 offset0:4 offset1:69
	ds_read2_b32 v[18:19], v152 offset0:134 offset1:199
	ds_read2_b32 v[40:41], v33 offset1:65
	ds_read2_b32 v[42:43], v33 offset0:130 offset1:195
	ds_read2_b32 v[44:45], v153 offset0:4 offset1:69
	ds_read2_b32 v[46:47], v153 offset0:134 offset1:199
	ds_read2_b32 v[48:49], v34 offset1:65
	ds_read2_b32 v[50:51], v34 offset0:130 offset1:195
	ds_read2_b32 v[52:53], v154 offset0:4 offset1:69
	ds_read2_b32 v[54:55], v154 offset0:134 offset1:199
	ds_read2_b32 v[56:57], v35 offset1:65
	ds_read2_b32 v[58:59], v35 offset0:130 offset1:195
	ds_read2_b32 v[60:61], v155 offset0:4 offset1:69
	ds_read2_b32 v[62:63], v155 offset0:134 offset1:199
	ds_read2_b32 v[64:65], v36 offset1:65
	ds_read2_b32 v[66:67], v36 offset0:130 offset1:195
	ds_read2_b32 v[68:69], v156 offset0:4 offset1:69
	ds_read2_b32 v[70:71], v156 offset0:134 offset1:199
	ds_read2_b32 v[72:73], v37 offset1:65
	ds_read2_b32 v[74:75], v37 offset0:130 offset1:195
	ds_read2_b32 v[76:77], v157 offset0:4 offset1:69
	ds_read2_b32 v[78:79], v157 offset0:134 offset1:199
	ds_read2_b32 v[80:81], v38 offset1:65
	ds_read2_b32 v[82:83], v38 offset0:130 offset1:195
	ds_read2_b32 v[84:85], v158 offset0:4 offset1:69
	ds_read2_b32 v[86:87], v158 offset0:134 offset1:199
	s_waitcnt lgkmcnt(14)
	v_cvt_pk_bf16_f32 v4, v4, v5
	v_cvt_pk_bf16_f32 v5, v6, v7
	v_cvt_pk_bf16_f32 v6, v8, v9
	v_cvt_pk_bf16_f32 v7, v10, v11
	v_cvt_pk_bf16_f32 v8, v12, v13
	v_cvt_pk_bf16_f32 v9, v14, v15
	v_cvt_pk_bf16_f32 v10, v16, v17
	v_cvt_pk_bf16_f32 v11, v18, v19
	v_cvt_pk_bf16_f32 v12, v40, v41
	v_cvt_pk_bf16_f32 v13, v42, v43
	v_cvt_pk_bf16_f32 v14, v44, v45
	v_cvt_pk_bf16_f32 v15, v46, v47
	v_cvt_pk_bf16_f32 v16, v48, v49
	v_cvt_pk_bf16_f32 v17, v50, v51
	v_cvt_pk_bf16_f32 v18, v52, v53
	v_cvt_pk_bf16_f32 v19, v54, v55
	v_cvt_pk_bf16_f32 v40, v56, v57
	v_cvt_pk_bf16_f32 v41, v58, v59
	s_waitcnt lgkmcnt(13)
	v_cvt_pk_bf16_f32 v42, v60, v61
	s_waitcnt lgkmcnt(12)
	v_cvt_pk_bf16_f32 v43, v62, v63
	s_waitcnt lgkmcnt(11)
	v_cvt_pk_bf16_f32 v44, v64, v65
	s_waitcnt lgkmcnt(10)
	v_cvt_pk_bf16_f32 v45, v66, v67
	s_waitcnt lgkmcnt(9)
	v_cvt_pk_bf16_f32 v46, v68, v69
	s_waitcnt lgkmcnt(8)
	v_cvt_pk_bf16_f32 v47, v70, v71
	s_waitcnt lgkmcnt(7)
	v_cvt_pk_bf16_f32 v48, v72, v73
	s_waitcnt lgkmcnt(6)
	v_cvt_pk_bf16_f32 v49, v74, v75
	s_waitcnt lgkmcnt(5)
	v_cvt_pk_bf16_f32 v50, v76, v77
	s_waitcnt lgkmcnt(4)
	v_cvt_pk_bf16_f32 v51, v78, v79
	s_waitcnt lgkmcnt(3)
	v_cvt_pk_bf16_f32 v52, v80, v81
	s_waitcnt lgkmcnt(2)
	v_cvt_pk_bf16_f32 v53, v82, v83
	s_waitcnt lgkmcnt(1)
	v_cvt_pk_bf16_f32 v54, v84, v85
	s_waitcnt lgkmcnt(0)
	v_cvt_pk_bf16_f32 v55, v86, v87
	global_store_dwordx4 v[106:107], v[4:7], off sc0 sc1
	global_store_dwordx4 v[108:109], v[8:11], off sc0 sc1
	global_store_dwordx4 v[110:111], v[12:15], off sc0 sc1
	global_store_dwordx4 v[112:113], v[16:19], off sc0 sc1
	global_store_dwordx4 v[114:115], v[40:43], off sc0 sc1
	global_store_dwordx4 v[116:117], v[44:47], off sc0 sc1
	global_store_dwordx4 v[118:119], v[48:51], off sc0 sc1
	global_store_dwordx4 v[120:121], v[52:55], off sc0 sc1
	s_waitcnt lgkmcnt(0)
	s_add_i32 s0, s0, s92
	s_add_i32 s3, s3, s38
	s_cmpk_lt_i32 s0, 0x1000
	s_cbranch_scc1 .LBB0_43

; __device__ __forceinline__ float bflo(unsigned w) { return __uint_as_float(w << 16); }
; __device__ __forceinline__ float bfhi(unsigned w) { return __uint_as_float(w & 0xffff0000u); }
; __global__ void __launch_bounds__(512, 2) mega(Params p, int ph_lo, int ph_hi) {
;     ...
;         for (int idx = gt; idx < NTOK * 128; idx += NGT) {
;             const int t = idx >> 7, c8 = (idx & 127) * 8, pos = t & (SEQ - 1);
;             float a[8];
;             { const f32x4 b0 = *(const f32x4*)(p.conv_b + c8), b1 = *(const f32x4*)(p.conv_b + c8 + 4); a[0] = b0[0]; a[1] = b0[1]; a[2] = b0[2]; a[3] = b0[3]; a[4] = b1[0]; a[5] = b1[1]; a[6] = b1[2]; a[7] = b1[3]; }
; #pragma unroll
;             for (int j = 0; j < 4; ++j) {
;                 if (pos - 3 + j >= 0) {
;                     const u32x4 xw = *(const u32x4*)(BIG + (size_t)(t - 3 + j) * INC + c8);
;                     const f32x4 w0 = *(const f32x4*)(p.conv_w + j * 1024 + c8), w1 = *(const f32x4*)(p.conv_w + j * 1024 + c8 + 4);
;                     a[0] += w0[0] * bflo(xw.x); a[1] += w0[1] * bfhi(xw.x); a[2] += w0[2] * bflo(xw.y); a[3] += w0[3] * bfhi(xw.y);
;                     a[4] += w1[0] * bflo(xw.z); a[5] += w1[1] * bfhi(xw.z); a[6] += w1[2] * bflo(xw.w); a[7] += w1[3] * bfhi(xw.w);
;                 }
;             }
;             u32x4 o; o.x = pk2(a[0], a[1]); o.y = pk2(a[2], a[3]); o.z = pk2(a[4], a[5]); o.w = pk2(a[6], a[7]);
;             *(u32x4*)(XN + (size_t)t * 1024 + c8) = o;
;         }
.Lcv_A:
	v_add_u32_e32 v25, s38, v9
	v_ashrrev_i32_e32 v26, 7, v25
	v_add_u32_e32 v27, -3, v26
	v_mad_i64_i32 v[28:29], s[12:13], v27, s18, v[168:169]
	v_lshl_add_u64 v[30:31], v[28:29], 0, s[98:99]
	v_lshl_add_u64 v[32:33], v[30:31], 0, s[98:99]
	v_lshl_add_u64 v[34:35], v[32:33], 0, s[98:99]
	global_load_dwordx4 v[152:155], v[28:29], off
	global_load_dwordx4 v[156:159], v[30:31], off
	global_load_dwordx4 v[160:163], v[32:33], off
	global_load_dwordx4 v[164:167], v[34:35], off
	v_and_b32_e32 v15, 0x1fff, v14
	v_cmp_lt_u32_e64 s[6:7], 2, v15
	v_cmp_lt_u32_e64 s[8:9], 1, v15
	v_cmp_ne_u32_e64 s[10:11], 0, v15
	v_ashrrev_i32_e32 v15, 31, v14
	v_lshlrev_b64 v[16:17], 11, v[14:15]
	v_lshl_add_u64 v[16:17], v[170:171], 0, v[16:17]
	s_waitcnt vmcnt(4)
	v_mov_b64_e32 v[4:5], v[96:97]
	v_mov_b64_e32 v[6:7], v[98:99]
	v_mov_b64_e32 v[0:1], v[100:101]
	v_mov_b64_e32 v[2:3], v[102:103]
	v_cndmask_b32_e64 v36, 0, v136, s[6:7]
	v_cndmask_b32_e64 v37, 0, v137, s[6:7]
	v_cndmask_b32_e64 v38, 0, v138, s[6:7]
	v_cndmask_b32_e64 v39, 0, v139, s[6:7]
	v_lshlrev_b32_e32 v40, 16, v36
	v_and_b32_e32 v41, 0xffff0000, v36
	v_lshlrev_b32_e32 v42, 16, v37
	v_and_b32_e32 v43, 0xffff0000, v37
	v_lshlrev_b32_e32 v44, 16, v38
	v_and_b32_e32 v45, 0xffff0000, v38
	v_lshlrev_b32_e32 v46, 16, v39
	v_and_b32_e32 v47, 0xffff0000, v39
	v_pk_fma_f32 v[4:5], v[104:105], v[40:41], v[4:5]
	v_pk_fma_f32 v[6:7], v[106:107], v[42:43], v[6:7]
	v_pk_fma_f32 v[0:1], v[108:109], v[44:45], v[0:1]
	v_pk_fma_f32 v[2:3], v[110:111], v[46:47], v[2:3]
	v_cndmask_b32_e64 v36, 0, v140, s[8:9]
	v_cndmask_b32_e64 v37, 0, v141, s[8:9]
	v_cndmask_b32_e64 v38, 0, v142, s[8:9]
	v_cndmask_b32_e64 v39, 0, v143, s[8:9]
	v_lshlrev_b32_e32 v40, 16, v36
	v_and_b32_e32 v41, 0xffff0000, v36
	v_lshlrev_b32_e32 v42, 16, v37
	v_and_b32_e32 v43, 0xffff0000, v37
	v_lshlrev_b32_e32 v44, 16, v38
	v_and_b32_e32 v45, 0xffff0000, v38
	v_lshlrev_b32_e32 v46, 16, v39
	v_and_b32_e32 v47, 0xffff0000, v39
	v_pk_fma_f32 v[4:5], v[112:113], v[40:41], v[4:5]
	v_pk_fma_f32 v[6:7], v[114:115], v[42:43], v[6:7]
	v_pk_fma_f32 v[0:1], v[116:117], v[44:45], v[0:1]
	v_pk_fma_f32 v[2:3], v[118:119], v[46:47], v[2:3]
	v_cndmask_b32_e64 v36, 0, v144, s[10:11]
	v_cndmask_b32_e64 v37, 0, v145, s[10:11]
	v_cndmask_b32_e64 v38, 0, v146, s[10:11]
	v_cndmask_b32_e64 v39, 0, v147, s[10:11]
	v_lshlrev_b32_e32 v40, 16, v36
	v_and_b32_e32 v41, 0xffff0000, v36
	v_lshlrev_b32_e32 v42, 16, v37
	v_and_b32_e32 v43, 0xffff0000, v37
	v_lshlrev_b32_e32 v44, 16, v38
	v_and_b32_e32 v45, 0xffff0000, v38
	v_lshlrev_b32_e32 v46, 16, v39
	v_and_b32_e32 v47, 0xffff0000, v39
	v_pk_fma_f32 v[4:5], v[120:121], v[40:41], v[4:5]
	v_pk_fma_f32 v[6:7], v[122:123], v[42:43], v[6:7]
	v_pk_fma_f32 v[0:1], v[124:125], v[44:45], v[0:1]
	v_pk_fma_f32 v[2:3], v[126:127], v[46:47], v[2:3]
	v_lshlrev_b32_e32 v40, 16, v148
	v_and_b32_e32 v41, 0xffff0000, v148
	v_lshlrev_b32_e32 v42, 16, v149
	v_and_b32_e32 v43, 0xffff0000, v149
	v_lshlrev_b32_e32 v44, 16, v150
	v_and_b32_e32 v45, 0xffff0000, v150
	v_lshlrev_b32_e32 v46, 16, v151
	v_and_b32_e32 v47, 0xffff0000, v151
	v_pk_fma_f32 v[4:5], v[128:129], v[40:41], v[4:5]
	v_pk_fma_f32 v[6:7], v[130:131], v[42:43], v[6:7]
	v_pk_fma_f32 v[0:1], v[132:133], v[44:45], v[0:1]
	v_pk_fma_f32 v[2:3], v[134:135], v[46:47], v[2:3]
	v_cvt_pk_bf16_f32 v36, v4, v5
	v_cvt_pk_bf16_f32 v37, v6, v7
	v_cvt_pk_bf16_f32 v38, v0, v1
	v_cvt_pk_bf16_f32 v39, v2, v3
	global_store_dwordx4 v[16:17], v[36:39], off sc0 sc1
	v_mov_b32_e32 v9, v25
	v_mov_b32_e32 v14, v26
	v_cmp_lt_i32_e32 vcc, s19, v9
	s_or_b64 s[4:5], vcc, s[4:5]
	s_andn2_b64 exec, exec, s[4:5]
	s_cbranch_execz .LBB0_92
; __device__ __forceinline__ float bflo(unsigned w) { return __uint_as_float(w << 16); }
; __device__ __forceinline__ float bfhi(unsigned w) { return __uint_as_float(w & 0xffff0000u); }
; __global__ void __launch_bounds__(512, 2) mega(Params p, int ph_lo, int ph_hi) {
;     ...
;         for (int idx = gt; idx < NTOK * 128; idx += NGT) {
;             const int t = idx >> 7, c8 = (idx & 127) * 8, pos = t & (SEQ - 1);
;             float a[8];
;             { const f32x4 b0 = *(const f32x4*)(p.conv_b + c8), b1 = *(const f32x4*)(p.conv_b + c8 + 4); a[0] = b0[0]; a[1] = b0[1]; a[2] = b0[2]; a[3] = b0[3]; a[4] = b1[0]; a[5] = b1[1]; a[6] = b1[2]; a[7] = b1[3]; }
; #pragma unroll
;             for (int j = 0; j < 4; ++j) {
;                 if (pos - 3 + j >= 0) {
;                     const u32x4 xw = *(const u32x4*)(BIG + (size_t)(t - 3 + j) * INC + c8);
;                     const f32x4 w0 = *(const f32x4*)(p.conv_w + j * 1024 + c8), w1 = *(const f32x4*)(p.conv_w + j * 1024 + c8 + 4);
;                     a[0] += w0[0] * bflo(xw.x); a[1] += w0[1] * bfhi(xw.x); a[2] += w0[2] * bflo(xw.y); a[3] += w0[3] * bfhi(xw.y);
;                     a[4] += w1[0] * bflo(xw.z); a[5] += w1[1] * bfhi(xw.z); a[6] += w1[2] * bflo(xw.w); a[7] += w1[3] * bfhi(xw.w);
;                 }
;             }
;             u32x4 o; o.x = pk2(a[0], a[1]); o.y = pk2(a[2], a[3]); o.z = pk2(a[4], a[5]); o.w = pk2(a[6], a[7]);
;             *(u32x4*)(XN + (size_t)t * 1024 + c8) = o;
;         }
.Lcv_B:
	v_add_u32_e32 v25, s38, v9
	v_ashrrev_i32_e32 v26, 7, v25
	v_add_u32_e32 v27, -3, v26
	v_mad_i64_i32 v[28:29], s[12:13], v27, s18, v[168:169]
	v_lshl_add_u64 v[30:31], v[28:29], 0, s[98:99]
	v_lshl_add_u64 v[32:33], v[30:31], 0, s[98:99]
	v_lshl_add_u64 v[34:35], v[32:33], 0, s[98:99]
	global_load_dwordx4 v[136:139], v[28:29], off
	global_load_dwordx4 v[140:143], v[30:31], off
	global_load_dwordx4 v[144:147], v[32:33], off
	global_load_dwordx4 v[148:151], v[34:35], off
	v_and_b32_e32 v15, 0x1fff, v14
	v_cmp_lt_u32_e64 s[6:7], 2, v15
	v_cmp_lt_u32_e64 s[8:9], 1, v15
	v_cmp_ne_u32_e64 s[10:11], 0, v15
	v_ashrrev_i32_e32 v15, 31, v14
	v_lshlrev_b64 v[16:17], 11, v[14:15]
	v_lshl_add_u64 v[16:17], v[170:171], 0, v[16:17]
	s_waitcnt vmcnt(4)
	v_mov_b64_e32 v[4:5], v[96:97]
	v_mov_b64_e32 v[6:7], v[98:99]
	v_mov_b64_e32 v[0:1], v[100:101]
	v_mov_b64_e32 v[2:3], v[102:103]
	v_cndmask_b32_e64 v36, 0, v152, s[6:7]
	v_cndmask_b32_e64 v37, 0, v153, s[6:7]
	v_cndmask_b32_e64 v38, 0, v154, s[6:7]
	v_cndmask_b32_e64 v39, 0, v155, s[6:7]
	v_lshlrev_b32_e32 v40, 16, v36
	v_and_b32_e32 v41, 0xffff0000, v36
	v_lshlrev_b32_e32 v42, 16, v37
	v_and_b32_e32 v43, 0xffff0000, v37
	v_lshlrev_b32_e32 v44, 16, v38
	v_and_b32_e32 v45, 0xffff0000, v38
	v_lshlrev_b32_e32 v46, 16, v39
	v_and_b32_e32 v47, 0xffff0000, v39
	v_pk_fma_f32 v[4:5], v[104:105], v[40:41], v[4:5]
	v_pk_fma_f32 v[6:7], v[106:107], v[42:43], v[6:7]
	v_pk_fma_f32 v[0:1], v[108:109], v[44:45], v[0:1]
	v_pk_fma_f32 v[2:3], v[110:111], v[46:47], v[2:3]
	v_cndmask_b32_e64 v36, 0, v156, s[8:9]
	v_cndmask_b32_e64 v37, 0, v157, s[8:9]
	v_cndmask_b32_e64 v38, 0, v158, s[8:9]
	v_cndmask_b32_e64 v39, 0, v159, s[8:9]
	v_lshlrev_b32_e32 v40, 16, v36
	v_and_b32_e32 v41, 0xffff0000, v36
	v_lshlrev_b32_e32 v42, 16, v37
	v_and_b32_e32 v43, 0xffff0000, v37
	v_lshlrev_b32_e32 v44, 16, v38
	v_and_b32_e32 v45, 0xffff0000, v38
	v_lshlrev_b32_e32 v46, 16, v39
	v_and_b32_e32 v47, 0xffff0000, v39
	v_pk_fma_f32 v[4:5], v[112:113], v[40:41], v[4:5]
	v_pk_fma_f32 v[6:7], v[114:115], v[42:43], v[6:7]
	v_pk_fma_f32 v[0:1], v[116:117], v[44:45], v[0:1]
	v_pk_fma_f32 v[2:3], v[118:119], v[46:47], v[2:3]
	v_cndmask_b32_e64 v36, 0, v160, s[10:11]
	v_cndmask_b32_e64 v37, 0, v161, s[10:11]
	v_cndmask_b32_e64 v38, 0, v162, s[10:11]
	v_cndmask_b32_e64 v39, 0, v163, s[10:11]
	v_lshlrev_b32_e32 v40, 16, v36
	v_and_b32_e32 v41, 0xffff0000, v36
	v_lshlrev_b32_e32 v42, 16, v37
	v_and_b32_e32 v43, 0xffff0000, v37
	v_lshlrev_b32_e32 v44, 16, v38
	v_and_b32_e32 v45, 0xffff0000, v38
	v_lshlrev_b32_e32 v46, 16, v39
	v_and_b32_e32 v47, 0xffff0000, v39
	v_pk_fma_f32 v[4:5], v[120:121], v[40:41], v[4:5]
	v_pk_fma_f32 v[6:7], v[122:123], v[42:43], v[6:7]
	v_pk_fma_f32 v[0:1], v[124:125], v[44:45], v[0:1]
	v_pk_fma_f32 v[2:3], v[126:127], v[46:47], v[2:3]
	v_lshlrev_b32_e32 v40, 16, v164
	v_and_b32_e32 v41, 0xffff0000, v164
	v_lshlrev_b32_e32 v42, 16, v165
	v_and_b32_e32 v43, 0xffff0000, v165
	v_lshlrev_b32_e32 v44, 16, v166
	v_and_b32_e32 v45, 0xffff0000, v166
	v_lshlrev_b32_e32 v46, 16, v167
	v_and_b32_e32 v47, 0xffff0000, v167
	v_pk_fma_f32 v[4:5], v[128:129], v[40:41], v[4:5]
	v_pk_fma_f32 v[6:7], v[130:131], v[42:43], v[6:7]
	v_pk_fma_f32 v[0:1], v[132:133], v[44:45], v[0:1]
	v_pk_fma_f32 v[2:3], v[134:135], v[46:47], v[2:3]
	v_cvt_pk_bf16_f32 v36, v4, v5
	v_cvt_pk_bf16_f32 v37, v6, v7
	v_cvt_pk_bf16_f32 v38, v0, v1
	v_cvt_pk_bf16_f32 v39, v2, v3
	global_store_dwordx4 v[16:17], v[36:39], off sc0 sc1
	v_mov_b32_e32 v9, v25
	v_mov_b32_e32 v14, v26
	v_cmp_lt_i32_e32 vcc, s19, v9
	s_or_b64 s[4:5], vcc, s[4:5]
	s_andn2_b64 exec, exec, s[4:5]
	s_cbranch_execz .LBB0_92
	s_branch .Lcv_A

; #define LAS __attribute__((address_space(3)))
; __device__ __forceinline__ void lds_wait() { asm volatile("s_waitcnt lgkmcnt(0)" ::: "memory"); }
; __device__ __forceinline__ void transpose_item(const float* W, int K, int N, bf16_t* WT, int gate, const float* kscale, LAS float* scr, int item, int lane) {
;     const int nblk = N / 64, kb = item / nblk, nb = item % nblk, k0 = 64 * kb, n0 = 64 * nb;
;     const int c4 = (lane & 15) * 4, kr = lane >> 4;
;     f32x4 v[16];
; #pragma unroll
;     for (int i = 0; i < 16; ++i) v[i] = __builtin_nontemporal_load((const f32x4*)(W + (size_t)(k0 + 4 * i + kr) * N + n0 + c4));
; #pragma unroll
;     for (int i = 0; i < 16; ++i) { LAS float* d = scr + (4 * i + kr) * 65 + c4; d[0] = v[i][0]; d[1] = v[i][1]; d[2] = v[i][2]; d[3] = v[i][3]; }
;     lds_wait();
.LBB0_562:
	s_mul_hi_i32 s4, s3, 0x2aaaaaab
	s_lshr_b32 s5, s4, 31
	s_ashr_i32 s4, s4, 4
	s_add_i32 s5, s4, s5
	s_lshl_b32 s4, s5, 6
	s_mulk_i32 s5, 0xe800
	s_add_i32 s6, s0, s5
	v_add_u32_e32 v43, s4, v8
	s_ashr_i32 s7, s6, 31
	s_ashr_i32 s5, s4, 31
	v_add_u32_e32 v48, 4, v43
	v_add_u32_e32 v49, 8, v43
	v_add_u32_e32 v50, 12, v43
	v_add_u32_e32 v51, 16, v43
	v_add_u32_e32 v52, 20, v43
	v_add_u32_e32 v53, 24, v43
	v_add_u32_e32 v54, 28, v43
	v_add_u32_e32 v55, 32, v43
	v_add_u32_e32 v56, 36, v43
	v_add_u32_e32 v57, 40, v43
	v_add_u32_e32 v58, 44, v43
	v_add_u32_e32 v59, 48, v43
	v_add_u32_e32 v60, 52, v43
	v_add_u32_e32 v61, 56, v43
	v_add_u32_e32 v62, 60, v43
	v_add_u32_e32 v44, s6, v9
	v_lshl_add_u64 v[46:47], s[6:7], 2, v[2:3]
	v_lshl_add_u64 v[108:109], s[4:5], 2, v[4:5]
	v_lshl_add_u64 v[110:111], s[4:5], 1, v[6:7]
	v_ashrrev_i32_e32 v45, 31, v44
	v_mad_i64_i32 v[76:77], s[4:5], v43, s1, v[46:47]
	v_mad_i64_i32 v[78:79], s[4:5], v48, s1, v[46:47]
	v_mad_i64_i32 v[80:81], s[4:5], v49, s1, v[46:47]
	v_mad_i64_i32 v[82:83], s[4:5], v50, s1, v[46:47]
	v_mad_i64_i32 v[84:85], s[4:5], v51, s1, v[46:47]
	v_mad_i64_i32 v[86:87], s[4:5], v52, s1, v[46:47]
	v_mad_i64_i32 v[88:89], s[4:5], v53, s1, v[46:47]
	v_mad_i64_i32 v[90:91], s[4:5], v54, s1, v[46:47]
	v_mad_i64_i32 v[92:93], s[4:5], v55, s1, v[46:47]
	v_mad_i64_i32 v[94:95], s[4:5], v56, s1, v[46:47]
	v_mad_i64_i32 v[96:97], s[4:5], v57, s1, v[46:47]
	v_mad_i64_i32 v[98:99], s[4:5], v58, s1, v[46:47]
	v_mad_i64_i32 v[100:101], s[4:5], v59, s1, v[46:47]
	v_mad_i64_i32 v[102:103], s[4:5], v60, s1, v[46:47]
	v_mad_i64_i32 v[104:105], s[4:5], v61, s1, v[46:47]
	v_mad_i64_i32 v[106:107], s[4:5], v62, s1, v[46:47]
	v_add_u32_e32 v112, 8, v44
	v_add_u32_e32 v114, 16, v44
	v_add_u32_e32 v116, 24, v44
	v_add_u32_e32 v118, 32, v44
	v_add_u32_e32 v120, 40, v44
	v_add_u32_e32 v122, 48, v44
	v_add_u32_e32 v124, 56, v44
	v_lshlrev_b64 v[126:127], 12, v[44:45]
	global_load_dwordx4 v[44:47], v[76:77], off nt
	global_load_dwordx4 v[48:51], v[78:79], off nt
	global_load_dwordx4 v[52:55], v[80:81], off nt
	global_load_dwordx4 v[56:59], v[82:83], off nt
	global_load_dwordx4 v[60:63], v[84:85], off nt
	global_load_dwordx4 v[64:67], v[86:87], off nt
	global_load_dwordx4 v[68:71], v[88:89], off nt
	global_load_dwordx4 v[72:75], v[90:91], off nt
	global_load_dwordx4 v[76:79], v[92:93], off nt
	global_load_dwordx4 v[80:83], v[94:95], off nt
	s_nop 0
	global_load_dwordx4 v[84:87], v[96:97], off nt
	global_load_dwordx4 v[88:91], v[98:99], off nt
	global_load_dwordx4 v[92:95], v[100:101], off nt
	s_nop 0
	global_load_dwordx4 v[96:99], v[102:103], off nt
	s_nop 0
	global_load_dwordx4 v[100:103], v[104:105], off nt
	s_nop 0
	global_load_dwordx4 v[104:107], v[106:107], off nt
	v_ashrrev_i32_e32 v113, 31, v112
	v_ashrrev_i32_e32 v115, 31, v114
	v_ashrrev_i32_e32 v117, 31, v116
	v_ashrrev_i32_e32 v119, 31, v118
	v_ashrrev_i32_e32 v121, 31, v120
	v_ashrrev_i32_e32 v123, 31, v122
	v_ashrrev_i32_e32 v125, 31, v124
	v_lshlrev_b64 v[112:113], 12, v[112:113]
	v_lshlrev_b64 v[114:115], 12, v[114:115]
	v_lshlrev_b64 v[116:117], 12, v[116:117]
	v_lshlrev_b64 v[118:119], 12, v[118:119]
	v_lshlrev_b64 v[120:121], 12, v[120:121]
	v_lshlrev_b64 v[122:123], 12, v[122:123]
	v_lshlrev_b64 v[124:125], 12, v[124:125]
	v_lshl_add_u64 v[126:127], v[110:111], 0, v[126:127]
	v_lshl_add_u64 v[112:113], v[110:111], 0, v[112:113]
	v_lshl_add_u64 v[114:115], v[110:111], 0, v[114:115]
	s_waitcnt vmcnt(15)
	ds_write2_b32 v11, v44, v45 offset1:1
	ds_write2_b32 v11, v46, v47 offset0:2 offset1:3
	s_waitcnt vmcnt(14)
	ds_write2_b32 v12, v48, v49 offset1:1
	ds_write2_b32 v13, v50, v51 offset1:1
	s_waitcnt vmcnt(13)
	ds_write2_b32 v14, v52, v53 offset1:1
	ds_write2_b32 v15, v54, v55 offset1:1
	s_waitcnt vmcnt(12)
	ds_write2_b32 v16, v56, v57 offset1:1
	ds_write2_b32 v17, v58, v59 offset1:1
	s_waitcnt vmcnt(11)
	ds_write2_b32 v18, v60, v61 offset1:1
	ds_write2_b32 v19, v62, v63 offset1:1
	s_waitcnt vmcnt(10)
	ds_write2_b32 v20, v64, v65 offset1:1
	ds_write2_b32 v21, v66, v67 offset1:1
	s_waitcnt vmcnt(9)
	ds_write2_b32 v22, v68, v69 offset1:1
	ds_write2_b32 v23, v70, v71 offset1:1
	s_waitcnt vmcnt(8)
	ds_write2_b32 v24, v72, v73 offset1:1
	ds_write2_b32 v25, v74, v75 offset1:1
	s_waitcnt vmcnt(7)
	ds_write2_b32 v26, v76, v77 offset1:1
	ds_write2_b32 v27, v78, v79 offset1:1
	s_waitcnt vmcnt(6)
	ds_write2_b32 v28, v80, v81 offset1:1
	ds_write2_b32 v29, v82, v83 offset1:1
	s_waitcnt vmcnt(5)
	ds_write2_b32 v30, v84, v85 offset1:1
	ds_write2_b32 v31, v86, v87 offset1:1
	s_waitcnt vmcnt(4)
	ds_write2_b32 v32, v88, v89 offset1:1
	ds_write2_b32 v33, v90, v91 offset1:1
	s_waitcnt vmcnt(3)
	ds_write2_b32 v34, v92, v93 offset1:1
	ds_write2_b32 v35, v94, v95 offset1:1
	s_waitcnt vmcnt(2)
	ds_write2_b32 v36, v96, v97 offset1:1
	ds_write2_b32 v37, v98, v99 offset1:1
	s_waitcnt vmcnt(1)
	ds_write2_b32 v38, v100, v101 offset1:1
	ds_write2_b32 v39, v102, v103 offset1:1
	s_waitcnt vmcnt(0)
	ds_write2_b32 v40, v104, v105 offset1:1
	ds_write2_b32 v41, v106, v107 offset1:1
	s_waitcnt lgkmcnt(0)
; #define LAS __attribute__((address_space(3)))
; __device__ __forceinline__ void lds_wait() { asm volatile("s_waitcnt lgkmcnt(0)" ::: "memory"); }
; __device__ __forceinline__ void transpose_item(const float* W, int K, int N, bf16_t* WT, int gate, const float* kscale, LAS float* scr, int item, int lane) {
;     ...
;     lds_wait();
;     const int c = lane & 7;
;     f32x4 k0v = {1.f, 1.f, 1.f, 1.f}, k1v = k0v;
;     if (kscale) { k0v = *(const f32x4*)(kscale + k0 + 8 * c); k1v = *(const f32x4*)(kscale + k0 + 8 * c + 4); }
; #pragma unroll
;     for (int j = 0; j < 8; ++j) { const int n = (lane >> 3) + 8 * j; const LAS float* s = scr + (8 * c) * 65 + n;
;         u32x4 o; o.x = pk2(s[0 * 65] * k0v[0], s[1 * 65] * k0v[1]); o.y = pk2(s[2 * 65] * k0v[2], s[3 * 65] * k0v[3]); o.z = pk2(s[4 * 65] * k1v[0], s[5 * 65] * k1v[1]); o.w = pk2(s[6 * 65] * k1v[2], s[7 * 65] * k1v[3]);
;         const int nn = n0 + n; const int row = gate < 0 ? nn : (256 * (nn >> 7) + 128 * gate + (nn & 127));
;         *(u32x4*)(WT + (size_t)row * K + k0 + 8 * c) = o; }
;     lds_wait();
	global_load_dwordx4 v[44:47], v[108:109], off
	global_load_dwordx4 v[48:51], v[108:109], off offset:16
	v_lshl_add_u64 v[116:117], v[110:111], 0, v[116:117]
	v_lshl_add_u64 v[118:119], v[110:111], 0, v[118:119]
	v_lshl_add_u64 v[120:121], v[110:111], 0, v[120:121]
	v_lshl_add_u64 v[122:123], v[110:111], 0, v[122:123]
	v_lshl_add_u64 v[110:111], v[110:111], 0, v[124:125]
	ds_read2_b32 v[52:53], v10 offset1:8
	ds_read2_b32 v[54:55], v10 offset0:65 offset1:73
	ds_read2_b32 v[56:57], v10 offset0:130 offset1:138
	ds_read2_b32 v[58:59], v10 offset0:195 offset1:203
	ds_read2_b32 v[60:61], v42 offset0:4 offset1:12
	ds_read2_b32 v[62:63], v42 offset0:69 offset1:77
	ds_read2_b32 v[64:65], v42 offset0:134 offset1:142
	ds_read2_b32 v[66:67], v42 offset0:199 offset1:207
	ds_read2_b32 v[68:69], v10 offset0:16 offset1:24
	ds_read2_b32 v[70:71], v10 offset0:81 offset1:89
	ds_read2_b32 v[72:73], v10 offset0:146 offset1:154
	ds_read2_b32 v[74:75], v10 offset0:211 offset1:219
	ds_read2_b32 v[76:77], v42 offset0:20 offset1:28
	ds_read2_b32 v[78:79], v42 offset0:85 offset1:93
	ds_read2_b32 v[80:81], v42 offset0:150 offset1:158
	ds_read2_b32 v[82:83], v42 offset0:215 offset1:223
	ds_read2_b32 v[84:85], v10 offset0:32 offset1:40
	ds_read2_b32 v[86:87], v10 offset0:97 offset1:105
	ds_read2_b32 v[88:89], v10 offset0:162 offset1:170
	ds_read2_b32 v[90:91], v10 offset0:227 offset1:235
	ds_read2_b32 v[92:93], v42 offset0:36 offset1:44
	ds_read2_b32 v[94:95], v42 offset0:101 offset1:109
	ds_read2_b32 v[96:97], v42 offset0:166 offset1:174
	ds_read2_b32 v[98:99], v42 offset0:231 offset1:239
	ds_read2_b32 v[100:101], v10 offset0:48 offset1:56
	ds_read2_b32 v[102:103], v10 offset0:113 offset1:121
	ds_read2_b32 v[104:105], v10 offset0:178 offset1:186
	ds_read2_b32 v[106:107], v10 offset0:243 offset1:251
	ds_read2_b32 v[108:109], v42 offset0:52 offset1:60
	ds_read2_b32 v[124:125], v42 offset0:117 offset1:125
	ds_read2_b32 v[128:129], v42 offset0:182 offset1:190
	ds_read2_b32 v[130:131], v42 offset0:247 offset1:255
	s_add_i32 s3, s3, s92
	s_add_i32 s0, s0, s38
	s_cmpk_lt_i32 s3, 0xc00
	s_waitcnt vmcnt(1) lgkmcnt(14)
	v_mul_f32_e32 v43, v44, v52
	v_mul_f32_e32 v52, v45, v54
	v_mul_f32_e32 v54, v46, v56
	v_mul_f32_e32 v56, v47, v58
	s_waitcnt vmcnt(0)
	v_mul_f32_e32 v58, v48, v60
	v_mul_f32_e32 v60, v49, v62
	v_mul_f32_e32 v62, v50, v64
	v_mul_f32_e32 v64, v51, v66
	v_mul_f32_e32 v53, v44, v53
	v_mul_f32_e32 v55, v45, v55
	v_mul_f32_e32 v57, v46, v57
	v_mul_f32_e32 v59, v47, v59
	v_mul_f32_e32 v61, v48, v61
	v_mul_f32_e32 v63, v49, v63
	v_mul_f32_e32 v65, v50, v65
	v_mul_f32_e32 v66, v51, v67
	v_mul_f32_e32 v67, v44, v68
	v_mul_f32_e32 v68, v45, v70
	v_mul_f32_e32 v70, v46, v72
	v_mul_f32_e32 v72, v47, v74
	v_mul_f32_e32 v74, v48, v76
	v_mul_f32_e32 v76, v49, v78
	v_mul_f32_e32 v78, v50, v80
	v_mul_f32_e32 v80, v51, v82
	v_mul_f32_e32 v69, v44, v69
	v_mul_f32_e32 v71, v45, v71
	v_mul_f32_e32 v73, v46, v73
	v_mul_f32_e32 v75, v47, v75
	v_mul_f32_e32 v77, v48, v77
	v_mul_f32_e32 v79, v49, v79
	v_mul_f32_e32 v81, v50, v81
	v_mul_f32_e32 v82, v51, v83
	v_mul_f32_e32 v83, v44, v84
	v_mul_f32_e32 v84, v45, v86
	s_waitcnt lgkmcnt(13)
	v_mul_f32_e32 v86, v46, v88
	s_waitcnt lgkmcnt(12)
	v_mul_f32_e32 v88, v47, v90
	s_waitcnt lgkmcnt(11)
	v_mul_f32_e32 v90, v48, v92
	s_waitcnt lgkmcnt(10)
	v_mul_f32_e32 v92, v49, v94
	s_waitcnt lgkmcnt(9)
	v_mul_f32_e32 v94, v50, v96
	s_waitcnt lgkmcnt(8)
	v_mul_f32_e32 v96, v51, v98
	v_mul_f32_e32 v85, v44, v85
	v_mul_f32_e32 v87, v45, v87
	v_mul_f32_e32 v89, v46, v89
	v_mul_f32_e32 v91, v47, v91
	v_mul_f32_e32 v93, v48, v93
	v_mul_f32_e32 v95, v49, v95
	v_mul_f32_e32 v97, v50, v97
	v_mul_f32_e32 v98, v51, v99
	s_waitcnt lgkmcnt(7)
	v_mul_f32_e32 v99, v44, v100
	s_waitcnt lgkmcnt(6)
	v_mul_f32_e32 v100, v45, v102
	s_waitcnt lgkmcnt(5)
	v_mul_f32_e32 v102, v46, v104
	s_waitcnt lgkmcnt(4)
	v_mul_f32_e32 v104, v47, v106
	s_waitcnt lgkmcnt(3)
	v_mul_f32_e32 v106, v48, v108
	s_waitcnt lgkmcnt(2)
	v_mul_f32_e32 v108, v49, v124
	s_waitcnt lgkmcnt(1)
	v_mul_f32_e32 v124, v50, v128
	s_waitcnt lgkmcnt(0)
	v_mul_f32_e32 v128, v51, v130
	v_mul_f32_e32 v101, v44, v101
	v_mul_f32_e32 v103, v45, v103
	v_mul_f32_e32 v105, v46, v105
	v_mul_f32_e32 v107, v47, v107
	v_mul_f32_e32 v109, v48, v109
	v_mul_f32_e32 v125, v49, v125
	v_mul_f32_e32 v129, v50, v129
	v_mul_f32_e32 v130, v51, v131
	v_cvt_pk_bf16_f32 v44, v43, v52
	v_cvt_pk_bf16_f32 v45, v54, v56
	v_cvt_pk_bf16_f32 v46, v58, v60
	v_cvt_pk_bf16_f32 v47, v62, v64
	v_cvt_pk_bf16_f32 v48, v53, v55
	v_cvt_pk_bf16_f32 v49, v57, v59
	v_cvt_pk_bf16_f32 v50, v61, v63
	v_cvt_pk_bf16_f32 v51, v65, v66
	v_cvt_pk_bf16_f32 v52, v67, v68
	v_cvt_pk_bf16_f32 v53, v70, v72
	v_cvt_pk_bf16_f32 v54, v74, v76
	v_cvt_pk_bf16_f32 v55, v78, v80
	v_cvt_pk_bf16_f32 v56, v69, v71
	v_cvt_pk_bf16_f32 v57, v73, v75
	v_cvt_pk_bf16_f32 v58, v77, v79
	v_cvt_pk_bf16_f32 v59, v81, v82
	v_cvt_pk_bf16_f32 v60, v83, v84
	v_cvt_pk_bf16_f32 v61, v86, v88
	v_cvt_pk_bf16_f32 v62, v90, v92
	v_cvt_pk_bf16_f32 v63, v94, v96
	v_cvt_pk_bf16_f32 v64, v85, v87
	v_cvt_pk_bf16_f32 v65, v89, v91
	v_cvt_pk_bf16_f32 v66, v93, v95
	v_cvt_pk_bf16_f32 v67, v97, v98
	v_cvt_pk_bf16_f32 v68, v99, v100
	v_cvt_pk_bf16_f32 v69, v102, v104
	v_cvt_pk_bf16_f32 v70, v106, v108
	v_cvt_pk_bf16_f32 v71, v124, v128
	v_cvt_pk_bf16_f32 v72, v101, v103
	v_cvt_pk_bf16_f32 v73, v105, v107
	v_cvt_pk_bf16_f32 v74, v109, v125
	v_cvt_pk_bf16_f32 v75, v129, v130
	global_store_dwordx4 v[126:127], v[44:47], off sc0 sc1
	global_store_dwordx4 v[112:113], v[48:51], off sc0 sc1
	global_store_dwordx4 v[114:115], v[52:55], off sc0 sc1
	global_store_dwordx4 v[116:117], v[56:59], off sc0 sc1
	global_store_dwordx4 v[118:119], v[60:63], off sc0 sc1
	global_store_dwordx4 v[120:121], v[64:67], off sc0 sc1
	global_store_dwordx4 v[122:123], v[68:71], off sc0 sc1
	global_store_dwordx4 v[110:111], v[72:75], off sc0 sc1
	s_waitcnt lgkmcnt(0)
	s_cbranch_scc1 .LBB0_562

; #define LAS __attribute__((address_space(3)))
; __device__ __forceinline__ void lds_wait() { asm volatile("s_waitcnt lgkmcnt(0)" ::: "memory"); }
; __device__ __forceinline__ void transpose_item(const float* W, int K, int N, bf16_t* WT, int gate, const float* kscale, LAS float* scr, int item, int lane) {
;     const int nblk = N / 64, kb = item / nblk, nb = item % nblk, k0 = 64 * kb, n0 = 64 * nb;
;     const int c4 = (lane & 15) * 4, kr = lane >> 4;
;     f32x4 v[16];
; #pragma unroll
;     for (int i = 0; i < 16; ++i) v[i] = __builtin_nontemporal_load((const f32x4*)(W + (size_t)(k0 + 4 * i + kr) * N + n0 + c4));
; #pragma unroll
;     for (int i = 0; i < 16; ++i) { LAS float* d = scr + (4 * i + kr) * 65 + c4; d[0] = v[i][0]; d[1] = v[i][1]; d[2] = v[i][2]; d[3] = v[i][3]; }
;     lds_wait();
.LBB0_814:
	s_ashr_i32 s4, s1, 31
	s_lshr_b32 s4, s4, 27
	s_add_i32 s4, s1, s4
	s_ashr_i32 s5, s4, 5
	s_lshl_b32 s4, s5, 6
	s_lshl_b32 s5, s5, 11
	v_add_u32_e32 v42, s4, v10
	s_sub_i32 s6, s0, s5
	v_add_u32_e32 v44, 4, v42
	v_add_u32_e32 v46, 8, v42
	v_add_u32_e32 v48, 12, v42
	v_add_u32_e32 v50, 16, v42
	v_add_u32_e32 v52, 20, v42
	v_add_u32_e32 v54, 24, v42
	v_add_u32_e32 v56, 28, v42
	s_ashr_i32 s7, s6, 31
	v_ashrrev_i32_e32 v43, 31, v42
	v_add_u32_e32 v58, 32, v42
	v_add_u32_e32 v60, 36, v42
	v_add_u32_e32 v62, 40, v42
	v_add_u32_e32 v64, 44, v42
	v_add_u32_e32 v66, 48, v42
	v_add_u32_e32 v68, 52, v42
	v_add_u32_e32 v70, 56, v42
	v_add_u32_e32 v72, 60, v42
	v_add_u32_e32 v74, s6, v11
	v_ashrrev_i32_e32 v45, 31, v44
	v_ashrrev_i32_e32 v47, 31, v46
	v_ashrrev_i32_e32 v49, 31, v48
	v_ashrrev_i32_e32 v51, 31, v50
	v_ashrrev_i32_e32 v53, 31, v52
	v_ashrrev_i32_e32 v55, 31, v54
	v_ashrrev_i32_e32 v57, 31, v56
	s_ashr_i32 s5, s4, 31
	v_lshl_add_u64 v[76:77], s[6:7], 2, v[0:1]
	v_lshlrev_b64 v[42:43], 13, v[42:43]
	v_ashrrev_i32_e32 v59, 31, v58
	v_ashrrev_i32_e32 v61, 31, v60
	v_ashrrev_i32_e32 v63, 31, v62
	v_ashrrev_i32_e32 v65, 31, v64
	v_ashrrev_i32_e32 v67, 31, v66
	v_ashrrev_i32_e32 v69, 31, v68
	v_ashrrev_i32_e32 v71, 31, v70
	v_ashrrev_i32_e32 v73, 31, v72
	v_ashrrev_i32_e32 v75, 31, v74
	v_add_u32_e32 v78, 8, v74
	v_add_u32_e32 v80, 16, v74
	v_add_u32_e32 v82, 24, v74
	v_add_u32_e32 v84, 32, v74
	v_add_u32_e32 v86, 40, v74
	v_add_u32_e32 v88, 48, v74
	v_add_u32_e32 v90, 56, v74
	v_lshlrev_b64 v[92:93], 13, v[44:45]
	v_lshlrev_b64 v[46:47], 13, v[46:47]
	v_lshlrev_b64 v[48:49], 13, v[48:49]
	v_lshlrev_b64 v[50:51], 13, v[50:51]
	v_lshlrev_b64 v[52:53], 13, v[52:53]
	v_lshlrev_b64 v[54:55], 13, v[54:55]
	v_lshlrev_b64 v[56:57], 13, v[56:57]
	v_lshl_add_u64 v[106:107], s[4:5], 1, v[2:3]
	v_lshl_add_u64 v[42:43], v[76:77], 0, v[42:43]
	v_lshlrev_b64 v[58:59], 13, v[58:59]
	v_lshlrev_b64 v[60:61], 13, v[60:61]
	v_lshlrev_b64 v[62:63], 13, v[62:63]
	v_lshlrev_b64 v[64:65], 13, v[64:65]
	v_lshlrev_b64 v[66:67], 13, v[66:67]
	v_lshlrev_b64 v[68:69], 13, v[68:69]
	v_lshlrev_b64 v[70:71], 13, v[70:71]
	v_lshlrev_b64 v[72:73], 13, v[72:73]
	v_lshlrev_b64 v[74:75], 12, v[74:75]
	v_ashrrev_i32_e32 v79, 31, v78
	v_ashrrev_i32_e32 v81, 31, v80
	v_ashrrev_i32_e32 v83, 31, v82
	v_ashrrev_i32_e32 v85, 31, v84
	v_ashrrev_i32_e32 v87, 31, v86
	v_ashrrev_i32_e32 v89, 31, v88
	v_ashrrev_i32_e32 v91, 31, v90
	v_lshl_add_u64 v[92:93], v[76:77], 0, v[92:93]
	v_lshl_add_u64 v[94:95], v[76:77], 0, v[46:47]
	v_lshl_add_u64 v[96:97], v[76:77], 0, v[48:49]
	v_lshl_add_u64 v[98:99], v[76:77], 0, v[50:51]
	v_lshl_add_u64 v[100:101], v[76:77], 0, v[52:53]
	v_lshl_add_u64 v[102:103], v[76:77], 0, v[54:55]
	v_lshl_add_u64 v[104:105], v[76:77], 0, v[56:57]
	global_load_dwordx4 v[42:45], v[42:43], off nt
	v_lshl_add_u64 v[108:109], v[76:77], 0, v[58:59]
	v_lshl_add_u64 v[110:111], v[76:77], 0, v[60:61]
	v_lshl_add_u64 v[112:113], v[76:77], 0, v[62:63]
	v_lshl_add_u64 v[114:115], v[76:77], 0, v[64:65]
	v_lshl_add_u64 v[116:117], v[76:77], 0, v[66:67]
	v_lshl_add_u64 v[118:119], v[76:77], 0, v[68:69]
	v_lshl_add_u64 v[120:121], v[76:77], 0, v[70:71]
	v_lshl_add_u64 v[122:123], v[76:77], 0, v[72:73]
	v_lshl_add_u64 v[124:125], v[106:107], 0, v[74:75]
	v_lshlrev_b64 v[126:127], 12, v[78:79]
	v_lshlrev_b64 v[128:129], 12, v[80:81]
	v_lshlrev_b64 v[130:131], 12, v[82:83]
	v_lshlrev_b64 v[132:133], 12, v[84:85]
	v_lshlrev_b64 v[134:135], 12, v[86:87]
	v_lshlrev_b64 v[136:137], 12, v[88:89]
	v_lshlrev_b64 v[138:139], 12, v[90:91]
	global_load_dwordx4 v[46:49], v[92:93], off nt
	global_load_dwordx4 v[50:53], v[94:95], off nt
	global_load_dwordx4 v[54:57], v[96:97], off nt
	global_load_dwordx4 v[58:61], v[98:99], off nt
	global_load_dwordx4 v[62:65], v[100:101], off nt
	global_load_dwordx4 v[66:69], v[102:103], off nt
	global_load_dwordx4 v[70:73], v[104:105], off nt
	global_load_dwordx4 v[74:77], v[108:109], off nt
	global_load_dwordx4 v[78:81], v[110:111], off nt
	global_load_dwordx4 v[82:85], v[112:113], off nt
	global_load_dwordx4 v[86:89], v[114:115], off nt
	global_load_dwordx4 v[90:93], v[116:117], off nt
	global_load_dwordx4 v[94:97], v[118:119], off nt
	global_load_dwordx4 v[98:101], v[120:121], off nt
	global_load_dwordx4 v[102:105], v[122:123], off nt
	s_waitcnt vmcnt(15)
	ds_write2_b32 v6, v42, v43 offset1:1
	ds_write2_b32 v6, v44, v45 offset0:2 offset1:3
	s_waitcnt vmcnt(14)
	ds_write2_b32 v7, v46, v47 offset1:1
	ds_write2_b32 v9, v48, v49 offset1:1
	s_waitcnt vmcnt(13)
	ds_write2_b32 v12, v50, v51 offset1:1
	ds_write2_b32 v13, v52, v53 offset1:1
	s_waitcnt vmcnt(12)
	ds_write2_b32 v14, v54, v55 offset1:1
	ds_write2_b32 v15, v56, v57 offset1:1
	s_waitcnt vmcnt(11)
	ds_write2_b32 v16, v58, v59 offset1:1
	ds_write2_b32 v17, v60, v61 offset1:1
	s_waitcnt vmcnt(10)
; #define LAS __attribute__((address_space(3)))
; __device__ __forceinline__ void lds_wait() { asm volatile("s_waitcnt lgkmcnt(0)" ::: "memory"); }
; __device__ __forceinline__ void transpose_item(const float* W, int K, int N, bf16_t* WT, int gate, const float* kscale, LAS float* scr, int item, int lane) {
;     ...
;     for (int i = 0; i < 16; ++i) { LAS float* d = scr + (4 * i + kr) * 65 + c4; d[0] = v[i][0]; d[1] = v[i][1]; d[2] = v[i][2]; d[3] = v[i][3]; }
;     lds_wait();
;     const int c = lane & 7;
;     f32x4 k0v = {1.f, 1.f, 1.f, 1.f}, k1v = k0v;
;     if (kscale) { k0v = *(const f32x4*)(kscale + k0 + 8 * c); k1v = *(const f32x4*)(kscale + k0 + 8 * c + 4); }
; #pragma unroll
;     for (int j = 0; j < 8; ++j) { const int n = (lane >> 3) + 8 * j; const LAS float* s = scr + (8 * c) * 65 + n;
;         u32x4 o; o.x = pk2(s[0 * 65] * k0v[0], s[1 * 65] * k0v[1]); o.y = pk2(s[2 * 65] * k0v[2], s[3 * 65] * k0v[3]); o.z = pk2(s[4 * 65] * k1v[0], s[5 * 65] * k1v[1]); o.w = pk2(s[6 * 65] * k1v[2], s[7 * 65] * k1v[3]);
;         const int nn = n0 + n; const int row = gate < 0 ? nn : (256 * (nn >> 7) + 128 * gate + (nn & 127));
;         *(u32x4*)(WT + (size_t)row * K + k0 + 8 * c) = o; }
;     lds_wait();
	ds_write2_b32 v18, v62, v63 offset1:1
	ds_write2_b32 v19, v64, v65 offset1:1
	s_waitcnt vmcnt(9)
	ds_write2_b32 v20, v66, v67 offset1:1
	ds_write2_b32 v21, v68, v69 offset1:1
	s_waitcnt vmcnt(8)
	ds_write2_b32 v22, v70, v71 offset1:1
	ds_write2_b32 v23, v72, v73 offset1:1
	s_waitcnt vmcnt(7)
	ds_write2_b32 v24, v74, v75 offset1:1
	ds_write2_b32 v25, v76, v77 offset1:1
	s_waitcnt vmcnt(6)
	ds_write2_b32 v26, v78, v79 offset1:1
	ds_write2_b32 v27, v80, v81 offset1:1
	s_waitcnt vmcnt(5)
	ds_write2_b32 v28, v82, v83 offset1:1
	ds_write2_b32 v29, v84, v85 offset1:1
	s_waitcnt vmcnt(4)
	ds_write2_b32 v30, v86, v87 offset1:1
	ds_write2_b32 v31, v88, v89 offset1:1
	s_waitcnt vmcnt(3)
	ds_write2_b32 v32, v90, v91 offset1:1
	ds_write2_b32 v33, v92, v93 offset1:1
	s_waitcnt vmcnt(2)
	ds_write2_b32 v34, v94, v95 offset1:1
	ds_write2_b32 v35, v96, v97 offset1:1
	s_waitcnt vmcnt(1)
	ds_write2_b32 v36, v98, v99 offset1:1
	ds_write2_b32 v37, v100, v101 offset1:1
	s_waitcnt vmcnt(0)
	ds_write2_b32 v38, v102, v103 offset1:1
	ds_write2_b32 v39, v104, v105 offset1:1
	s_waitcnt lgkmcnt(0)
	ds_read2_b32 v[46:47], v5 offset0:65 offset1:73
	ds_read2_b32 v[48:49], v5 offset1:8
	ds_read2_b32 v[50:51], v5 offset0:130 offset1:138
	ds_read2_b32 v[52:53], v5 offset0:195 offset1:203
	ds_read2_b32 v[54:55], v40 offset0:4 offset1:12
	ds_read2_b32 v[56:57], v40 offset0:69 offset1:77
	ds_read2_b32 v[58:59], v40 offset0:134 offset1:142
	ds_read2_b32 v[60:61], v40 offset0:199 offset1:207
	ds_read2_b32 v[62:63], v5 offset0:81 offset1:89
	ds_read2_b32 v[64:65], v5 offset0:16 offset1:24
	ds_read2_b32 v[66:67], v5 offset0:146 offset1:154
	ds_read2_b32 v[68:69], v5 offset0:211 offset1:219
	ds_read2_b32 v[70:71], v40 offset0:20 offset1:28
	ds_read2_b32 v[72:73], v40 offset0:85 offset1:93
	ds_read2_b32 v[74:75], v40 offset0:150 offset1:158
	ds_read2_b32 v[76:77], v40 offset0:215 offset1:223
	ds_read2_b32 v[78:79], v5 offset0:32 offset1:40
	ds_read2_b32 v[80:81], v5 offset0:97 offset1:105
	ds_read2_b32 v[82:83], v5 offset0:162 offset1:170
	ds_read2_b32 v[84:85], v5 offset0:227 offset1:235
	ds_read2_b32 v[86:87], v40 offset0:36 offset1:44
	ds_read2_b32 v[88:89], v40 offset0:101 offset1:109
	ds_read2_b32 v[90:91], v40 offset0:166 offset1:174
	ds_read2_b32 v[92:93], v40 offset0:231 offset1:239
	ds_read2_b32 v[94:95], v5 offset0:48 offset1:56
	ds_read2_b32 v[96:97], v5 offset0:113 offset1:121
	ds_read2_b32 v[98:99], v5 offset0:178 offset1:186
	ds_read2_b32 v[100:101], v5 offset0:243 offset1:251
	ds_read2_b32 v[102:103], v40 offset0:52 offset1:60
	ds_read2_b32 v[104:105], v40 offset0:117 offset1:125
	ds_read2_b32 v[120:121], v40 offset0:182 offset1:190
	ds_read2_b32 v[122:123], v40 offset0:247 offset1:255
	s_waitcnt lgkmcnt(14)
	v_cvt_pk_bf16_f32 v42, v48, v46
	v_cvt_pk_bf16_f32 v43, v50, v52
	v_cvt_pk_bf16_f32 v44, v54, v56
	v_cvt_pk_bf16_f32 v45, v58, v60
	v_lshl_add_u64 v[108:109], v[106:107], 0, v[126:127]
	v_lshl_add_u64 v[110:111], v[106:107], 0, v[128:129]
	v_lshl_add_u64 v[112:113], v[106:107], 0, v[130:131]
	v_lshl_add_u64 v[114:115], v[106:107], 0, v[132:133]
	v_lshl_add_u64 v[116:117], v[106:107], 0, v[134:135]
	v_lshl_add_u64 v[118:119], v[106:107], 0, v[136:137]
	v_lshl_add_u64 v[106:107], v[106:107], 0, v[138:139]
	v_cvt_pk_bf16_f32 v46, v49, v47
	v_cvt_pk_bf16_f32 v47, v51, v53
	v_cvt_pk_bf16_f32 v48, v55, v57
	v_cvt_pk_bf16_f32 v49, v59, v61
	v_cvt_pk_bf16_f32 v50, v64, v62
	v_cvt_pk_bf16_f32 v51, v66, v68
	v_cvt_pk_bf16_f32 v52, v70, v72
	v_cvt_pk_bf16_f32 v53, v74, v76
	v_cvt_pk_bf16_f32 v54, v65, v63
	v_cvt_pk_bf16_f32 v55, v67, v69
	v_cvt_pk_bf16_f32 v56, v71, v73
	v_cvt_pk_bf16_f32 v57, v75, v77
	v_cvt_pk_bf16_f32 v58, v78, v80
	s_waitcnt lgkmcnt(12)
	v_cvt_pk_bf16_f32 v59, v82, v84
	s_waitcnt lgkmcnt(10)
	v_cvt_pk_bf16_f32 v60, v86, v88
	s_waitcnt lgkmcnt(8)
	v_cvt_pk_bf16_f32 v61, v90, v92
	v_cvt_pk_bf16_f32 v62, v79, v81
	v_cvt_pk_bf16_f32 v63, v83, v85
	v_cvt_pk_bf16_f32 v64, v87, v89
	v_cvt_pk_bf16_f32 v65, v91, v93
	s_waitcnt lgkmcnt(6)
	v_cvt_pk_bf16_f32 v66, v94, v96
	s_waitcnt lgkmcnt(4)
	v_cvt_pk_bf16_f32 v67, v98, v100
	s_waitcnt lgkmcnt(2)
	v_cvt_pk_bf16_f32 v68, v102, v104
	s_waitcnt lgkmcnt(0)
	v_cvt_pk_bf16_f32 v69, v120, v122
	v_cvt_pk_bf16_f32 v70, v95, v97
	v_cvt_pk_bf16_f32 v71, v99, v101
	v_cvt_pk_bf16_f32 v72, v103, v105
	v_cvt_pk_bf16_f32 v73, v121, v123
	global_store_dwordx4 v[124:125], v[42:45], off sc0 sc1
	global_store_dwordx4 v[108:109], v[46:49], off sc0 sc1
	global_store_dwordx4 v[110:111], v[50:53], off sc0 sc1
	global_store_dwordx4 v[112:113], v[54:57], off sc0 sc1
	global_store_dwordx4 v[114:115], v[58:61], off sc0 sc1
	global_store_dwordx4 v[116:117], v[62:65], off sc0 sc1
	global_store_dwordx4 v[118:119], v[66:69], off sc0 sc1
	global_store_dwordx4 v[106:107], v[70:73], off sc0 sc1
	s_waitcnt lgkmcnt(0)
	s_add_i32 s1, s1, s92
	s_add_i32 s0, s0, s38
	s_cmpk_lt_i32 s1, 0x400
	s_cbranch_scc1 .LBB0_814

; #define LAS __attribute__((address_space(3)))
; __device__ __forceinline__ void lds_wait() { asm volatile("s_waitcnt lgkmcnt(0)" ::: "memory"); }
; __device__ __forceinline__ void transpose_item(const float* W, int K, int N, bf16_t* WT, int gate, const float* kscale, LAS float* scr, int item, int lane) {
;     const int nblk = N / 64, kb = item / nblk, nb = item % nblk, k0 = 64 * kb, n0 = 64 * nb;
;     const int c4 = (lane & 15) * 4, kr = lane >> 4;
;     f32x4 v[16];
; #pragma unroll
;     for (int i = 0; i < 16; ++i) v[i] = __builtin_nontemporal_load((const f32x4*)(W + (size_t)(k0 + 4 * i + kr) * N + n0 + c4));
; #pragma unroll
;     for (int i = 0; i < 16; ++i) { LAS float* d = scr + (4 * i + kr) * 65 + c4; d[0] = v[i][0]; d[1] = v[i][1]; d[2] = v[i][2]; d[3] = v[i][3]; }
;     lds_wait();
.LBB0_817:
	s_ashr_i32 s19, s18, 31
	s_lshr_b32 s19, s19, 25
	s_add_i32 s19, s18, s19
	s_ashr_i32 s19, s19, 7
	s_lshl_b32 s20, s19, 6
	s_lshl_b32 s19, s19, 13
	s_sub_i32 s26, s17, s19
	v_add_u32_e32 v44, s20, v10
	s_ashr_i32 s27, s26, 31
	v_ashrrev_i32_e32 v45, 31, v44
	v_lshl_add_u64 v[48:49], s[26:27], 2, v[4:5]
	v_lshlrev_b64 v[44:45], 15, v[44:45]
	v_lshl_add_u64 v[48:49], v[48:49], 0, v[44:45]
	v_add_co_u32_e32 v66, vcc, s1, v48
	v_add_u32_e32 v46, s26, v11
	s_nop 0
	v_addc_co_u32_e32 v67, vcc, 0, v49, vcc
	v_add_co_u32_e32 v68, vcc, s3, v48
	s_ashr_i32 s21, s20, 31
	s_nop 0
	v_addc_co_u32_e32 v69, vcc, 0, v49, vcc
	v_add_co_u32_e32 v70, vcc, s4, v48
	v_ashrrev_i32_e32 v47, 31, v46
	s_nop 0
	v_addc_co_u32_e32 v71, vcc, 0, v49, vcc
	v_add_co_u32_e32 v72, vcc, s5, v48
	v_add_u32_e32 v50, 8, v46
	s_nop 0
	v_addc_co_u32_e32 v73, vcc, 0, v49, vcc
	v_add_co_u32_e32 v74, vcc, s6, v48
	v_add_u32_e32 v52, 16, v46
	s_nop 0
	v_addc_co_u32_e32 v75, vcc, 0, v49, vcc
	v_add_co_u32_e32 v76, vcc, s7, v48
	v_add_u32_e32 v54, 24, v46
	s_nop 0
	v_addc_co_u32_e32 v77, vcc, 0, v49, vcc
	v_add_co_u32_e32 v78, vcc, s8, v48
	v_add_u32_e32 v56, 32, v46
	s_nop 0
	v_addc_co_u32_e32 v79, vcc, 0, v49, vcc
	v_add_co_u32_e32 v80, vcc, s9, v48
	v_add_u32_e32 v58, 40, v46
	s_nop 0
	v_addc_co_u32_e32 v81, vcc, 0, v49, vcc
	v_add_co_u32_e32 v82, vcc, s10, v48
	v_add_u32_e32 v60, 48, v46
	s_nop 0
	v_addc_co_u32_e32 v83, vcc, 0, v49, vcc
	v_add_co_u32_e32 v84, vcc, s11, v48
	v_add_u32_e32 v62, 56, v46
	s_nop 0
	v_addc_co_u32_e32 v85, vcc, 0, v49, vcc
	v_add_co_u32_e32 v88, vcc, s12, v48
	v_lshl_add_u64 v[110:111], s[20:21], 1, v[8:9]
	s_nop 0
	v_addc_co_u32_e32 v89, vcc, 0, v49, vcc
	v_add_co_u32_e32 v92, vcc, s13, v48
	v_lshlrev_b64 v[64:65], 12, v[46:47]
	s_nop 0
	v_addc_co_u32_e32 v93, vcc, 0, v49, vcc
	v_add_co_u32_e32 v96, vcc, s14, v48
	v_ashrrev_i32_e32 v51, 31, v50
	s_nop 0
	v_addc_co_u32_e32 v97, vcc, 0, v49, vcc
	v_add_co_u32_e32 v100, vcc, s15, v48
	v_ashrrev_i32_e32 v53, 31, v52
	s_nop 0
	v_addc_co_u32_e32 v101, vcc, 0, v49, vcc
	v_add_co_u32_e32 v104, vcc, s16, v48
	v_ashrrev_i32_e32 v55, 31, v54
	v_ashrrev_i32_e32 v57, 31, v56
	v_ashrrev_i32_e32 v59, 31, v58
	v_ashrrev_i32_e32 v61, 31, v60
	v_ashrrev_i32_e32 v63, 31, v62
	v_addc_co_u32_e32 v105, vcc, 0, v49, vcc
	global_load_dwordx4 v[44:47], v[48:49], off nt
	v_lshl_add_u64 v[112:113], v[110:111], 0, v[64:65]
	v_lshlrev_b64 v[114:115], 12, v[50:51]
	v_lshlrev_b64 v[116:117], 12, v[52:53]
	v_lshlrev_b64 v[118:119], 12, v[54:55]
	v_lshlrev_b64 v[120:121], 12, v[56:57]
	v_lshlrev_b64 v[122:123], 12, v[58:59]
	v_lshlrev_b64 v[124:125], 12, v[60:61]
	v_lshlrev_b64 v[126:127], 12, v[62:63]
	global_load_dwordx4 v[48:51], v[66:67], off nt
	global_load_dwordx4 v[52:55], v[68:69], off nt
	global_load_dwordx4 v[56:59], v[70:71], off nt
	global_load_dwordx4 v[60:63], v[72:73], off nt
	s_nop 0
	global_load_dwordx4 v[64:67], v[74:75], off nt
	global_load_dwordx4 v[68:71], v[76:77], off nt
	s_nop 0
	global_load_dwordx4 v[72:75], v[78:79], off nt
	s_nop 0
	global_load_dwordx4 v[76:79], v[80:81], off nt
	s_nop 0
	global_load_dwordx4 v[80:83], v[82:83], off nt
	s_nop 0
	global_load_dwordx4 v[84:87], v[84:85], off nt
	s_nop 0
	global_load_dwordx4 v[88:91], v[88:89], off nt
	s_nop 0
	global_load_dwordx4 v[92:95], v[92:93], off nt
	s_nop 0
	global_load_dwordx4 v[96:99], v[96:97], off nt
	s_nop 0
	global_load_dwordx4 v[100:103], v[100:101], off nt
	s_nop 0
	global_load_dwordx4 v[104:107], v[104:105], off nt
	v_lshl_add_u64 v[108:109], s[20:21], 2, v[6:7]
	v_lshl_add_u64 v[114:115], v[110:111], 0, v[114:115]
	v_lshl_add_u64 v[116:117], v[110:111], 0, v[116:117]
	v_lshl_add_u64 v[118:119], v[110:111], 0, v[118:119]
	v_lshl_add_u64 v[120:121], v[110:111], 0, v[120:121]
	v_lshl_add_u64 v[122:123], v[110:111], 0, v[122:123]
	v_lshl_add_u64 v[124:125], v[110:111], 0, v[124:125]
	v_lshl_add_u64 v[110:111], v[110:111], 0, v[126:127]
	s_add_i32 s18, s18, s92
	s_add_i32 s17, s17, s38
	s_cmpk_lt_i32 s18, 0x1000
	s_waitcnt vmcnt(15)
	ds_write2_b32 v13, v44, v45 offset1:1
	ds_write2_b32 v13, v46, v47 offset0:2 offset1:3
	s_waitcnt vmcnt(14)
	ds_write2_b32 v1, v48, v49 offset1:1
	ds_write2_b32 v3, v50, v51 offset1:1
	s_waitcnt vmcnt(13)
	ds_write2_b32 v14, v52, v53 offset1:1
	ds_write2_b32 v15, v54, v55 offset1:1
	s_waitcnt vmcnt(12)
	ds_write2_b32 v16, v56, v57 offset1:1
	ds_write2_b32 v17, v58, v59 offset1:1
	s_waitcnt vmcnt(11)
	ds_write2_b32 v18, v60, v61 offset1:1
	ds_write2_b32 v19, v62, v63 offset1:1
	s_waitcnt vmcnt(10)
	ds_write2_b32 v20, v64, v65 offset1:1
	ds_write2_b32 v21, v66, v67 offset1:1
	s_waitcnt vmcnt(9)
	ds_write2_b32 v22, v68, v69 offset1:1
	ds_write2_b32 v23, v70, v71 offset1:1
	s_waitcnt vmcnt(8)
	ds_write2_b32 v24, v72, v73 offset1:1
	ds_write2_b32 v25, v74, v75 offset1:1
	s_waitcnt vmcnt(7)
	ds_write2_b32 v26, v76, v77 offset1:1
	ds_write2_b32 v27, v78, v79 offset1:1
	s_waitcnt vmcnt(6)
	ds_write2_b32 v28, v80, v81 offset1:1
	ds_write2_b32 v29, v82, v83 offset1:1
	s_waitcnt vmcnt(5)
	ds_write2_b32 v30, v84, v85 offset1:1
	ds_write2_b32 v31, v86, v87 offset1:1
	s_waitcnt vmcnt(4)
	ds_write2_b32 v32, v88, v89 offset1:1
	ds_write2_b32 v33, v90, v91 offset1:1
	s_waitcnt vmcnt(3)
	ds_write2_b32 v34, v92, v93 offset1:1
	ds_write2_b32 v35, v94, v95 offset1:1
	s_waitcnt vmcnt(2)
	ds_write2_b32 v36, v96, v97 offset1:1
	ds_write2_b32 v37, v98, v99 offset1:1
	s_waitcnt vmcnt(1)
	ds_write2_b32 v38, v100, v101 offset1:1
	ds_write2_b32 v39, v102, v103 offset1:1
	s_waitcnt vmcnt(0)
	ds_write2_b32 v40, v104, v105 offset1:1
	ds_write2_b32 v41, v106, v107 offset1:1
	s_waitcnt lgkmcnt(0)
; #define LAS __attribute__((address_space(3)))
; __device__ __forceinline__ void transpose_item(const float* W, int K, int N, bf16_t* WT, int gate, const float* kscale, LAS float* scr, int item, int lane) {
;     ...
;     f32x4 k0v = {1.f, 1.f, 1.f, 1.f}, k1v = k0v;
;     if (kscale) { k0v = *(const f32x4*)(kscale + k0 + 8 * c); k1v = *(const f32x4*)(kscale + k0 + 8 * c + 4); }
; #pragma unroll
;     for (int j = 0; j < 8; ++j) { const int n = (lane >> 3) + 8 * j; const LAS float* s = scr + (8 * c) * 65 + n;
;         u32x4 o; o.x = pk2(s[0 * 65] * k0v[0], s[1 * 65] * k0v[1]); o.y = pk2(s[2 * 65] * k0v[2], s[3 * 65] * k0v[3]); o.z = pk2(s[4 * 65] * k1v[0], s[5 * 65] * k1v[1]); o.w = pk2(s[6 * 65] * k1v[2], s[7 * 65] * k1v[3]);
;         const int nn = n0 + n; const int row = gate < 0 ? nn : (256 * (nn >> 7) + 128 * gate + (nn & 127));
;         *(u32x4*)(WT + (size_t)row * K + k0 + 8 * c) = o; }
	global_load_dwordx4 v[44:47], v[108:109], off
	global_load_dwordx4 v[48:51], v[108:109], off offset:16
	ds_read2_b32 v[52:53], v12 offset1:8
	ds_read2_b32 v[54:55], v12 offset0:65 offset1:73
	ds_read2_b32 v[56:57], v12 offset0:130 offset1:138
	ds_read2_b32 v[58:59], v12 offset0:195 offset1:203
	ds_read2_b32 v[60:61], v42 offset0:4 offset1:12
	ds_read2_b32 v[62:63], v42 offset0:69 offset1:77
	ds_read2_b32 v[64:65], v42 offset0:134 offset1:142
	ds_read2_b32 v[66:67], v42 offset0:199 offset1:207
	ds_read2_b32 v[68:69], v12 offset0:16 offset1:24
	ds_read2_b32 v[70:71], v12 offset0:81 offset1:89
	ds_read2_b32 v[72:73], v12 offset0:146 offset1:154
	ds_read2_b32 v[74:75], v12 offset0:211 offset1:219
	ds_read2_b32 v[76:77], v42 offset0:20 offset1:28
	ds_read2_b32 v[78:79], v42 offset0:85 offset1:93
	ds_read2_b32 v[80:81], v42 offset0:150 offset1:158
	ds_read2_b32 v[82:83], v42 offset0:215 offset1:223
	ds_read2_b32 v[84:85], v12 offset0:32 offset1:40
	ds_read2_b32 v[86:87], v12 offset0:97 offset1:105
	ds_read2_b32 v[88:89], v12 offset0:162 offset1:170
	ds_read2_b32 v[90:91], v12 offset0:227 offset1:235
	ds_read2_b32 v[92:93], v42 offset0:36 offset1:44
	ds_read2_b32 v[94:95], v42 offset0:101 offset1:109
	ds_read2_b32 v[96:97], v42 offset0:166 offset1:174
	ds_read2_b32 v[98:99], v42 offset0:231 offset1:239
	ds_read2_b32 v[100:101], v12 offset0:48 offset1:56
	ds_read2_b32 v[102:103], v12 offset0:113 offset1:121
	ds_read2_b32 v[104:105], v12 offset0:178 offset1:186
	ds_read2_b32 v[106:107], v12 offset0:243 offset1:251
	ds_read2_b32 v[108:109], v42 offset0:52 offset1:60
	ds_read2_b32 v[126:127], v42 offset0:117 offset1:125
	ds_read2_b32 v[128:129], v42 offset0:182 offset1:190
	ds_read2_b32 v[130:131], v42 offset0:247 offset1:255
	s_waitcnt vmcnt(1) lgkmcnt(14)
	v_mul_f32_e32 v43, v44, v52
	v_mul_f32_e32 v52, v45, v54
	v_mul_f32_e32 v54, v46, v56
	v_mul_f32_e32 v56, v47, v58
	s_waitcnt vmcnt(0)
	v_mul_f32_e32 v58, v48, v60
	v_mul_f32_e32 v60, v49, v62
	v_mul_f32_e32 v62, v50, v64
	v_mul_f32_e32 v64, v51, v66
	v_mul_f32_e32 v53, v44, v53
	v_mul_f32_e32 v55, v45, v55
	v_mul_f32_e32 v57, v46, v57
	v_mul_f32_e32 v59, v47, v59
	v_mul_f32_e32 v61, v48, v61
	v_mul_f32_e32 v63, v49, v63
	v_mul_f32_e32 v65, v50, v65
	v_mul_f32_e32 v66, v51, v67
	v_mul_f32_e32 v67, v44, v68
	v_mul_f32_e32 v68, v45, v70
	v_mul_f32_e32 v70, v46, v72
	v_mul_f32_e32 v72, v47, v74
	v_mul_f32_e32 v74, v48, v76
	v_mul_f32_e32 v76, v49, v78
	v_mul_f32_e32 v78, v50, v80
	v_mul_f32_e32 v80, v51, v82
	v_mul_f32_e32 v69, v44, v69
	v_mul_f32_e32 v71, v45, v71
	v_mul_f32_e32 v73, v46, v73
	v_mul_f32_e32 v75, v47, v75
	v_mul_f32_e32 v77, v48, v77
	v_mul_f32_e32 v79, v49, v79
	v_mul_f32_e32 v81, v50, v81
	v_mul_f32_e32 v82, v51, v83
	v_mul_f32_e32 v83, v44, v84
	v_mul_f32_e32 v84, v45, v86
	s_waitcnt lgkmcnt(13)
	v_mul_f32_e32 v86, v46, v88
	s_waitcnt lgkmcnt(12)
	v_mul_f32_e32 v88, v47, v90
	s_waitcnt lgkmcnt(11)
	v_mul_f32_e32 v90, v48, v92
	s_waitcnt lgkmcnt(10)
	v_mul_f32_e32 v92, v49, v94
	s_waitcnt lgkmcnt(9)
	v_mul_f32_e32 v94, v50, v96
	s_waitcnt lgkmcnt(8)
	v_mul_f32_e32 v96, v51, v98
	v_mul_f32_e32 v85, v44, v85
	v_mul_f32_e32 v87, v45, v87
	v_mul_f32_e32 v89, v46, v89
	v_mul_f32_e32 v91, v47, v91
	v_mul_f32_e32 v93, v48, v93
	v_mul_f32_e32 v95, v49, v95
	v_mul_f32_e32 v97, v50, v97
	v_mul_f32_e32 v98, v51, v99
	s_waitcnt lgkmcnt(7)
	v_mul_f32_e32 v99, v44, v100
	s_waitcnt lgkmcnt(6)
	v_mul_f32_e32 v100, v45, v102
	s_waitcnt lgkmcnt(5)
	v_mul_f32_e32 v102, v46, v104
	s_waitcnt lgkmcnt(4)
	v_mul_f32_e32 v104, v47, v106
	s_waitcnt lgkmcnt(3)
	v_mul_f32_e32 v106, v48, v108
	s_waitcnt lgkmcnt(2)
	v_mul_f32_e32 v108, v49, v126
	s_waitcnt lgkmcnt(1)
	v_mul_f32_e32 v126, v50, v128
	s_waitcnt lgkmcnt(0)
	v_mul_f32_e32 v128, v51, v130
	v_mul_f32_e32 v101, v44, v101
	v_mul_f32_e32 v103, v45, v103
	v_mul_f32_e32 v105, v46, v105
	v_mul_f32_e32 v107, v47, v107
	v_mul_f32_e32 v109, v48, v109
	v_mul_f32_e32 v127, v49, v127
	v_mul_f32_e32 v129, v50, v129
	v_mul_f32_e32 v130, v51, v131
	v_cvt_pk_bf16_f32 v44, v43, v52
	v_cvt_pk_bf16_f32 v45, v54, v56
	v_cvt_pk_bf16_f32 v46, v58, v60
	v_cvt_pk_bf16_f32 v47, v62, v64
	v_cvt_pk_bf16_f32 v48, v53, v55
	v_cvt_pk_bf16_f32 v49, v57, v59
	v_cvt_pk_bf16_f32 v50, v61, v63
	v_cvt_pk_bf16_f32 v51, v65, v66
	v_cvt_pk_bf16_f32 v52, v67, v68
	v_cvt_pk_bf16_f32 v53, v70, v72
	v_cvt_pk_bf16_f32 v54, v74, v76
	v_cvt_pk_bf16_f32 v55, v78, v80
	v_cvt_pk_bf16_f32 v56, v69, v71
	v_cvt_pk_bf16_f32 v57, v73, v75
	v_cvt_pk_bf16_f32 v58, v77, v79
	v_cvt_pk_bf16_f32 v59, v81, v82
	v_cvt_pk_bf16_f32 v60, v83, v84
	v_cvt_pk_bf16_f32 v61, v86, v88
	v_cvt_pk_bf16_f32 v62, v90, v92
	v_cvt_pk_bf16_f32 v63, v94, v96
	v_cvt_pk_bf16_f32 v64, v85, v87
	v_cvt_pk_bf16_f32 v65, v89, v91
	v_cvt_pk_bf16_f32 v66, v93, v95
	v_cvt_pk_bf16_f32 v67, v97, v98
	v_cvt_pk_bf16_f32 v68, v99, v100
	v_cvt_pk_bf16_f32 v69, v102, v104
	v_cvt_pk_bf16_f32 v70, v106, v108
	v_cvt_pk_bf16_f32 v71, v126, v128
	v_cvt_pk_bf16_f32 v72, v101, v103
	v_cvt_pk_bf16_f32 v73, v105, v107
	v_cvt_pk_bf16_f32 v74, v109, v127
	v_cvt_pk_bf16_f32 v75, v129, v130
	global_store_dwordx4 v[112:113], v[44:47], off sc0 sc1
	global_store_dwordx4 v[114:115], v[48:51], off sc0 sc1
	global_store_dwordx4 v[116:117], v[52:55], off sc0 sc1
	global_store_dwordx4 v[118:119], v[56:59], off sc0 sc1
	global_store_dwordx4 v[120:121], v[60:63], off sc0 sc1
	global_store_dwordx4 v[122:123], v[64:67], off sc0 sc1
	global_store_dwordx4 v[124:125], v[68:71], off sc0 sc1
	global_store_dwordx4 v[110:111], v[72:75], off sc0 sc1
	s_waitcnt lgkmcnt(0)
	s_cbranch_scc1 .LBB0_817
	v_readlane_b32 s4, v253, 0
	v_lshlrev_b32_e32 v4, 2, v0
	v_mov_b32_e32 v5, 0
	v_readlane_b32 s5, v253, 1
	v_readlane_b32 s10, v253, 6
	v_readlane_b32 s11, v253, 7
	s_mov_b64 s[4:5], 0x4000000
	v_readlane_b32 s60, v253, 12
	v_lshl_add_u64 v[0:1], s[10:11], 0, v[4:5]
	v_lshl_add_u64 v[0:1], v[0:1], 0, s[4:5]
	v_readlane_b32 s4, v253, 10
	v_lshlrev_b32_e32 v4, 1, v2
	v_readlane_b32 s5, v253, 11
	v_readlane_b32 s62, v253, 15
	s_mov_b32 s1, s54
	v_lshl_add_u64 v[2:3], s[4:5], 0, v[4:5]
	v_readlane_b32 s61, v253, 13
	v_readlane_b32 s63, v253, 16
	v_readlane_b32 s6, v253, 2
	v_readlane_b32 s7, v253, 3
	v_readlane_b32 s8, v253, 4
	v_readlane_b32 s9, v253, 5
; #define LAS __attribute__((address_space(3)))
; __device__ __forceinline__ void transpose_item(const float* W, int K, int N, bf16_t* WT, int gate, const float* kscale, LAS float* scr, int item, int lane) {
;     const int nblk = N / 64, kb = item / nblk, nb = item % nblk, k0 = 64 * kb, n0 = 64 * nb;
;     const int c4 = (lane & 15) * 4, kr = lane >> 4;
;     f32x4 v[16];
; #pragma unroll
;     for (int i = 0; i < 16; ++i) v[i] = __builtin_nontemporal_load((const f32x4*)(W + (size_t)(k0 + 4 * i + kr) * N + n0 + c4));
; #pragma unroll
;     for (int i = 0; i < 16; ++i) { LAS float* d = scr + (4 * i + kr) * 65 + c4; d[0] = v[i][0]; d[1] = v[i][1]; d[2] = v[i][2]; d[3] = v[i][3]; }
.LBB0_819:
	s_ashr_i32 s3, s1, 31
	s_lshr_b32 s3, s3, 27
	s_add_i32 s3, s1, s3
	s_ashr_i32 s3, s3, 5
	s_lshl_b32 s4, s3, 6
	s_lshl_b32 s3, s3, 11
	v_add_u32_e32 v4, s4, v10
	s_sub_i32 s6, s0, s3
	v_add_u32_e32 v6, 4, v4
	v_add_u32_e32 v14, 12, v4
	v_add_u32_e32 v16, 16, v4
	v_add_u32_e32 v18, 20, v4
	v_add_u32_e32 v20, 24, v4
	v_add_u32_e32 v22, 28, v4
	v_add_u32_e32 v24, 32, v4
	v_add_u32_e32 v26, 36, v4
	s_ashr_i32 s7, s6, 31
	v_ashrrev_i32_e32 v5, 31, v4
	v_add_u32_e32 v8, 8, v4
	v_add_u32_e32 v28, 40, v4
	v_add_u32_e32 v30, 44, v4
	v_add_u32_e32 v32, 48, v4
	v_add_u32_e32 v34, 52, v4
	v_add_u32_e32 v36, 56, v4
	v_add_u32_e32 v38, 60, v4
	v_add_u32_e32 v40, s6, v11
	v_ashrrev_i32_e32 v7, 31, v6
	v_ashrrev_i32_e32 v15, 31, v14
	v_ashrrev_i32_e32 v17, 31, v16
	v_ashrrev_i32_e32 v19, 31, v18
	v_ashrrev_i32_e32 v21, 31, v20
	v_ashrrev_i32_e32 v23, 31, v22
	v_ashrrev_i32_e32 v25, 31, v24
	v_ashrrev_i32_e32 v27, 31, v26
	s_ashr_i32 s5, s4, 31
	v_lshl_add_u64 v[42:43], s[6:7], 2, v[0:1]
	v_lshlrev_b64 v[4:5], 13, v[4:5]
	v_ashrrev_i32_e32 v9, 31, v8
	v_ashrrev_i32_e32 v29, 31, v28
	v_ashrrev_i32_e32 v31, 31, v30
	v_ashrrev_i32_e32 v33, 31, v32
	v_ashrrev_i32_e32 v35, 31, v34
	v_ashrrev_i32_e32 v37, 31, v36
	v_ashrrev_i32_e32 v39, 31, v38
	v_ashrrev_i32_e32 v41, 31, v40
	v_add_u32_e32 v44, 8, v40
	v_add_u32_e32 v46, 16, v40
	v_add_u32_e32 v48, 24, v40
	v_add_u32_e32 v50, 32, v40
	v_add_u32_e32 v52, 40, v40
	v_add_u32_e32 v54, 48, v40
	v_add_u32_e32 v56, 56, v40
	v_lshlrev_b64 v[58:59], 13, v[6:7]
	v_lshlrev_b64 v[14:15], 13, v[14:15]
	v_lshlrev_b64 v[16:17], 13, v[16:17]
	v_lshlrev_b64 v[18:19], 13, v[18:19]
	v_lshlrev_b64 v[20:21], 13, v[20:21]
	v_lshlrev_b64 v[22:23], 13, v[22:23]
	v_lshlrev_b64 v[24:25], 13, v[24:25]
	v_lshlrev_b64 v[26:27], 13, v[26:27]
	v_lshl_add_u64 v[74:75], s[4:5], 1, v[2:3]
	v_lshl_add_u64 v[4:5], v[42:43], 0, v[4:5]
	v_lshlrev_b64 v[8:9], 13, v[8:9]
	v_lshlrev_b64 v[28:29], 13, v[28:29]
	v_lshlrev_b64 v[30:31], 13, v[30:31]
	v_lshlrev_b64 v[32:33], 13, v[32:33]
	v_lshlrev_b64 v[34:35], 13, v[34:35]
	v_lshlrev_b64 v[36:37], 13, v[36:37]
	v_lshlrev_b64 v[38:39], 13, v[38:39]
	v_lshlrev_b64 v[40:41], 14, v[40:41]
	v_ashrrev_i32_e32 v45, 31, v44
	v_ashrrev_i32_e32 v47, 31, v46
	v_ashrrev_i32_e32 v49, 31, v48
	v_ashrrev_i32_e32 v51, 31, v50
	v_ashrrev_i32_e32 v53, 31, v52
	v_ashrrev_i32_e32 v55, 31, v54
	v_ashrrev_i32_e32 v57, 31, v56
	v_lshl_add_u64 v[58:59], v[42:43], 0, v[58:59]
	v_lshl_add_u64 v[60:61], v[42:43], 0, v[14:15]
	v_lshl_add_u64 v[62:63], v[42:43], 0, v[16:17]
	v_lshl_add_u64 v[64:65], v[42:43], 0, v[18:19]
	v_lshl_add_u64 v[66:67], v[42:43], 0, v[20:21]
	v_lshl_add_u64 v[68:69], v[42:43], 0, v[22:23]
	v_lshl_add_u64 v[70:71], v[42:43], 0, v[24:25]
	v_lshl_add_u64 v[72:73], v[42:43], 0, v[26:27]
	global_load_dwordx4 v[4:7], v[4:5], off nt
	v_lshl_add_u64 v[8:9], v[42:43], 0, v[8:9]
	v_lshl_add_u64 v[76:77], v[42:43], 0, v[28:29]
	v_lshl_add_u64 v[78:79], v[42:43], 0, v[30:31]
	v_lshl_add_u64 v[80:81], v[42:43], 0, v[32:33]
	v_lshl_add_u64 v[82:83], v[42:43], 0, v[34:35]
	v_lshl_add_u64 v[84:85], v[42:43], 0, v[36:37]
	v_lshl_add_u64 v[86:87], v[42:43], 0, v[38:39]
	v_lshl_add_u64 v[88:89], v[74:75], 0, v[40:41]
	v_lshlrev_b64 v[90:91], 14, v[44:45]
	v_lshlrev_b64 v[92:93], 14, v[46:47]
	v_lshlrev_b64 v[94:95], 14, v[48:49]
	v_lshlrev_b64 v[96:97], 14, v[50:51]
	v_lshlrev_b64 v[98:99], 14, v[52:53]
	v_lshlrev_b64 v[100:101], 14, v[54:55]
	v_lshlrev_b64 v[102:103], 14, v[56:57]
	global_load_dwordx4 v[14:17], v[58:59], off nt
	global_load_dwordx4 v[18:21], v[8:9], off nt
	global_load_dwordx4 v[22:25], v[60:61], off nt
	global_load_dwordx4 v[26:29], v[62:63], off nt
	global_load_dwordx4 v[30:33], v[64:65], off nt
	global_load_dwordx4 v[34:37], v[66:67], off nt
	global_load_dwordx4 v[38:41], v[68:69], off nt
	global_load_dwordx4 v[42:45], v[70:71], off nt
	global_load_dwordx4 v[46:49], v[72:73], off nt
	global_load_dwordx4 v[50:53], v[76:77], off nt
	global_load_dwordx4 v[54:57], v[78:79], off nt
	global_load_dwordx4 v[58:61], v[80:81], off nt
	global_load_dwordx4 v[62:65], v[82:83], off nt
	global_load_dwordx4 v[66:69], v[84:85], off nt
	global_load_dwordx4 v[70:73], v[86:87], off nt
	v_add_u32_e32 v104, 0x410, v13
	v_add_u32_e32 v105, 0x418, v13
	v_add_u32_e32 v106, 0x820, v13
	v_add_u32_e32 v107, 0x828, v13
	v_add_u32_e32 v108, 0xc30, v13
	v_add_u32_e32 v109, 0xc38, v13
	v_add_u32_e32 v110, 0x1040, v13
	v_add_u32_e32 v111, 0x1048, v13
	v_add_u32_e32 v112, 0x1450, v13
	v_add_u32_e32 v113, 0x1458, v13
	v_add_u32_e32 v114, 0x1860, v13
	v_add_u32_e32 v115, 0x1868, v13
	v_add_u32_e32 v116, 0x1c70, v13
	v_add_u32_e32 v117, 0x1c78, v13
	v_add_u32_e32 v118, 0x2080, v13
	v_add_u32_e32 v119, 0x2088, v13
	v_add_u32_e32 v120, 0x2490, v13
	v_add_u32_e32 v121, 0x2498, v13
	v_add_u32_e32 v122, 0x28a0, v13
	v_add_u32_e32 v123, 0x28a8, v13
	v_add_u32_e32 v124, 0x2cb0, v13
	v_add_u32_e32 v125, 0x2cb8, v13
	v_add_u32_e32 v126, 0x30c0, v13
	v_add_u32_e32 v127, 0x30c8, v13
	v_add_u32_e32 v128, 0x34d0, v13
	v_add_u32_e32 v129, 0x34d8, v13
	v_add_u32_e32 v130, 0x38e0, v13
	v_add_u32_e32 v131, 0x38e8, v13
	v_add_u32_e32 v132, 0x3cf0, v13
	v_add_u32_e32 v133, 0x3cf8, v13
	s_waitcnt vmcnt(15)
	ds_write2_b32 v13, v4, v5 offset1:1
	ds_write2_b32 v13, v6, v7 offset0:2 offset1:3
	s_waitcnt vmcnt(14)
; #define LAS __attribute__((address_space(3)))
; __device__ __forceinline__ void lds_wait() { asm volatile("s_waitcnt lgkmcnt(0)" ::: "memory"); }
; __device__ __forceinline__ void transpose_item(const float* W, int K, int N, bf16_t* WT, int gate, const float* kscale, LAS float* scr, int item, int lane) {
;     ...
;     for (int i = 0; i < 16; ++i) { LAS float* d = scr + (4 * i + kr) * 65 + c4; d[0] = v[i][0]; d[1] = v[i][1]; d[2] = v[i][2]; d[3] = v[i][3]; }
;     lds_wait();
;     const int c = lane & 7;
;     f32x4 k0v = {1.f, 1.f, 1.f, 1.f}, k1v = k0v;
;     if (kscale) { k0v = *(const f32x4*)(kscale + k0 + 8 * c); k1v = *(const f32x4*)(kscale + k0 + 8 * c + 4); }
; #pragma unroll
;     for (int j = 0; j < 8; ++j) { const int n = (lane >> 3) + 8 * j; const LAS float* s = scr + (8 * c) * 65 + n;
;         u32x4 o; o.x = pk2(s[0 * 65] * k0v[0], s[1 * 65] * k0v[1]); o.y = pk2(s[2 * 65] * k0v[2], s[3 * 65] * k0v[3]); o.z = pk2(s[4 * 65] * k1v[0], s[5 * 65] * k1v[1]); o.w = pk2(s[6 * 65] * k1v[2], s[7 * 65] * k1v[3]);
;         const int nn = n0 + n; const int row = gate < 0 ? nn : (256 * (nn >> 7) + 128 * gate + (nn & 127));
;         *(u32x4*)(WT + (size_t)row * K + k0 + 8 * c) = o; }
;     lds_wait();
	ds_write2_b32 v104, v14, v15 offset1:1
	ds_write2_b32 v105, v16, v17 offset1:1
	s_waitcnt vmcnt(13)
	ds_write2_b32 v106, v18, v19 offset1:1
	ds_write2_b32 v107, v20, v21 offset1:1
	s_waitcnt vmcnt(12)
	ds_write2_b32 v108, v22, v23 offset1:1
	ds_write2_b32 v109, v24, v25 offset1:1
	s_waitcnt vmcnt(11)
	ds_write2_b32 v110, v26, v27 offset1:1
	ds_write2_b32 v111, v28, v29 offset1:1
	s_waitcnt vmcnt(10)
	ds_write2_b32 v112, v30, v31 offset1:1
	ds_write2_b32 v113, v32, v33 offset1:1
	s_waitcnt vmcnt(9)
	ds_write2_b32 v114, v34, v35 offset1:1
	ds_write2_b32 v115, v36, v37 offset1:1
	s_waitcnt vmcnt(8)
	ds_write2_b32 v116, v38, v39 offset1:1
	ds_write2_b32 v117, v40, v41 offset1:1
	s_waitcnt vmcnt(7)
	ds_write2_b32 v118, v42, v43 offset1:1
	ds_write2_b32 v119, v44, v45 offset1:1
	s_waitcnt vmcnt(6)
	ds_write2_b32 v120, v46, v47 offset1:1
	ds_write2_b32 v121, v48, v49 offset1:1
	s_waitcnt vmcnt(5)
	ds_write2_b32 v122, v50, v51 offset1:1
	ds_write2_b32 v123, v52, v53 offset1:1
	s_waitcnt vmcnt(4)
	ds_write2_b32 v124, v54, v55 offset1:1
	ds_write2_b32 v125, v56, v57 offset1:1
	s_waitcnt vmcnt(3)
	ds_write2_b32 v126, v58, v59 offset1:1
	ds_write2_b32 v127, v60, v61 offset1:1
	s_waitcnt vmcnt(2)
	ds_write2_b32 v128, v62, v63 offset1:1
	ds_write2_b32 v129, v64, v65 offset1:1
	s_waitcnt vmcnt(1)
	ds_write2_b32 v130, v66, v67 offset1:1
	ds_write2_b32 v131, v68, v69 offset1:1
	s_waitcnt vmcnt(0)
	ds_write2_b32 v132, v70, v71 offset1:1
	ds_write2_b32 v133, v72, v73 offset1:1
	s_waitcnt lgkmcnt(0)
	v_add_u32_e32 v134, 0x400, v12
	v_lshl_add_u64 v[8:9], v[74:75], 0, v[90:91]
	ds_read2_b32 v[14:15], v12 offset0:65 offset1:73
	ds_read2_b32 v[16:17], v12 offset1:8
	ds_read2_b32 v[18:19], v12 offset0:130 offset1:138
	ds_read2_b32 v[20:21], v12 offset0:195 offset1:203
	ds_read2_b32 v[22:23], v134 offset0:4 offset1:12
	ds_read2_b32 v[24:25], v134 offset0:69 offset1:77
	ds_read2_b32 v[26:27], v134 offset0:134 offset1:142
	ds_read2_b32 v[28:29], v134 offset0:199 offset1:207
	ds_read2_b32 v[30:31], v12 offset0:81 offset1:89
	ds_read2_b32 v[32:33], v12 offset0:16 offset1:24
	ds_read2_b32 v[34:35], v12 offset0:146 offset1:154
	ds_read2_b32 v[36:37], v12 offset0:211 offset1:219
	ds_read2_b32 v[38:39], v134 offset0:20 offset1:28
	ds_read2_b32 v[40:41], v134 offset0:85 offset1:93
	ds_read2_b32 v[42:43], v134 offset0:150 offset1:158
	ds_read2_b32 v[44:45], v134 offset0:215 offset1:223
	ds_read2_b32 v[46:47], v12 offset0:32 offset1:40
	ds_read2_b32 v[48:49], v12 offset0:97 offset1:105
	ds_read2_b32 v[50:51], v12 offset0:162 offset1:170
	ds_read2_b32 v[52:53], v12 offset0:227 offset1:235
	ds_read2_b32 v[54:55], v134 offset0:36 offset1:44
	ds_read2_b32 v[56:57], v134 offset0:101 offset1:109
	ds_read2_b32 v[58:59], v134 offset0:166 offset1:174
	ds_read2_b32 v[60:61], v134 offset0:231 offset1:239
	ds_read2_b32 v[62:63], v12 offset0:48 offset1:56
	ds_read2_b32 v[64:65], v12 offset0:113 offset1:121
	ds_read2_b32 v[66:67], v12 offset0:178 offset1:186
	ds_read2_b32 v[68:69], v12 offset0:243 offset1:251
	ds_read2_b32 v[70:71], v134 offset0:52 offset1:60
	ds_read2_b32 v[72:73], v134 offset0:117 offset1:125
	ds_read2_b32 v[86:87], v134 offset0:182 offset1:190
	ds_read2_b32 v[90:91], v134 offset0:247 offset1:255
	s_waitcnt lgkmcnt(14)
	v_cvt_pk_bf16_f32 v4, v16, v14
	v_cvt_pk_bf16_f32 v5, v18, v20
	v_cvt_pk_bf16_f32 v6, v22, v24
	v_cvt_pk_bf16_f32 v7, v26, v28
	v_lshl_add_u64 v[76:77], v[74:75], 0, v[92:93]
	v_lshl_add_u64 v[78:79], v[74:75], 0, v[94:95]
	v_lshl_add_u64 v[80:81], v[74:75], 0, v[96:97]
	v_lshl_add_u64 v[82:83], v[74:75], 0, v[98:99]
	v_lshl_add_u64 v[84:85], v[74:75], 0, v[100:101]
	v_lshl_add_u64 v[74:75], v[74:75], 0, v[102:103]
	v_cvt_pk_bf16_f32 v14, v17, v15
	v_cvt_pk_bf16_f32 v15, v19, v21
	v_cvt_pk_bf16_f32 v16, v23, v25
	v_cvt_pk_bf16_f32 v17, v27, v29
	v_cvt_pk_bf16_f32 v18, v32, v30
	v_cvt_pk_bf16_f32 v19, v34, v36
	v_cvt_pk_bf16_f32 v20, v38, v40
	v_cvt_pk_bf16_f32 v21, v42, v44
	v_cvt_pk_bf16_f32 v22, v33, v31
	v_cvt_pk_bf16_f32 v23, v35, v37
	v_cvt_pk_bf16_f32 v24, v39, v41
	v_cvt_pk_bf16_f32 v25, v43, v45
	v_cvt_pk_bf16_f32 v26, v46, v48
	s_waitcnt lgkmcnt(12)
	v_cvt_pk_bf16_f32 v27, v50, v52
	s_waitcnt lgkmcnt(10)
	v_cvt_pk_bf16_f32 v28, v54, v56
	s_waitcnt lgkmcnt(8)
	v_cvt_pk_bf16_f32 v29, v58, v60
	v_cvt_pk_bf16_f32 v30, v47, v49
	v_cvt_pk_bf16_f32 v31, v51, v53
	v_cvt_pk_bf16_f32 v32, v55, v57
	v_cvt_pk_bf16_f32 v33, v59, v61
	s_waitcnt lgkmcnt(6)
	v_cvt_pk_bf16_f32 v34, v62, v64
	s_waitcnt lgkmcnt(4)
	v_cvt_pk_bf16_f32 v35, v66, v68
	s_waitcnt lgkmcnt(2)
	v_cvt_pk_bf16_f32 v36, v70, v72
	s_waitcnt lgkmcnt(0)
	v_cvt_pk_bf16_f32 v37, v86, v90
	v_cvt_pk_bf16_f32 v38, v63, v65
	v_cvt_pk_bf16_f32 v39, v67, v69
	v_cvt_pk_bf16_f32 v40, v71, v73
	v_cvt_pk_bf16_f32 v41, v87, v91
	global_store_dwordx4 v[88:89], v[4:7], off sc0 sc1
	global_store_dwordx4 v[8:9], v[14:17], off sc0 sc1
	global_store_dwordx4 v[76:77], v[18:21], off sc0 sc1
	global_store_dwordx4 v[78:79], v[22:25], off sc0 sc1
	global_store_dwordx4 v[80:81], v[26:29], off sc0 sc1
	global_store_dwordx4 v[82:83], v[30:33], off sc0 sc1
	global_store_dwordx4 v[84:85], v[34:37], off sc0 sc1
	global_store_dwordx4 v[74:75], v[38:41], off sc0 sc1
	s_waitcnt lgkmcnt(0)
	s_add_i32 s1, s1, s92
	s_add_i32 s0, s0, s38
	s_cmpk_lt_i32 s1, 0x1000
	s_cbranch_scc1 .LBB0_819
	s_branch .LBB0_821
